# K-loop MMA blocks: accumulate chains in a snake order so that every consecutive pair of chains shares one operand fragment pair
# baseline (speedup 1.0000x reference)
.LBB0_322:
	s_ashr_i32 s43, s42, 31
	s_lshl_b64 s[46:47], s[42:43], 19
	s_add_u32 s46, s12, s46
	s_addc_u32 s47, s13, s47
	s_and_b64 s[48:49], s[4:5], exec
	s_cselect_b32 s18, s47, s7
	s_cselect_b32 s43, s46, s6
	s_ashr_i32 s45, s44, 31
	s_lshl_b64 s[48:49], s[44:45], 19
	s_add_u32 s48, s59, s48
	s_addc_u32 s49, s60, s49
	s_and_b64 s[50:51], s[4:5], exec
	s_cselect_b32 s45, s49, s9
	s_cselect_b32 s55, s48, s8
	s_add_u32 s6, s6, 0x40080
	s_addc_u32 s7, s7, 0
	s_add_u32 s56, s8, 0x100
	s_addc_u32 s57, s9, 0
	s_mov_b32 s78, -2
	ds_read_b128 v[96:99], v209
	ds_read_b128 v[100:103], v209 offset:1024
	ds_read_b128 v[120:123], v209 offset:2048
	ds_read_b128 v[124:127], v209 offset:3072
	ds_read_b128 v[144:147], v210
	ds_read_b128 v[148:151], v210 offset:1024
	ds_read_b128 v[152:155], v210 offset:2048
	ds_read_b128 v[156:159], v210 offset:3072
	s_add_u32 s8, s6, 0xfffc0080
	s_addc_u32 s9, s7, -1
	s_cmp_eq_u32 s78, 12
	s_cselect_b32 s51, s18, s9
	s_cselect_b32 s50, s43, s8
	s_cselect_b32 s9, s45, s57
	s_cselect_b32 s8, s55, s56
	v_lshl_add_u64 v[206:207], s[6:7], 0, v[170:171]
	s_add_i32 m0, s17, 0xc000
	ds_read_b128 v[178:181], v211
	ds_read_b128 v[182:185], v211 offset:1024
	ds_read_b128 v[186:189], v211 offset:2048
	ds_read_b128 v[190:193], v211 offset:3072
	ds_read_b128 v[194:197], v211 offset:4096
	ds_read_b128 v[198:201], v211 offset:5120
	ds_read_b128 v[202:205], v211 offset:6144
	ds_read_b128 v[218:221], v211 offset:7168
	global_load_lds_dwordx4 v[206:207], off
	s_add_i32 m0, s17, 0xe000
	v_lshl_add_u64 v[206:207], s[6:7], 0, v[172:173]
	global_load_lds_dwordx4 v[206:207], off
	s_waitcnt vmcnt(8) lgkmcnt(0)
	s_barrier
	s_setprio 1
	v_mfma_f32_16x16x32_bf16 v[140:143], v[96:99], v[178:181], 0
	v_mfma_f32_16x16x32_bf16 v[140:143], v[100:103], v[182:185], v[140:143]
	v_mfma_f32_16x16x32_bf16 v[136:139], v[120:123], v[178:181], 0
	v_mfma_f32_16x16x32_bf16 v[136:139], v[124:127], v[182:185], v[136:139]
	v_mfma_f32_16x16x32_bf16 v[112:115], v[120:123], v[186:189], 0
	v_mfma_f32_16x16x32_bf16 v[112:115], v[124:127], v[190:193], v[112:115]
	v_mfma_f32_16x16x32_bf16 v[116:119], v[96:99], v[186:189], 0
	v_mfma_f32_16x16x32_bf16 v[116:119], v[100:103], v[190:193], v[116:119]
	v_mfma_f32_16x16x32_bf16 v[92:95], v[96:99], v[194:197], 0
	v_mfma_f32_16x16x32_bf16 v[92:95], v[100:103], v[198:201], v[92:95]
	v_mfma_f32_16x16x32_bf16 v[88:91], v[120:123], v[194:197], 0
	v_mfma_f32_16x16x32_bf16 v[88:91], v[124:127], v[198:201], v[88:91]
	v_mfma_f32_16x16x32_bf16 v[72:75], v[120:123], v[202:205], 0
	v_mfma_f32_16x16x32_bf16 v[72:75], v[124:127], v[218:221], v[72:75]
	v_mfma_f32_16x16x32_bf16 v[76:79], v[96:99], v[202:205], 0
	v_mfma_f32_16x16x32_bf16 v[76:79], v[100:103], v[218:221], v[76:79]
	v_mfma_f32_16x16x32_bf16 v[132:135], v[144:147], v[178:181], 0
	v_mfma_f32_16x16x32_bf16 v[132:135], v[148:151], v[182:185], v[132:135]
	v_mfma_f32_16x16x32_bf16 v[128:131], v[152:155], v[178:181], 0
	v_mfma_f32_16x16x32_bf16 v[128:131], v[156:159], v[182:185], v[128:131]
	v_mfma_f32_16x16x32_bf16 v[104:107], v[152:155], v[186:189], 0
	v_mfma_f32_16x16x32_bf16 v[104:107], v[156:159], v[190:193], v[104:107]
	v_mfma_f32_16x16x32_bf16 v[108:111], v[144:147], v[186:189], 0
	v_mfma_f32_16x16x32_bf16 v[108:111], v[148:151], v[190:193], v[108:111]
	v_mfma_f32_16x16x32_bf16 v[84:87], v[144:147], v[194:197], 0
	v_mfma_f32_16x16x32_bf16 v[84:87], v[148:151], v[198:201], v[84:87]
	v_mfma_f32_16x16x32_bf16 v[80:83], v[152:155], v[194:197], 0
	v_mfma_f32_16x16x32_bf16 v[80:83], v[156:159], v[198:201], v[80:83]
	s_setprio 2
	s_barrier
	v_mfma_f32_16x16x32_bf16 v[64:67], v[152:155], v[202:205], 0
	v_mfma_f32_16x16x32_bf16 v[64:67], v[156:159], v[218:221], v[64:67]
	v_mfma_f32_16x16x32_bf16 v[68:71], v[144:147], v[202:205], 0
	v_mfma_f32_16x16x32_bf16 v[68:71], v[148:151], v[218:221], v[68:71]
	s_setprio 2
	s_add_i32 s79, s73, s61
	v_lshl_add_u64 v[206:207], s[8:9], 0, v[162:163]
	s_mov_b32 m0, s79
	ds_read_b128 v[178:181], v211 offset:16384
	ds_read_b128 v[182:185], v211 offset:17408
	ds_read_b128 v[186:189], v211 offset:18432
	ds_read_b128 v[190:193], v211 offset:19456
	ds_read_b128 v[194:197], v211 offset:20480
	ds_read_b128 v[198:201], v211 offset:21504
	ds_read_b128 v[202:205], v211 offset:22528
	ds_read_b128 v[218:221], v211 offset:23552
	global_load_lds_dwordx4 v[206:207], off
	s_add_i32 m0, s79, 0x2000
	s_add_u32 s80, s8, 0x40000
	v_lshl_add_u64 v[222:223], s[8:9], 0, v[166:167]
	s_addc_u32 s81, s9, 0
	s_add_i32 s79, s74, s61
	global_load_lds_dwordx4 v[222:223], off
	v_lshl_add_u64 v[224:225], s[80:81], 0, v[162:163]
	s_mov_b32 m0, s79
	v_lshl_add_u64 v[226:227], s[50:51], 0, v[164:165]
	global_load_lds_dwordx4 v[224:225], off
	s_add_i32 m0, s79, 0x2000
	v_lshl_add_u64 v[224:225], s[80:81], 0, v[166:167]
	global_load_lds_dwordx4 v[224:225], off
	s_mov_b32 m0, s17
	v_lshl_add_u64 v[224:225], s[50:51], 0, v[160:161]
	global_load_lds_dwordx4 v[224:225], off
	s_mov_b32 m0, s62
	s_nop 0
	global_load_lds_dwordx4 v[226:227], off
	s_waitcnt vmcnt(8) lgkmcnt(0)
	s_barrier
	s_setprio 1
	v_mfma_f32_16x16x32_bf16 v[60:63], v[96:99], v[178:181], 0
	v_mfma_f32_16x16x32_bf16 v[60:63], v[100:103], v[182:185], v[60:63]
	v_mfma_f32_16x16x32_bf16 v[56:59], v[120:123], v[178:181], 0
	v_mfma_f32_16x16x32_bf16 v[56:59], v[124:127], v[182:185], v[56:59]
	v_mfma_f32_16x16x32_bf16 v[40:43], v[120:123], v[186:189], 0
	v_mfma_f32_16x16x32_bf16 v[40:43], v[124:127], v[190:193], v[40:43]
	v_mfma_f32_16x16x32_bf16 v[44:47], v[96:99], v[186:189], 0
	v_mfma_f32_16x16x32_bf16 v[44:47], v[100:103], v[190:193], v[44:47]
	v_mfma_f32_16x16x32_bf16 v[28:31], v[96:99], v[194:197], 0
	v_mfma_f32_16x16x32_bf16 v[28:31], v[100:103], v[198:201], v[28:31]
	v_mfma_f32_16x16x32_bf16 v[24:27], v[120:123], v[194:197], 0
	v_mfma_f32_16x16x32_bf16 v[24:27], v[124:127], v[198:201], v[24:27]
	v_mfma_f32_16x16x32_bf16 v[8:11], v[120:123], v[202:205], 0
	v_mfma_f32_16x16x32_bf16 v[8:11], v[124:127], v[218:221], v[8:11]
	v_mfma_f32_16x16x32_bf16 v[12:15], v[96:99], v[202:205], 0
	v_mfma_f32_16x16x32_bf16 v[12:15], v[100:103], v[218:221], v[12:15]
	v_mfma_f32_16x16x32_bf16 v[52:55], v[144:147], v[178:181], 0
	v_mfma_f32_16x16x32_bf16 v[52:55], v[148:151], v[182:185], v[52:55]
	v_mfma_f32_16x16x32_bf16 v[48:51], v[152:155], v[178:181], 0
	v_mfma_f32_16x16x32_bf16 v[48:51], v[156:159], v[182:185], v[48:51]
	v_mfma_f32_16x16x32_bf16 v[32:35], v[152:155], v[186:189], 0
	v_mfma_f32_16x16x32_bf16 v[32:35], v[156:159], v[190:193], v[32:35]
	v_mfma_f32_16x16x32_bf16 v[36:39], v[144:147], v[186:189], 0
	v_mfma_f32_16x16x32_bf16 v[36:39], v[148:151], v[190:193], v[36:39]
	v_mfma_f32_16x16x32_bf16 v[20:23], v[144:147], v[194:197], 0
	v_mfma_f32_16x16x32_bf16 v[20:23], v[148:151], v[198:201], v[20:23]
	v_mfma_f32_16x16x32_bf16 v[16:19], v[152:155], v[194:197], 0
	v_mfma_f32_16x16x32_bf16 v[16:19], v[156:159], v[198:201], v[16:19]
	s_setprio 2
	s_barrier
	v_mfma_f32_16x16x32_bf16 v[0:3], v[152:155], v[202:205], 0
	v_mfma_f32_16x16x32_bf16 v[0:3], v[156:159], v[218:221], v[0:3]
	v_mfma_f32_16x16x32_bf16 v[4:7], v[144:147], v[202:205], 0
	v_mfma_f32_16x16x32_bf16 v[4:7], v[148:151], v[218:221], v[4:7]
	s_setprio 0
	s_add_i32 s79, 0, 0x18000
	s_add_i32 s80, 0, 0x1c000
	v_add_u32_e32 v124, s79, v208
	v_add_u32_e32 v156, s80, v208
	ds_read_b128 v[96:99], v124
	ds_read_b128 v[100:103], v124 offset:1024
	ds_read_b128 v[120:123], v124 offset:2048
	ds_read_b128 v[124:127], v124 offset:3072
	ds_read_b128 v[144:147], v156
	ds_read_b128 v[148:151], v156 offset:1024
	ds_read_b128 v[152:155], v156 offset:2048
	ds_read_b128 v[156:159], v156 offset:3072
	s_add_u32 s50, s50, 0x40000
	s_addc_u32 s51, s51, 0
	s_mov_b32 m0, s63
	v_lshl_add_u64 v[228:229], s[50:51], 0, v[160:161]
	ds_read_b128 v[178:181], v211 offset:32768
	ds_read_b128 v[182:185], v211 offset:33792
	ds_read_b128 v[186:189], v211 offset:34816
	ds_read_b128 v[190:193], v211 offset:35840
	ds_read_b128 v[194:197], v211 offset:36864
	ds_read_b128 v[198:201], v211 offset:37888
	ds_read_b128 v[202:205], v211 offset:38912
	ds_read_b128 v[218:221], v211 offset:39936
	global_load_lds_dwordx4 v[228:229], off
	s_mov_b32 m0, s64
	v_lshl_add_u64 v[228:229], s[50:51], 0, v[164:165]
	global_load_lds_dwordx4 v[228:229], off
	s_waitcnt vmcnt(8) lgkmcnt(0)
	s_barrier
	s_setprio 1
	v_mfma_f32_16x16x32_bf16 v[140:143], v[96:99], v[178:181], v[140:143]
	v_mfma_f32_16x16x32_bf16 v[140:143], v[100:103], v[182:185], v[140:143]
	v_mfma_f32_16x16x32_bf16 v[136:139], v[120:123], v[178:181], v[136:139]
	v_mfma_f32_16x16x32_bf16 v[136:139], v[124:127], v[182:185], v[136:139]
	v_mfma_f32_16x16x32_bf16 v[112:115], v[120:123], v[186:189], v[112:115]
	v_mfma_f32_16x16x32_bf16 v[112:115], v[124:127], v[190:193], v[112:115]
	v_mfma_f32_16x16x32_bf16 v[116:119], v[96:99], v[186:189], v[116:119]
	v_mfma_f32_16x16x32_bf16 v[116:119], v[100:103], v[190:193], v[116:119]
	v_mfma_f32_16x16x32_bf16 v[92:95], v[96:99], v[194:197], v[92:95]
	v_mfma_f32_16x16x32_bf16 v[92:95], v[100:103], v[198:201], v[92:95]
	v_mfma_f32_16x16x32_bf16 v[88:91], v[120:123], v[194:197], v[88:91]
	v_mfma_f32_16x16x32_bf16 v[88:91], v[124:127], v[198:201], v[88:91]
	v_mfma_f32_16x16x32_bf16 v[72:75], v[120:123], v[202:205], v[72:75]
	v_mfma_f32_16x16x32_bf16 v[72:75], v[124:127], v[218:221], v[72:75]
	v_mfma_f32_16x16x32_bf16 v[76:79], v[96:99], v[202:205], v[76:79]
	v_mfma_f32_16x16x32_bf16 v[76:79], v[100:103], v[218:221], v[76:79]
	v_mfma_f32_16x16x32_bf16 v[132:135], v[144:147], v[178:181], v[132:135]
	v_mfma_f32_16x16x32_bf16 v[132:135], v[148:151], v[182:185], v[132:135]
	v_mfma_f32_16x16x32_bf16 v[128:131], v[152:155], v[178:181], v[128:131]
	v_mfma_f32_16x16x32_bf16 v[128:131], v[156:159], v[182:185], v[128:131]
	v_mfma_f32_16x16x32_bf16 v[104:107], v[152:155], v[186:189], v[104:107]
	v_mfma_f32_16x16x32_bf16 v[104:107], v[156:159], v[190:193], v[104:107]
	v_mfma_f32_16x16x32_bf16 v[108:111], v[144:147], v[186:189], v[108:111]
	v_mfma_f32_16x16x32_bf16 v[108:111], v[148:151], v[190:193], v[108:111]
	v_mfma_f32_16x16x32_bf16 v[84:87], v[144:147], v[194:197], v[84:87]
	v_mfma_f32_16x16x32_bf16 v[84:87], v[148:151], v[198:201], v[84:87]
	v_mfma_f32_16x16x32_bf16 v[80:83], v[152:155], v[194:197], v[80:83]
	v_mfma_f32_16x16x32_bf16 v[80:83], v[156:159], v[198:201], v[80:83]
	s_setprio 2
	s_barrier
	v_mfma_f32_16x16x32_bf16 v[64:67], v[152:155], v[202:205], v[64:67]
	v_mfma_f32_16x16x32_bf16 v[64:67], v[156:159], v[218:221], v[64:67]
	v_mfma_f32_16x16x32_bf16 v[68:71], v[144:147], v[202:205], v[68:71]
	v_mfma_f32_16x16x32_bf16 v[68:71], v[148:151], v[218:221], v[68:71]
	s_setprio 2
	s_add_i32 s50, s79, s61
	v_lshl_add_u64 v[206:207], v[206:207], 0, s[36:37]
	s_mov_b32 m0, s50
	ds_read_b128 v[178:181], v211 offset:49152
	ds_read_b128 v[182:185], v211 offset:50176
	ds_read_b128 v[186:189], v211 offset:51200
	ds_read_b128 v[190:193], v211 offset:52224
	ds_read_b128 v[194:197], v211 offset:53248
	ds_read_b128 v[198:201], v211 offset:54272
	ds_read_b128 v[202:205], v211 offset:55296
	ds_read_b128 v[218:221], v211 offset:56320
	global_load_lds_dwordx4 v[206:207], off
	s_add_i32 m0, s50, 0x2000
	s_add_u32 s8, s8, 0x40080
	v_lshl_add_u64 v[206:207], v[222:223], 0, s[36:37]
	s_addc_u32 s9, s9, 0
	s_add_i32 s50, s80, s61
	global_load_lds_dwordx4 v[206:207], off
	s_mov_b32 m0, s50
	v_lshl_add_u64 v[206:207], s[8:9], 0, v[162:163]
	global_load_lds_dwordx4 v[206:207], off
	s_add_i32 m0, s50, 0x2000
	v_lshl_add_u64 v[206:207], s[8:9], 0, v[166:167]
	global_load_lds_dwordx4 v[206:207], off
	s_mov_b32 m0, s68
	v_lshl_add_u64 v[206:207], v[224:225], 0, s[36:37]
	global_load_lds_dwordx4 v[206:207], off
	s_mov_b32 m0, s69
	v_lshl_add_u64 v[206:207], v[226:227], 0, s[36:37]
	global_load_lds_dwordx4 v[206:207], off
	s_waitcnt vmcnt(8) lgkmcnt(0)
	s_barrier
	s_setprio 1
	v_mfma_f32_16x16x32_bf16 v[60:63], v[96:99], v[178:181], v[60:63]
	v_mfma_f32_16x16x32_bf16 v[60:63], v[100:103], v[182:185], v[60:63]
	v_mfma_f32_16x16x32_bf16 v[56:59], v[120:123], v[178:181], v[56:59]
	v_mfma_f32_16x16x32_bf16 v[56:59], v[124:127], v[182:185], v[56:59]
	v_mfma_f32_16x16x32_bf16 v[40:43], v[120:123], v[186:189], v[40:43]
	v_mfma_f32_16x16x32_bf16 v[40:43], v[124:127], v[190:193], v[40:43]
	v_mfma_f32_16x16x32_bf16 v[44:47], v[96:99], v[186:189], v[44:47]
	v_mfma_f32_16x16x32_bf16 v[44:47], v[100:103], v[190:193], v[44:47]
	v_mfma_f32_16x16x32_bf16 v[28:31], v[96:99], v[194:197], v[28:31]
	v_mfma_f32_16x16x32_bf16 v[28:31], v[100:103], v[198:201], v[28:31]
	v_mfma_f32_16x16x32_bf16 v[24:27], v[120:123], v[194:197], v[24:27]
	v_mfma_f32_16x16x32_bf16 v[24:27], v[124:127], v[198:201], v[24:27]
	v_mfma_f32_16x16x32_bf16 v[8:11], v[120:123], v[202:205], v[8:11]
	v_mfma_f32_16x16x32_bf16 v[8:11], v[124:127], v[218:221], v[8:11]
	v_mfma_f32_16x16x32_bf16 v[12:15], v[96:99], v[202:205], v[12:15]
	v_mfma_f32_16x16x32_bf16 v[12:15], v[100:103], v[218:221], v[12:15]
	v_mfma_f32_16x16x32_bf16 v[52:55], v[144:147], v[178:181], v[52:55]
	v_mfma_f32_16x16x32_bf16 v[52:55], v[148:151], v[182:185], v[52:55]
	v_mfma_f32_16x16x32_bf16 v[48:51], v[152:155], v[178:181], v[48:51]
	v_mfma_f32_16x16x32_bf16 v[48:51], v[156:159], v[182:185], v[48:51]
	v_mfma_f32_16x16x32_bf16 v[32:35], v[152:155], v[186:189], v[32:35]
	v_mfma_f32_16x16x32_bf16 v[32:35], v[156:159], v[190:193], v[32:35]
	v_mfma_f32_16x16x32_bf16 v[36:39], v[144:147], v[186:189], v[36:39]
	v_mfma_f32_16x16x32_bf16 v[36:39], v[148:151], v[190:193], v[36:39]
	v_mfma_f32_16x16x32_bf16 v[20:23], v[144:147], v[194:197], v[20:23]
	v_mfma_f32_16x16x32_bf16 v[20:23], v[148:151], v[198:201], v[20:23]
	v_mfma_f32_16x16x32_bf16 v[16:19], v[152:155], v[194:197], v[16:19]
	v_mfma_f32_16x16x32_bf16 v[16:19], v[156:159], v[198:201], v[16:19]
	s_setprio 2
	s_barrier
	v_mfma_f32_16x16x32_bf16 v[0:3], v[152:155], v[202:205], v[0:3]
	v_mfma_f32_16x16x32_bf16 v[0:3], v[156:159], v[218:221], v[0:3]
	v_mfma_f32_16x16x32_bf16 v[4:7], v[144:147], v[202:205], v[4:7]
	v_mfma_f32_16x16x32_bf16 v[4:7], v[148:151], v[218:221], v[4:7]
	s_setprio 0
	s_add_i32 s78, s78, 2
	s_add_u32 s6, s6, 0x100
	s_addc_u32 s7, s7, 0
	s_add_u32 s56, s56, 0x100
	s_addc_u32 s57, s57, 0
	s_cmp_gt_u32 s78, 13
.LBB0_323:
	ds_read_b128 v[96:99], v209
	ds_read_b128 v[100:103], v209 offset:1024
	ds_read_b128 v[120:123], v209 offset:2048
	ds_read_b128 v[124:127], v209 offset:3072
	ds_read_b128 v[144:147], v210
	ds_read_b128 v[148:151], v210 offset:1024
	ds_read_b128 v[152:155], v210 offset:2048
	ds_read_b128 v[156:159], v210 offset:3072
	s_add_u32 s8, s6, 0xfffc0080
	s_addc_u32 s9, s7, -1
	s_cmp_eq_u32 s78, 12
	s_cselect_b32 s51, s18, s9
	s_cselect_b32 s50, s43, s8
	s_cselect_b32 s9, s45, s57
	s_cselect_b32 s8, s55, s56
	v_lshl_add_u64 v[206:207], s[6:7], 0, v[170:171]
	s_add_i32 m0, s17, 0xc000
	ds_read_b128 v[178:181], v211
	ds_read_b128 v[182:185], v211 offset:1024
	ds_read_b128 v[186:189], v211 offset:2048
	ds_read_b128 v[190:193], v211 offset:3072
	ds_read_b128 v[194:197], v211 offset:4096
	ds_read_b128 v[198:201], v211 offset:5120
	ds_read_b128 v[202:205], v211 offset:6144
	ds_read_b128 v[218:221], v211 offset:7168
	global_load_lds_dwordx4 v[206:207], off
	s_add_i32 m0, s17, 0xe000
	v_lshl_add_u64 v[206:207], s[6:7], 0, v[172:173]
	global_load_lds_dwordx4 v[206:207], off
	s_waitcnt vmcnt(8) lgkmcnt(0)
	s_barrier
	s_setprio 1
	v_mfma_f32_16x16x32_bf16 v[140:143], v[96:99], v[178:181], v[140:143]
	v_mfma_f32_16x16x32_bf16 v[140:143], v[100:103], v[182:185], v[140:143]
	v_mfma_f32_16x16x32_bf16 v[136:139], v[120:123], v[178:181], v[136:139]
	v_mfma_f32_16x16x32_bf16 v[136:139], v[124:127], v[182:185], v[136:139]
	v_mfma_f32_16x16x32_bf16 v[112:115], v[120:123], v[186:189], v[112:115]
	v_mfma_f32_16x16x32_bf16 v[112:115], v[124:127], v[190:193], v[112:115]
	v_mfma_f32_16x16x32_bf16 v[116:119], v[96:99], v[186:189], v[116:119]
	v_mfma_f32_16x16x32_bf16 v[116:119], v[100:103], v[190:193], v[116:119]
	v_mfma_f32_16x16x32_bf16 v[92:95], v[96:99], v[194:197], v[92:95]
	v_mfma_f32_16x16x32_bf16 v[92:95], v[100:103], v[198:201], v[92:95]
	v_mfma_f32_16x16x32_bf16 v[88:91], v[120:123], v[194:197], v[88:91]
	v_mfma_f32_16x16x32_bf16 v[88:91], v[124:127], v[198:201], v[88:91]
	v_mfma_f32_16x16x32_bf16 v[72:75], v[120:123], v[202:205], v[72:75]
	v_mfma_f32_16x16x32_bf16 v[72:75], v[124:127], v[218:221], v[72:75]
	v_mfma_f32_16x16x32_bf16 v[76:79], v[96:99], v[202:205], v[76:79]
	v_mfma_f32_16x16x32_bf16 v[76:79], v[100:103], v[218:221], v[76:79]
	v_mfma_f32_16x16x32_bf16 v[132:135], v[144:147], v[178:181], v[132:135]
	v_mfma_f32_16x16x32_bf16 v[132:135], v[148:151], v[182:185], v[132:135]
	v_mfma_f32_16x16x32_bf16 v[128:131], v[152:155], v[178:181], v[128:131]
	v_mfma_f32_16x16x32_bf16 v[128:131], v[156:159], v[182:185], v[128:131]
	v_mfma_f32_16x16x32_bf16 v[104:107], v[152:155], v[186:189], v[104:107]
	v_mfma_f32_16x16x32_bf16 v[104:107], v[156:159], v[190:193], v[104:107]
	v_mfma_f32_16x16x32_bf16 v[108:111], v[144:147], v[186:189], v[108:111]
	v_mfma_f32_16x16x32_bf16 v[108:111], v[148:151], v[190:193], v[108:111]
	v_mfma_f32_16x16x32_bf16 v[84:87], v[144:147], v[194:197], v[84:87]
	v_mfma_f32_16x16x32_bf16 v[84:87], v[148:151], v[198:201], v[84:87]
	v_mfma_f32_16x16x32_bf16 v[80:83], v[152:155], v[194:197], v[80:83]
	v_mfma_f32_16x16x32_bf16 v[80:83], v[156:159], v[198:201], v[80:83]
	s_setprio 2
	s_barrier
	v_mfma_f32_16x16x32_bf16 v[64:67], v[152:155], v[202:205], v[64:67]
	v_mfma_f32_16x16x32_bf16 v[64:67], v[156:159], v[218:221], v[64:67]
	v_mfma_f32_16x16x32_bf16 v[68:71], v[144:147], v[202:205], v[68:71]
	v_mfma_f32_16x16x32_bf16 v[68:71], v[148:151], v[218:221], v[68:71]
	s_setprio 2
	s_add_i32 s79, s73, s61
	v_lshl_add_u64 v[206:207], s[8:9], 0, v[162:163]
	s_mov_b32 m0, s79
	ds_read_b128 v[178:181], v211 offset:16384
	ds_read_b128 v[182:185], v211 offset:17408
	ds_read_b128 v[186:189], v211 offset:18432
	ds_read_b128 v[190:193], v211 offset:19456
	ds_read_b128 v[194:197], v211 offset:20480
	ds_read_b128 v[198:201], v211 offset:21504
	ds_read_b128 v[202:205], v211 offset:22528
	ds_read_b128 v[218:221], v211 offset:23552
	global_load_lds_dwordx4 v[206:207], off
	s_add_i32 m0, s79, 0x2000
	s_add_u32 s80, s8, 0x40000
	v_lshl_add_u64 v[222:223], s[8:9], 0, v[166:167]
	s_addc_u32 s81, s9, 0
	s_add_i32 s79, s74, s61
	global_load_lds_dwordx4 v[222:223], off
	v_lshl_add_u64 v[224:225], s[80:81], 0, v[162:163]
	s_mov_b32 m0, s79
	v_lshl_add_u64 v[226:227], s[50:51], 0, v[164:165]
	global_load_lds_dwordx4 v[224:225], off
	s_add_i32 m0, s79, 0x2000
	v_lshl_add_u64 v[224:225], s[80:81], 0, v[166:167]
	global_load_lds_dwordx4 v[224:225], off
	s_mov_b32 m0, s17
	v_lshl_add_u64 v[224:225], s[50:51], 0, v[160:161]
	global_load_lds_dwordx4 v[224:225], off
	s_mov_b32 m0, s62
	s_nop 0
	global_load_lds_dwordx4 v[226:227], off
	s_waitcnt vmcnt(8) lgkmcnt(0)
	s_barrier
	s_setprio 1
	v_mfma_f32_16x16x32_bf16 v[60:63], v[96:99], v[178:181], v[60:63]
	v_mfma_f32_16x16x32_bf16 v[60:63], v[100:103], v[182:185], v[60:63]
	v_mfma_f32_16x16x32_bf16 v[56:59], v[120:123], v[178:181], v[56:59]
	v_mfma_f32_16x16x32_bf16 v[56:59], v[124:127], v[182:185], v[56:59]
	v_mfma_f32_16x16x32_bf16 v[40:43], v[120:123], v[186:189], v[40:43]
	v_mfma_f32_16x16x32_bf16 v[40:43], v[124:127], v[190:193], v[40:43]
	v_mfma_f32_16x16x32_bf16 v[44:47], v[96:99], v[186:189], v[44:47]
	v_mfma_f32_16x16x32_bf16 v[44:47], v[100:103], v[190:193], v[44:47]
	v_mfma_f32_16x16x32_bf16 v[28:31], v[96:99], v[194:197], v[28:31]
	v_mfma_f32_16x16x32_bf16 v[28:31], v[100:103], v[198:201], v[28:31]
	v_mfma_f32_16x16x32_bf16 v[24:27], v[120:123], v[194:197], v[24:27]
	v_mfma_f32_16x16x32_bf16 v[24:27], v[124:127], v[198:201], v[24:27]
	v_mfma_f32_16x16x32_bf16 v[8:11], v[120:123], v[202:205], v[8:11]
	v_mfma_f32_16x16x32_bf16 v[8:11], v[124:127], v[218:221], v[8:11]
	v_mfma_f32_16x16x32_bf16 v[12:15], v[96:99], v[202:205], v[12:15]
	v_mfma_f32_16x16x32_bf16 v[12:15], v[100:103], v[218:221], v[12:15]
	v_mfma_f32_16x16x32_bf16 v[52:55], v[144:147], v[178:181], v[52:55]
	v_mfma_f32_16x16x32_bf16 v[52:55], v[148:151], v[182:185], v[52:55]
	v_mfma_f32_16x16x32_bf16 v[48:51], v[152:155], v[178:181], v[48:51]
	v_mfma_f32_16x16x32_bf16 v[48:51], v[156:159], v[182:185], v[48:51]
	v_mfma_f32_16x16x32_bf16 v[32:35], v[152:155], v[186:189], v[32:35]
	v_mfma_f32_16x16x32_bf16 v[32:35], v[156:159], v[190:193], v[32:35]
	v_mfma_f32_16x16x32_bf16 v[36:39], v[144:147], v[186:189], v[36:39]
	v_mfma_f32_16x16x32_bf16 v[36:39], v[148:151], v[190:193], v[36:39]
	v_mfma_f32_16x16x32_bf16 v[20:23], v[144:147], v[194:197], v[20:23]
	v_mfma_f32_16x16x32_bf16 v[20:23], v[148:151], v[198:201], v[20:23]
	v_mfma_f32_16x16x32_bf16 v[16:19], v[152:155], v[194:197], v[16:19]
	v_mfma_f32_16x16x32_bf16 v[16:19], v[156:159], v[198:201], v[16:19]
	s_setprio 2
	s_barrier
	v_mfma_f32_16x16x32_bf16 v[0:3], v[152:155], v[202:205], v[0:3]
	v_mfma_f32_16x16x32_bf16 v[0:3], v[156:159], v[218:221], v[0:3]
	v_mfma_f32_16x16x32_bf16 v[4:7], v[144:147], v[202:205], v[4:7]
	v_mfma_f32_16x16x32_bf16 v[4:7], v[148:151], v[218:221], v[4:7]
	s_setprio 0
	s_add_i32 s79, 0, 0x18000
	s_add_i32 s80, 0, 0x1c000
	v_add_u32_e32 v124, s79, v208
	v_add_u32_e32 v156, s80, v208
	ds_read_b128 v[96:99], v124
	ds_read_b128 v[100:103], v124 offset:1024
	ds_read_b128 v[120:123], v124 offset:2048
	ds_read_b128 v[124:127], v124 offset:3072
	ds_read_b128 v[144:147], v156
	ds_read_b128 v[148:151], v156 offset:1024
	ds_read_b128 v[152:155], v156 offset:2048
	ds_read_b128 v[156:159], v156 offset:3072
	s_add_u32 s50, s50, 0x40000
	s_addc_u32 s51, s51, 0
	s_mov_b32 m0, s63
	v_lshl_add_u64 v[228:229], s[50:51], 0, v[160:161]
	ds_read_b128 v[178:181], v211 offset:32768
	ds_read_b128 v[182:185], v211 offset:33792
	ds_read_b128 v[186:189], v211 offset:34816
	ds_read_b128 v[190:193], v211 offset:35840
	ds_read_b128 v[194:197], v211 offset:36864
	ds_read_b128 v[198:201], v211 offset:37888
	ds_read_b128 v[202:205], v211 offset:38912
	ds_read_b128 v[218:221], v211 offset:39936
	global_load_lds_dwordx4 v[228:229], off
	s_mov_b32 m0, s64
	v_lshl_add_u64 v[228:229], s[50:51], 0, v[164:165]
	global_load_lds_dwordx4 v[228:229], off
	s_waitcnt vmcnt(8) lgkmcnt(0)
	s_barrier
	s_setprio 1
	v_mfma_f32_16x16x32_bf16 v[140:143], v[96:99], v[178:181], v[140:143]
	v_mfma_f32_16x16x32_bf16 v[140:143], v[100:103], v[182:185], v[140:143]
	v_mfma_f32_16x16x32_bf16 v[136:139], v[120:123], v[178:181], v[136:139]
	v_mfma_f32_16x16x32_bf16 v[136:139], v[124:127], v[182:185], v[136:139]
	v_mfma_f32_16x16x32_bf16 v[112:115], v[120:123], v[186:189], v[112:115]
	v_mfma_f32_16x16x32_bf16 v[112:115], v[124:127], v[190:193], v[112:115]
	v_mfma_f32_16x16x32_bf16 v[116:119], v[96:99], v[186:189], v[116:119]
	v_mfma_f32_16x16x32_bf16 v[116:119], v[100:103], v[190:193], v[116:119]
	v_mfma_f32_16x16x32_bf16 v[92:95], v[96:99], v[194:197], v[92:95]
	v_mfma_f32_16x16x32_bf16 v[92:95], v[100:103], v[198:201], v[92:95]
	v_mfma_f32_16x16x32_bf16 v[88:91], v[120:123], v[194:197], v[88:91]
	v_mfma_f32_16x16x32_bf16 v[88:91], v[124:127], v[198:201], v[88:91]
	v_mfma_f32_16x16x32_bf16 v[72:75], v[120:123], v[202:205], v[72:75]
	v_mfma_f32_16x16x32_bf16 v[72:75], v[124:127], v[218:221], v[72:75]
	v_mfma_f32_16x16x32_bf16 v[76:79], v[96:99], v[202:205], v[76:79]
	v_mfma_f32_16x16x32_bf16 v[76:79], v[100:103], v[218:221], v[76:79]
	v_mfma_f32_16x16x32_bf16 v[132:135], v[144:147], v[178:181], v[132:135]
	v_mfma_f32_16x16x32_bf16 v[132:135], v[148:151], v[182:185], v[132:135]
	v_mfma_f32_16x16x32_bf16 v[128:131], v[152:155], v[178:181], v[128:131]
	v_mfma_f32_16x16x32_bf16 v[128:131], v[156:159], v[182:185], v[128:131]
	v_mfma_f32_16x16x32_bf16 v[104:107], v[152:155], v[186:189], v[104:107]
	v_mfma_f32_16x16x32_bf16 v[104:107], v[156:159], v[190:193], v[104:107]
	v_mfma_f32_16x16x32_bf16 v[108:111], v[144:147], v[186:189], v[108:111]
	v_mfma_f32_16x16x32_bf16 v[108:111], v[148:151], v[190:193], v[108:111]
	v_mfma_f32_16x16x32_bf16 v[84:87], v[144:147], v[194:197], v[84:87]
	v_mfma_f32_16x16x32_bf16 v[84:87], v[148:151], v[198:201], v[84:87]
	v_mfma_f32_16x16x32_bf16 v[80:83], v[152:155], v[194:197], v[80:83]
	v_mfma_f32_16x16x32_bf16 v[80:83], v[156:159], v[198:201], v[80:83]
	s_setprio 2
	s_barrier
	v_mfma_f32_16x16x32_bf16 v[64:67], v[152:155], v[202:205], v[64:67]
	v_mfma_f32_16x16x32_bf16 v[64:67], v[156:159], v[218:221], v[64:67]
	v_mfma_f32_16x16x32_bf16 v[68:71], v[144:147], v[202:205], v[68:71]
	v_mfma_f32_16x16x32_bf16 v[68:71], v[148:151], v[218:221], v[68:71]
	s_setprio 2
	s_add_i32 s50, s79, s61
	v_lshl_add_u64 v[206:207], v[206:207], 0, s[36:37]
	s_mov_b32 m0, s50
	ds_read_b128 v[178:181], v211 offset:49152
	ds_read_b128 v[182:185], v211 offset:50176
	ds_read_b128 v[186:189], v211 offset:51200
	ds_read_b128 v[190:193], v211 offset:52224
	ds_read_b128 v[194:197], v211 offset:53248
	ds_read_b128 v[198:201], v211 offset:54272
	ds_read_b128 v[202:205], v211 offset:55296
	ds_read_b128 v[218:221], v211 offset:56320
	global_load_lds_dwordx4 v[206:207], off
	s_add_i32 m0, s50, 0x2000
	s_add_u32 s8, s8, 0x40080
	v_lshl_add_u64 v[206:207], v[222:223], 0, s[36:37]
	s_addc_u32 s9, s9, 0
	s_add_i32 s50, s80, s61
	global_load_lds_dwordx4 v[206:207], off
	s_mov_b32 m0, s50
	v_lshl_add_u64 v[206:207], s[8:9], 0, v[162:163]
	global_load_lds_dwordx4 v[206:207], off
	s_add_i32 m0, s50, 0x2000
	v_lshl_add_u64 v[206:207], s[8:9], 0, v[166:167]
	global_load_lds_dwordx4 v[206:207], off
	s_mov_b32 m0, s68
	v_lshl_add_u64 v[206:207], v[224:225], 0, s[36:37]
	global_load_lds_dwordx4 v[206:207], off
	s_mov_b32 m0, s69
	v_lshl_add_u64 v[206:207], v[226:227], 0, s[36:37]
	global_load_lds_dwordx4 v[206:207], off
	s_waitcnt vmcnt(8) lgkmcnt(0)
	s_barrier
	s_setprio 1
	v_mfma_f32_16x16x32_bf16 v[60:63], v[96:99], v[178:181], v[60:63]
	v_mfma_f32_16x16x32_bf16 v[60:63], v[100:103], v[182:185], v[60:63]
	v_mfma_f32_16x16x32_bf16 v[56:59], v[120:123], v[178:181], v[56:59]
	v_mfma_f32_16x16x32_bf16 v[56:59], v[124:127], v[182:185], v[56:59]
	v_mfma_f32_16x16x32_bf16 v[40:43], v[120:123], v[186:189], v[40:43]
	v_mfma_f32_16x16x32_bf16 v[40:43], v[124:127], v[190:193], v[40:43]
	v_mfma_f32_16x16x32_bf16 v[44:47], v[96:99], v[186:189], v[44:47]
	v_mfma_f32_16x16x32_bf16 v[44:47], v[100:103], v[190:193], v[44:47]
	v_mfma_f32_16x16x32_bf16 v[28:31], v[96:99], v[194:197], v[28:31]
	v_mfma_f32_16x16x32_bf16 v[28:31], v[100:103], v[198:201], v[28:31]
	v_mfma_f32_16x16x32_bf16 v[24:27], v[120:123], v[194:197], v[24:27]
	v_mfma_f32_16x16x32_bf16 v[24:27], v[124:127], v[198:201], v[24:27]
	v_mfma_f32_16x16x32_bf16 v[8:11], v[120:123], v[202:205], v[8:11]
	v_mfma_f32_16x16x32_bf16 v[8:11], v[124:127], v[218:221], v[8:11]
	v_mfma_f32_16x16x32_bf16 v[12:15], v[96:99], v[202:205], v[12:15]
	v_mfma_f32_16x16x32_bf16 v[12:15], v[100:103], v[218:221], v[12:15]
	v_mfma_f32_16x16x32_bf16 v[52:55], v[144:147], v[178:181], v[52:55]
	v_mfma_f32_16x16x32_bf16 v[52:55], v[148:151], v[182:185], v[52:55]
	v_mfma_f32_16x16x32_bf16 v[48:51], v[152:155], v[178:181], v[48:51]
	v_mfma_f32_16x16x32_bf16 v[48:51], v[156:159], v[182:185], v[48:51]
	v_mfma_f32_16x16x32_bf16 v[32:35], v[152:155], v[186:189], v[32:35]
	v_mfma_f32_16x16x32_bf16 v[32:35], v[156:159], v[190:193], v[32:35]
	v_mfma_f32_16x16x32_bf16 v[36:39], v[144:147], v[186:189], v[36:39]
	v_mfma_f32_16x16x32_bf16 v[36:39], v[148:151], v[190:193], v[36:39]
	v_mfma_f32_16x16x32_bf16 v[20:23], v[144:147], v[194:197], v[20:23]
	v_mfma_f32_16x16x32_bf16 v[20:23], v[148:151], v[198:201], v[20:23]
	v_mfma_f32_16x16x32_bf16 v[16:19], v[152:155], v[194:197], v[16:19]
	v_mfma_f32_16x16x32_bf16 v[16:19], v[156:159], v[198:201], v[16:19]
	s_setprio 2
	s_barrier
	v_mfma_f32_16x16x32_bf16 v[0:3], v[152:155], v[202:205], v[0:3]
	v_mfma_f32_16x16x32_bf16 v[0:3], v[156:159], v[218:221], v[0:3]
	v_mfma_f32_16x16x32_bf16 v[4:7], v[144:147], v[202:205], v[4:7]
	v_mfma_f32_16x16x32_bf16 v[4:7], v[148:151], v[218:221], v[4:7]
	s_setprio 0
	s_add_i32 s78, s78, 2
	s_add_u32 s6, s6, 0x100
	s_addc_u32 s7, s7, 0
	s_add_u32 s56, s56, 0x100
	s_addc_u32 s57, s57, 0
	s_cmp_gt_u32 s78, 13
	s_cbranch_scc0 .LBB0_323

.LBB0_700:
	ds_read_b128 v[130:133], v203
	ds_read_b128 v[134:137], v203 offset:1024
	ds_read_b128 v[138:141], v203 offset:2048
	ds_read_b128 v[142:145], v203 offset:3072
	ds_read_b128 v[146:149], v195
	ds_read_b128 v[150:153], v195 offset:1024
	ds_read_b128 v[154:157], v195 offset:2048
	ds_read_b128 v[158:161], v195 offset:3072
	s_add_u32 s47, s44, 0xfff80080
	s_addc_u32 s48, s45, -1
	s_cmp_eq_u32 s46, 28
	s_cselect_b32 s49, s29, s48
	s_cselect_b32 s48, s71, s47
	s_cselect_b32 s47, s31, s84
	s_cselect_b32 s46, s72, s83
	s_mov_b32 m0, s73
	v_lshl_add_u64 v[174:175], s[44:45], 0, v[180:181]
	ds_read_b128 v[162:165], v211
	ds_read_b128 v[166:169], v211 offset:1024
	ds_read_b128 v[170:173], v211 offset:2048
	ds_read_b128 v[184:187], v211 offset:3072
	ds_read_b128 v[190:193], v211 offset:4096
	ds_read_b128 v[196:199], v211 offset:5120
	ds_read_b128 v[204:207], v211 offset:6144
	ds_read_b128 v[212:215], v211 offset:7168
	global_load_lds_dwordx4 v[174:175], off
	s_mov_b32 m0, s74
	v_lshl_add_u64 v[174:175], s[44:45], 0, v[182:183]
	global_load_lds_dwordx4 v[174:175], off
	s_waitcnt vmcnt(8) lgkmcnt(0)
	s_barrier
	s_setprio 1
	v_mfma_f32_16x16x32_bf16 v[124:127], v[130:133], v[162:165], v[124:127]
	v_mfma_f32_16x16x32_bf16 v[124:127], v[134:137], v[166:169], v[124:127]
	v_mfma_f32_16x16x32_bf16 v[120:123], v[138:141], v[162:165], v[120:123]
	v_mfma_f32_16x16x32_bf16 v[120:123], v[142:145], v[166:169], v[120:123]
	v_mfma_f32_16x16x32_bf16 v[104:107], v[138:141], v[170:173], v[104:107]
	v_mfma_f32_16x16x32_bf16 v[104:107], v[142:145], v[184:187], v[104:107]
	v_mfma_f32_16x16x32_bf16 v[108:111], v[130:133], v[170:173], v[108:111]
	v_mfma_f32_16x16x32_bf16 v[108:111], v[134:137], v[184:187], v[108:111]
	v_mfma_f32_16x16x32_bf16 v[92:95], v[130:133], v[190:193], v[92:95]
	v_mfma_f32_16x16x32_bf16 v[92:95], v[134:137], v[196:199], v[92:95]
	v_mfma_f32_16x16x32_bf16 v[88:91], v[138:141], v[190:193], v[88:91]
	v_mfma_f32_16x16x32_bf16 v[88:91], v[142:145], v[196:199], v[88:91]
	v_mfma_f32_16x16x32_bf16 v[72:75], v[138:141], v[204:207], v[72:75]
	v_mfma_f32_16x16x32_bf16 v[72:75], v[142:145], v[212:215], v[72:75]
	v_mfma_f32_16x16x32_bf16 v[76:79], v[130:133], v[204:207], v[76:79]
	v_mfma_f32_16x16x32_bf16 v[76:79], v[134:137], v[212:215], v[76:79]
	v_mfma_f32_16x16x32_bf16 v[116:119], v[146:149], v[162:165], v[116:119]
	v_mfma_f32_16x16x32_bf16 v[116:119], v[150:153], v[166:169], v[116:119]
	v_mfma_f32_16x16x32_bf16 v[112:115], v[154:157], v[162:165], v[112:115]
	v_mfma_f32_16x16x32_bf16 v[112:115], v[158:161], v[166:169], v[112:115]
	v_mfma_f32_16x16x32_bf16 v[96:99], v[154:157], v[170:173], v[96:99]
	v_mfma_f32_16x16x32_bf16 v[96:99], v[158:161], v[184:187], v[96:99]
	v_mfma_f32_16x16x32_bf16 v[100:103], v[146:149], v[170:173], v[100:103]
	v_mfma_f32_16x16x32_bf16 v[100:103], v[150:153], v[184:187], v[100:103]
	v_mfma_f32_16x16x32_bf16 v[84:87], v[146:149], v[190:193], v[84:87]
	v_mfma_f32_16x16x32_bf16 v[84:87], v[150:153], v[196:199], v[84:87]
	v_mfma_f32_16x16x32_bf16 v[80:83], v[154:157], v[190:193], v[80:83]
	v_mfma_f32_16x16x32_bf16 v[80:83], v[158:161], v[196:199], v[80:83]
	s_setprio 2
	s_barrier
	v_mfma_f32_16x16x32_bf16 v[64:67], v[154:157], v[204:207], v[64:67]
	v_mfma_f32_16x16x32_bf16 v[64:67], v[158:161], v[212:215], v[64:67]
	v_mfma_f32_16x16x32_bf16 v[68:71], v[146:149], v[204:207], v[68:71]
	v_mfma_f32_16x16x32_bf16 v[68:71], v[150:153], v[212:215], v[68:71]
	s_setprio 2
	s_mov_b32 m0, s75
	v_lshl_add_u64 v[174:175], s[46:47], 0, v[176:177]
	s_add_u32 s86, s46, 0x80000
	ds_read_b128 v[162:165], v211 offset:16384
	ds_read_b128 v[166:169], v211 offset:17408
	ds_read_b128 v[170:173], v211 offset:18432
	ds_read_b128 v[184:187], v211 offset:19456
	ds_read_b128 v[190:193], v211 offset:20480
	ds_read_b128 v[196:199], v211 offset:21504
	ds_read_b128 v[204:207], v211 offset:22528
	ds_read_b128 v[212:215], v211 offset:23552
	global_load_lds_dwordx4 v[174:175], off
	v_lshl_add_u64 v[200:201], s[46:47], 0, v[178:179]
	s_mov_b32 m0, s76
	s_addc_u32 s87, s47, 0
	global_load_lds_dwordx4 v[200:201], off
	v_lshl_add_u64 v[208:209], s[86:87], 0, v[176:177]
	s_mov_b32 m0, s77
	v_lshl_add_u64 v[216:217], s[48:49], 0, v[178:179]
	global_load_lds_dwordx4 v[208:209], off
	s_mov_b32 m0, s78
	v_lshl_add_u64 v[208:209], s[86:87], 0, v[178:179]
	global_load_lds_dwordx4 v[208:209], off
	s_mov_b32 m0, s56
	v_lshl_add_u64 v[208:209], s[48:49], 0, v[176:177]
	global_load_lds_dwordx4 v[208:209], off
	s_mov_b32 m0, s57
	s_nop 0
	global_load_lds_dwordx4 v[216:217], off
	s_waitcnt vmcnt(8) lgkmcnt(0)
	s_barrier
	s_setprio 1
	v_mfma_f32_16x16x32_bf16 v[60:63], v[130:133], v[162:165], v[60:63]
	v_mfma_f32_16x16x32_bf16 v[60:63], v[134:137], v[166:169], v[60:63]
	v_mfma_f32_16x16x32_bf16 v[56:59], v[138:141], v[162:165], v[56:59]
	v_mfma_f32_16x16x32_bf16 v[56:59], v[142:145], v[166:169], v[56:59]
	v_mfma_f32_16x16x32_bf16 v[40:43], v[138:141], v[170:173], v[40:43]
	v_mfma_f32_16x16x32_bf16 v[40:43], v[142:145], v[184:187], v[40:43]
	v_mfma_f32_16x16x32_bf16 v[44:47], v[130:133], v[170:173], v[44:47]
	v_mfma_f32_16x16x32_bf16 v[44:47], v[134:137], v[184:187], v[44:47]
	v_mfma_f32_16x16x32_bf16 v[28:31], v[130:133], v[190:193], v[28:31]
	v_mfma_f32_16x16x32_bf16 v[28:31], v[134:137], v[196:199], v[28:31]
	v_mfma_f32_16x16x32_bf16 v[24:27], v[138:141], v[190:193], v[24:27]
	v_mfma_f32_16x16x32_bf16 v[24:27], v[142:145], v[196:199], v[24:27]
	v_mfma_f32_16x16x32_bf16 v[8:11], v[138:141], v[204:207], v[8:11]
	v_mfma_f32_16x16x32_bf16 v[8:11], v[142:145], v[212:215], v[8:11]
	v_mfma_f32_16x16x32_bf16 v[12:15], v[130:133], v[204:207], v[12:15]
	v_mfma_f32_16x16x32_bf16 v[12:15], v[134:137], v[212:215], v[12:15]
	v_mfma_f32_16x16x32_bf16 v[52:55], v[146:149], v[162:165], v[52:55]
	v_mfma_f32_16x16x32_bf16 v[52:55], v[150:153], v[166:169], v[52:55]
	v_mfma_f32_16x16x32_bf16 v[48:51], v[154:157], v[162:165], v[48:51]
	v_mfma_f32_16x16x32_bf16 v[48:51], v[158:161], v[166:169], v[48:51]
	v_mfma_f32_16x16x32_bf16 v[32:35], v[154:157], v[170:173], v[32:35]
	v_mfma_f32_16x16x32_bf16 v[32:35], v[158:161], v[184:187], v[32:35]
	v_mfma_f32_16x16x32_bf16 v[36:39], v[146:149], v[170:173], v[36:39]
	v_mfma_f32_16x16x32_bf16 v[36:39], v[150:153], v[184:187], v[36:39]
	v_mfma_f32_16x16x32_bf16 v[20:23], v[146:149], v[190:193], v[20:23]
	v_mfma_f32_16x16x32_bf16 v[20:23], v[150:153], v[196:199], v[20:23]
	v_mfma_f32_16x16x32_bf16 v[16:19], v[154:157], v[190:193], v[16:19]
	v_mfma_f32_16x16x32_bf16 v[16:19], v[158:161], v[196:199], v[16:19]
	s_setprio 2
	s_barrier
	v_mfma_f32_16x16x32_bf16 v[0:3], v[154:157], v[204:207], v[0:3]
	v_mfma_f32_16x16x32_bf16 v[0:3], v[158:161], v[212:215], v[0:3]
	v_mfma_f32_16x16x32_bf16 v[4:7], v[146:149], v[204:207], v[4:7]
	v_mfma_f32_16x16x32_bf16 v[4:7], v[150:153], v[212:215], v[4:7]
	s_setprio 0
	ds_read_b128 v[130:133], v128
	ds_read_b128 v[134:137], v128 offset:1024
	ds_read_b128 v[138:141], v128 offset:2048
	ds_read_b128 v[142:145], v128 offset:3072
	ds_read_b128 v[146:149], v129
	ds_read_b128 v[150:153], v129 offset:1024
	ds_read_b128 v[154:157], v129 offset:2048
	ds_read_b128 v[158:161], v129 offset:3072
	s_add_u32 s48, s48, 0x80000
	s_addc_u32 s49, s49, 0
	s_mov_b32 m0, s58
	v_lshl_add_u64 v[218:219], s[48:49], 0, v[176:177]
	ds_read_b128 v[162:165], v211 offset:32768
	ds_read_b128 v[166:169], v211 offset:33792
	ds_read_b128 v[170:173], v211 offset:34816
	ds_read_b128 v[184:187], v211 offset:35840
	ds_read_b128 v[190:193], v211 offset:36864
	ds_read_b128 v[196:199], v211 offset:37888
	ds_read_b128 v[204:207], v211 offset:38912
	ds_read_b128 v[212:215], v211 offset:39936
	global_load_lds_dwordx4 v[218:219], off
	s_mov_b32 m0, s59
	v_lshl_add_u64 v[218:219], s[48:49], 0, v[178:179]
	global_load_lds_dwordx4 v[218:219], off
	s_waitcnt vmcnt(8) lgkmcnt(0)
	s_barrier
	s_setprio 1
	v_mfma_f32_16x16x32_bf16 v[124:127], v[130:133], v[162:165], v[124:127]
	v_mfma_f32_16x16x32_bf16 v[124:127], v[134:137], v[166:169], v[124:127]
	v_mfma_f32_16x16x32_bf16 v[120:123], v[138:141], v[162:165], v[120:123]
	v_mfma_f32_16x16x32_bf16 v[120:123], v[142:145], v[166:169], v[120:123]
	v_mfma_f32_16x16x32_bf16 v[104:107], v[138:141], v[170:173], v[104:107]
	v_mfma_f32_16x16x32_bf16 v[104:107], v[142:145], v[184:187], v[104:107]
	v_mfma_f32_16x16x32_bf16 v[108:111], v[130:133], v[170:173], v[108:111]
	v_mfma_f32_16x16x32_bf16 v[108:111], v[134:137], v[184:187], v[108:111]
	v_mfma_f32_16x16x32_bf16 v[92:95], v[130:133], v[190:193], v[92:95]
	v_mfma_f32_16x16x32_bf16 v[92:95], v[134:137], v[196:199], v[92:95]
	v_mfma_f32_16x16x32_bf16 v[88:91], v[138:141], v[190:193], v[88:91]
	v_mfma_f32_16x16x32_bf16 v[88:91], v[142:145], v[196:199], v[88:91]
	v_mfma_f32_16x16x32_bf16 v[72:75], v[138:141], v[204:207], v[72:75]
	v_mfma_f32_16x16x32_bf16 v[72:75], v[142:145], v[212:215], v[72:75]
	v_mfma_f32_16x16x32_bf16 v[76:79], v[130:133], v[204:207], v[76:79]
	v_mfma_f32_16x16x32_bf16 v[76:79], v[134:137], v[212:215], v[76:79]
	v_mfma_f32_16x16x32_bf16 v[116:119], v[146:149], v[162:165], v[116:119]
	v_mfma_f32_16x16x32_bf16 v[116:119], v[150:153], v[166:169], v[116:119]
	v_mfma_f32_16x16x32_bf16 v[112:115], v[154:157], v[162:165], v[112:115]
	v_mfma_f32_16x16x32_bf16 v[112:115], v[158:161], v[166:169], v[112:115]
	v_mfma_f32_16x16x32_bf16 v[96:99], v[154:157], v[170:173], v[96:99]
	v_mfma_f32_16x16x32_bf16 v[96:99], v[158:161], v[184:187], v[96:99]
	v_mfma_f32_16x16x32_bf16 v[100:103], v[146:149], v[170:173], v[100:103]
	v_mfma_f32_16x16x32_bf16 v[100:103], v[150:153], v[184:187], v[100:103]
	v_mfma_f32_16x16x32_bf16 v[84:87], v[146:149], v[190:193], v[84:87]
	v_mfma_f32_16x16x32_bf16 v[84:87], v[150:153], v[196:199], v[84:87]
	v_mfma_f32_16x16x32_bf16 v[80:83], v[154:157], v[190:193], v[80:83]
	v_mfma_f32_16x16x32_bf16 v[80:83], v[158:161], v[196:199], v[80:83]
	s_setprio 2
	s_barrier
	v_mfma_f32_16x16x32_bf16 v[64:67], v[154:157], v[204:207], v[64:67]
	v_mfma_f32_16x16x32_bf16 v[64:67], v[158:161], v[212:215], v[64:67]
	v_mfma_f32_16x16x32_bf16 v[68:71], v[146:149], v[204:207], v[68:71]
	v_mfma_f32_16x16x32_bf16 v[68:71], v[150:153], v[212:215], v[68:71]
	s_setprio 2
	s_mov_b32 m0, s79
	v_lshl_add_u64 v[174:175], v[174:175], 0, s[20:21]
	s_add_u32 s46, s46, 0x80080
	ds_read_b128 v[162:165], v211 offset:49152
	ds_read_b128 v[166:169], v211 offset:50176
	ds_read_b128 v[170:173], v211 offset:51200
	ds_read_b128 v[184:187], v211 offset:52224
	ds_read_b128 v[190:193], v211 offset:53248
	ds_read_b128 v[196:199], v211 offset:54272
	ds_read_b128 v[204:207], v211 offset:55296
	ds_read_b128 v[212:215], v211 offset:56320
	global_load_lds_dwordx4 v[174:175], off
	v_lshl_add_u64 v[174:175], v[200:201], 0, s[20:21]
	s_mov_b32 m0, s80
	s_addc_u32 s47, s47, 0
	global_load_lds_dwordx4 v[174:175], off
	s_mov_b32 m0, s81
	v_lshl_add_u64 v[174:175], s[46:47], 0, v[176:177]
	global_load_lds_dwordx4 v[174:175], off
	s_mov_b32 m0, s82
	v_lshl_add_u64 v[174:175], s[46:47], 0, v[178:179]
	global_load_lds_dwordx4 v[174:175], off
	s_mov_b32 m0, s61
	v_lshl_add_u64 v[174:175], v[208:209], 0, s[20:21]
	global_load_lds_dwordx4 v[174:175], off
	s_mov_b32 m0, s62
	v_lshl_add_u64 v[174:175], v[216:217], 0, s[20:21]
	global_load_lds_dwordx4 v[174:175], off
	s_waitcnt vmcnt(8) lgkmcnt(0)
	s_barrier
	s_setprio 1
	v_mfma_f32_16x16x32_bf16 v[60:63], v[130:133], v[162:165], v[60:63]
	v_mfma_f32_16x16x32_bf16 v[60:63], v[134:137], v[166:169], v[60:63]
	v_mfma_f32_16x16x32_bf16 v[56:59], v[138:141], v[162:165], v[56:59]
	v_mfma_f32_16x16x32_bf16 v[56:59], v[142:145], v[166:169], v[56:59]
	v_mfma_f32_16x16x32_bf16 v[40:43], v[138:141], v[170:173], v[40:43]
	v_mfma_f32_16x16x32_bf16 v[40:43], v[142:145], v[184:187], v[40:43]
	v_mfma_f32_16x16x32_bf16 v[44:47], v[130:133], v[170:173], v[44:47]
	v_mfma_f32_16x16x32_bf16 v[44:47], v[134:137], v[184:187], v[44:47]
	v_mfma_f32_16x16x32_bf16 v[28:31], v[130:133], v[190:193], v[28:31]
	v_mfma_f32_16x16x32_bf16 v[28:31], v[134:137], v[196:199], v[28:31]
	v_mfma_f32_16x16x32_bf16 v[24:27], v[138:141], v[190:193], v[24:27]
	v_mfma_f32_16x16x32_bf16 v[24:27], v[142:145], v[196:199], v[24:27]
	v_mfma_f32_16x16x32_bf16 v[8:11], v[138:141], v[204:207], v[8:11]
	v_mfma_f32_16x16x32_bf16 v[8:11], v[142:145], v[212:215], v[8:11]
	v_mfma_f32_16x16x32_bf16 v[12:15], v[130:133], v[204:207], v[12:15]
	v_mfma_f32_16x16x32_bf16 v[12:15], v[134:137], v[212:215], v[12:15]
	v_mfma_f32_16x16x32_bf16 v[52:55], v[146:149], v[162:165], v[52:55]
	v_mfma_f32_16x16x32_bf16 v[52:55], v[150:153], v[166:169], v[52:55]
	v_mfma_f32_16x16x32_bf16 v[48:51], v[154:157], v[162:165], v[48:51]
	v_mfma_f32_16x16x32_bf16 v[48:51], v[158:161], v[166:169], v[48:51]
	v_mfma_f32_16x16x32_bf16 v[32:35], v[154:157], v[170:173], v[32:35]
	v_mfma_f32_16x16x32_bf16 v[32:35], v[158:161], v[184:187], v[32:35]
	v_mfma_f32_16x16x32_bf16 v[36:39], v[146:149], v[170:173], v[36:39]
	v_mfma_f32_16x16x32_bf16 v[36:39], v[150:153], v[184:187], v[36:39]
	v_mfma_f32_16x16x32_bf16 v[20:23], v[146:149], v[190:193], v[20:23]
	v_mfma_f32_16x16x32_bf16 v[20:23], v[150:153], v[196:199], v[20:23]
	v_mfma_f32_16x16x32_bf16 v[16:19], v[154:157], v[190:193], v[16:19]
	v_mfma_f32_16x16x32_bf16 v[16:19], v[158:161], v[196:199], v[16:19]
	s_setprio 2
	s_barrier
	v_mfma_f32_16x16x32_bf16 v[0:3], v[154:157], v[204:207], v[0:3]
	v_mfma_f32_16x16x32_bf16 v[0:3], v[158:161], v[212:215], v[0:3]
	v_mfma_f32_16x16x32_bf16 v[4:7], v[146:149], v[204:207], v[4:7]
	v_mfma_f32_16x16x32_bf16 v[4:7], v[150:153], v[212:215], v[4:7]
	s_setprio 0
	s_add_i32 s70, s70, 1
	s_add_u32 s44, s44, 0x100
	s_addc_u32 s45, s45, 0
	s_add_u32 s83, s83, 0x100
	s_addc_u32 s84, s84, 0
	s_cmp_gt_u32 s85, 29
	s_cbranch_scc0 .LBB0_698
	s_lshl_b32 s29, s41, 12
	s_and_b32 s29, s29, 0x1000
	s_add_i32 s29, s29, 0
	v_mbcnt_lo_u32_b32 v128, -1, 0
	v_mbcnt_hi_u32_b32 v128, -1, v128
	s_add_i32 s29, s29, s63
	v_lshlrev_b32_e32 v128, 4, v128
	s_add_i32 s29, s29, 0x20400
	v_and_b32_e32 v128, 0xf0, v128
	v_add_u32_e32 v128, s29, v128
	ds_read2_b32 v[214:215], v128 offset0:3 offset1:67
	ds_read2_b32 v[206:207], v128 offset0:131 offset1:195
	v_add_u32_e32 v128, 12, v128
	ds_read2st64_b32 v[196:197], v128 offset0:8 offset1:9
	ds_read2st64_b32 v[190:191], v128 offset0:10 offset1:11
	s_and_b64 vcc, exec, s[22:23]
	s_waitcnt lgkmcnt(0)
	v_mov_b32_e32 v210, v215
	v_mov_b32_e32 v202, v207
	v_mov_b32_e32 v194, v197
	v_mov_b32_e32 v188, v191
	s_cbranch_vccz .LBB0_703
	s_barrier

.LBB0_783:
	s_ashr_i32 s23, s22, 31
	s_lshl_b64 s[26:27], s[22:23], 19
	s_add_u32 s26, s43, s26
	s_addc_u32 s27, s44, s27
	s_and_b64 s[28:29], s[4:5], exec
	s_cselect_b32 s23, s27, s37
	s_cselect_b32 s31, s26, s36
	s_ashr_i32 s25, s24, 31
	s_lshl_b64 s[28:29], s[24:25], 19
	s_add_u32 s28, s45, s28
	s_addc_u32 s29, s46, s29
	s_and_b64 s[40:41], s[4:5], exec
	s_cselect_b32 s25, s29, s39
	s_cselect_b32 s62, s28, s38
	s_add_u32 s36, s36, 0x40080
	s_addc_u32 s37, s37, 0
	s_add_u32 s63, s38, 0x100
	s_addc_u32 s64, s39, 0
	s_mov_b32 s65, -2
	ds_read_b128 v[144:147], v163
	ds_read_b128 v[148:151], v163 offset:1024
	ds_read_b128 v[152:155], v163 offset:2048
	ds_read_b128 v[156:159], v163 offset:3072
	ds_read_b128 v[168:171], v164
	ds_read_b128 v[172:175], v164 offset:1024
	ds_read_b128 v[176:179], v164 offset:2048
	ds_read_b128 v[180:183], v164 offset:3072
	s_add_u32 s38, s36, 0xfffc0080
	s_addc_u32 s39, s37, -1
	s_cmp_eq_u32 s65, 12
	s_cselect_b32 s41, s23, s39
	s_cselect_b32 s40, s31, s38
	s_cselect_b32 s39, s25, s64
	s_cselect_b32 s38, s62, s63
	v_lshl_add_u64 v[160:161], s[36:37], 0, v[136:137]
	s_add_i32 m0, s50, 0xc000
	ds_read_b128 v[184:187], v165
	ds_read_b128 v[188:191], v165 offset:1024
	ds_read_b128 v[192:195], v165 offset:2048
	ds_read_b128 v[196:199], v165 offset:3072
	ds_read_b128 v[200:203], v165 offset:4096
	ds_read_b128 v[204:207], v165 offset:5120
	ds_read_b128 v[208:211], v165 offset:6144
	ds_read_b128 v[212:215], v165 offset:7168
	global_load_lds_dwordx4 v[160:161], off
	s_add_i32 m0, s50, 0xe000
	v_lshl_add_u64 v[160:161], s[36:37], 0, v[138:139]
	global_load_lds_dwordx4 v[160:161], off
	s_waitcnt vmcnt(8) lgkmcnt(0)
	s_barrier
	s_setprio 1
	v_mfma_f32_16x16x32_bf16 v[124:127], v[144:147], v[184:187], 0
	v_mfma_f32_16x16x32_bf16 v[124:127], v[148:151], v[188:191], v[124:127]
	v_mfma_f32_16x16x32_bf16 v[120:123], v[152:155], v[184:187], 0
	v_mfma_f32_16x16x32_bf16 v[120:123], v[156:159], v[188:191], v[120:123]
	v_mfma_f32_16x16x32_bf16 v[104:107], v[152:155], v[192:195], 0
	v_mfma_f32_16x16x32_bf16 v[104:107], v[156:159], v[196:199], v[104:107]
	v_mfma_f32_16x16x32_bf16 v[108:111], v[144:147], v[192:195], 0
	v_mfma_f32_16x16x32_bf16 v[108:111], v[148:151], v[196:199], v[108:111]
	v_mfma_f32_16x16x32_bf16 v[92:95], v[144:147], v[200:203], 0
	v_mfma_f32_16x16x32_bf16 v[92:95], v[148:151], v[204:207], v[92:95]
	v_mfma_f32_16x16x32_bf16 v[88:91], v[152:155], v[200:203], 0
	v_mfma_f32_16x16x32_bf16 v[88:91], v[156:159], v[204:207], v[88:91]
	v_mfma_f32_16x16x32_bf16 v[72:75], v[152:155], v[208:211], 0
	v_mfma_f32_16x16x32_bf16 v[72:75], v[156:159], v[212:215], v[72:75]
	v_mfma_f32_16x16x32_bf16 v[76:79], v[144:147], v[208:211], 0
	v_mfma_f32_16x16x32_bf16 v[76:79], v[148:151], v[212:215], v[76:79]
	v_mfma_f32_16x16x32_bf16 v[116:119], v[168:171], v[184:187], 0
	v_mfma_f32_16x16x32_bf16 v[116:119], v[172:175], v[188:191], v[116:119]
	v_mfma_f32_16x16x32_bf16 v[112:115], v[176:179], v[184:187], 0
	v_mfma_f32_16x16x32_bf16 v[112:115], v[180:183], v[188:191], v[112:115]
	v_mfma_f32_16x16x32_bf16 v[96:99], v[176:179], v[192:195], 0
	v_mfma_f32_16x16x32_bf16 v[96:99], v[180:183], v[196:199], v[96:99]
	v_mfma_f32_16x16x32_bf16 v[100:103], v[168:171], v[192:195], 0
	v_mfma_f32_16x16x32_bf16 v[100:103], v[172:175], v[196:199], v[100:103]
	v_mfma_f32_16x16x32_bf16 v[84:87], v[168:171], v[200:203], 0
	v_mfma_f32_16x16x32_bf16 v[84:87], v[172:175], v[204:207], v[84:87]
	v_mfma_f32_16x16x32_bf16 v[80:83], v[176:179], v[200:203], 0
	v_mfma_f32_16x16x32_bf16 v[80:83], v[180:183], v[204:207], v[80:83]
	s_setprio 2
	s_barrier
	v_mfma_f32_16x16x32_bf16 v[64:67], v[176:179], v[208:211], 0
	v_mfma_f32_16x16x32_bf16 v[64:67], v[180:183], v[212:215], v[64:67]
	v_mfma_f32_16x16x32_bf16 v[68:71], v[168:171], v[208:211], 0
	v_mfma_f32_16x16x32_bf16 v[68:71], v[172:175], v[212:215], v[68:71]
	s_setprio 2
	s_add_i32 s66, s59, s47
	v_lshl_add_u64 v[160:161], s[38:39], 0, v[132:133]
	s_mov_b32 m0, s66
	ds_read_b128 v[184:187], v165 offset:16384
	ds_read_b128 v[188:191], v165 offset:17408
	ds_read_b128 v[192:195], v165 offset:18432
	ds_read_b128 v[196:199], v165 offset:19456
	ds_read_b128 v[200:203], v165 offset:20480
	ds_read_b128 v[204:207], v165 offset:21504
	ds_read_b128 v[208:211], v165 offset:22528
	ds_read_b128 v[212:215], v165 offset:23552
	global_load_lds_dwordx4 v[160:161], off
	s_add_i32 m0, s66, 0x2000
	s_add_u32 s66, s38, 0x40000
	v_lshl_add_u64 v[216:217], s[38:39], 0, v[128:129]
	s_addc_u32 s67, s39, 0
	s_add_i32 s68, s60, s47
	global_load_lds_dwordx4 v[216:217], off
	v_lshl_add_u64 v[218:219], s[66:67], 0, v[132:133]
	s_mov_b32 m0, s68
	v_lshl_add_u64 v[220:221], s[40:41], 0, v[130:131]
	global_load_lds_dwordx4 v[218:219], off
	s_add_i32 m0, s68, 0x2000
	v_lshl_add_u64 v[218:219], s[66:67], 0, v[128:129]
	global_load_lds_dwordx4 v[218:219], off
	s_mov_b32 m0, s50
	v_lshl_add_u64 v[218:219], s[40:41], 0, v[134:135]
	global_load_lds_dwordx4 v[218:219], off
	s_mov_b32 m0, s51
	s_nop 0
	global_load_lds_dwordx4 v[220:221], off
	s_waitcnt vmcnt(8) lgkmcnt(0)
	s_barrier
	s_setprio 1
	v_mfma_f32_16x16x32_bf16 v[60:63], v[144:147], v[184:187], 0
	v_mfma_f32_16x16x32_bf16 v[60:63], v[148:151], v[188:191], v[60:63]
	v_mfma_f32_16x16x32_bf16 v[56:59], v[152:155], v[184:187], 0
	v_mfma_f32_16x16x32_bf16 v[56:59], v[156:159], v[188:191], v[56:59]
	v_mfma_f32_16x16x32_bf16 v[40:43], v[152:155], v[192:195], 0
	v_mfma_f32_16x16x32_bf16 v[40:43], v[156:159], v[196:199], v[40:43]
	v_mfma_f32_16x16x32_bf16 v[44:47], v[144:147], v[192:195], 0
	v_mfma_f32_16x16x32_bf16 v[44:47], v[148:151], v[196:199], v[44:47]
	v_mfma_f32_16x16x32_bf16 v[28:31], v[144:147], v[200:203], 0
	v_mfma_f32_16x16x32_bf16 v[28:31], v[148:151], v[204:207], v[28:31]
	v_mfma_f32_16x16x32_bf16 v[24:27], v[152:155], v[200:203], 0
	v_mfma_f32_16x16x32_bf16 v[24:27], v[156:159], v[204:207], v[24:27]
	v_mfma_f32_16x16x32_bf16 v[8:11], v[152:155], v[208:211], 0
	v_mfma_f32_16x16x32_bf16 v[8:11], v[156:159], v[212:215], v[8:11]
	v_mfma_f32_16x16x32_bf16 v[12:15], v[144:147], v[208:211], 0
	v_mfma_f32_16x16x32_bf16 v[12:15], v[148:151], v[212:215], v[12:15]
	v_mfma_f32_16x16x32_bf16 v[52:55], v[168:171], v[184:187], 0
	v_mfma_f32_16x16x32_bf16 v[52:55], v[172:175], v[188:191], v[52:55]
	v_mfma_f32_16x16x32_bf16 v[48:51], v[176:179], v[184:187], 0
	v_mfma_f32_16x16x32_bf16 v[48:51], v[180:183], v[188:191], v[48:51]
	v_mfma_f32_16x16x32_bf16 v[32:35], v[176:179], v[192:195], 0
	v_mfma_f32_16x16x32_bf16 v[32:35], v[180:183], v[196:199], v[32:35]
	v_mfma_f32_16x16x32_bf16 v[36:39], v[168:171], v[192:195], 0
	v_mfma_f32_16x16x32_bf16 v[36:39], v[172:175], v[196:199], v[36:39]
	v_mfma_f32_16x16x32_bf16 v[20:23], v[168:171], v[200:203], 0
	v_mfma_f32_16x16x32_bf16 v[20:23], v[172:175], v[204:207], v[20:23]
	v_mfma_f32_16x16x32_bf16 v[16:19], v[176:179], v[200:203], 0
	v_mfma_f32_16x16x32_bf16 v[16:19], v[180:183], v[204:207], v[16:19]
	s_setprio 2
	s_barrier
	v_mfma_f32_16x16x32_bf16 v[0:3], v[176:179], v[208:211], 0
	v_mfma_f32_16x16x32_bf16 v[0:3], v[180:183], v[212:215], v[0:3]
	v_mfma_f32_16x16x32_bf16 v[4:7], v[168:171], v[208:211], 0
	v_mfma_f32_16x16x32_bf16 v[4:7], v[172:175], v[212:215], v[4:7]
	s_setprio 0
	s_add_i32 s66, 0, 0x18000
	s_add_i32 s67, 0, 0x1c000
	v_add_u32_e32 v156, s66, v162
	v_add_u32_e32 v167, s67, v162
	ds_read_b128 v[144:147], v156
	ds_read_b128 v[148:151], v156 offset:1024
	ds_read_b128 v[152:155], v156 offset:2048
	ds_read_b128 v[156:159], v156 offset:3072
	ds_read_b128 v[168:171], v167
	ds_read_b128 v[172:175], v167 offset:1024
	ds_read_b128 v[176:179], v167 offset:2048
	ds_read_b128 v[180:183], v167 offset:3072
	s_add_u32 s40, s40, 0x40000
	s_addc_u32 s41, s41, 0
	s_mov_b32 m0, s54
	v_lshl_add_u64 v[222:223], s[40:41], 0, v[134:135]
	ds_read_b128 v[184:187], v165 offset:32768
	ds_read_b128 v[188:191], v165 offset:33792
	ds_read_b128 v[192:195], v165 offset:34816
	ds_read_b128 v[196:199], v165 offset:35840
	ds_read_b128 v[200:203], v165 offset:36864
	ds_read_b128 v[204:207], v165 offset:37888
	ds_read_b128 v[208:211], v165 offset:38912
	ds_read_b128 v[212:215], v165 offset:39936
	global_load_lds_dwordx4 v[222:223], off
	s_mov_b32 m0, s55
	v_lshl_add_u64 v[222:223], s[40:41], 0, v[130:131]
	global_load_lds_dwordx4 v[222:223], off
	s_waitcnt vmcnt(8) lgkmcnt(0)
	s_barrier
	s_setprio 1
	v_mfma_f32_16x16x32_bf16 v[124:127], v[144:147], v[184:187], v[124:127]
	v_mfma_f32_16x16x32_bf16 v[124:127], v[148:151], v[188:191], v[124:127]
	v_mfma_f32_16x16x32_bf16 v[120:123], v[152:155], v[184:187], v[120:123]
	v_mfma_f32_16x16x32_bf16 v[120:123], v[156:159], v[188:191], v[120:123]
	v_mfma_f32_16x16x32_bf16 v[104:107], v[152:155], v[192:195], v[104:107]
	v_mfma_f32_16x16x32_bf16 v[104:107], v[156:159], v[196:199], v[104:107]
	v_mfma_f32_16x16x32_bf16 v[108:111], v[144:147], v[192:195], v[108:111]
	v_mfma_f32_16x16x32_bf16 v[108:111], v[148:151], v[196:199], v[108:111]
	v_mfma_f32_16x16x32_bf16 v[92:95], v[144:147], v[200:203], v[92:95]
	v_mfma_f32_16x16x32_bf16 v[92:95], v[148:151], v[204:207], v[92:95]
	v_mfma_f32_16x16x32_bf16 v[88:91], v[152:155], v[200:203], v[88:91]
	v_mfma_f32_16x16x32_bf16 v[88:91], v[156:159], v[204:207], v[88:91]
	v_mfma_f32_16x16x32_bf16 v[72:75], v[152:155], v[208:211], v[72:75]
	v_mfma_f32_16x16x32_bf16 v[72:75], v[156:159], v[212:215], v[72:75]
	v_mfma_f32_16x16x32_bf16 v[76:79], v[144:147], v[208:211], v[76:79]
	v_mfma_f32_16x16x32_bf16 v[76:79], v[148:151], v[212:215], v[76:79]
	v_mfma_f32_16x16x32_bf16 v[116:119], v[168:171], v[184:187], v[116:119]
	v_mfma_f32_16x16x32_bf16 v[116:119], v[172:175], v[188:191], v[116:119]
	v_mfma_f32_16x16x32_bf16 v[112:115], v[176:179], v[184:187], v[112:115]
	v_mfma_f32_16x16x32_bf16 v[112:115], v[180:183], v[188:191], v[112:115]
	v_mfma_f32_16x16x32_bf16 v[96:99], v[176:179], v[192:195], v[96:99]
	v_mfma_f32_16x16x32_bf16 v[96:99], v[180:183], v[196:199], v[96:99]
	v_mfma_f32_16x16x32_bf16 v[100:103], v[168:171], v[192:195], v[100:103]
	v_mfma_f32_16x16x32_bf16 v[100:103], v[172:175], v[196:199], v[100:103]
	v_mfma_f32_16x16x32_bf16 v[84:87], v[168:171], v[200:203], v[84:87]
	v_mfma_f32_16x16x32_bf16 v[84:87], v[172:175], v[204:207], v[84:87]
	v_mfma_f32_16x16x32_bf16 v[80:83], v[176:179], v[200:203], v[80:83]
	v_mfma_f32_16x16x32_bf16 v[80:83], v[180:183], v[204:207], v[80:83]
	s_setprio 2
	s_barrier
	v_mfma_f32_16x16x32_bf16 v[64:67], v[176:179], v[208:211], v[64:67]
	v_mfma_f32_16x16x32_bf16 v[64:67], v[180:183], v[212:215], v[64:67]
	v_mfma_f32_16x16x32_bf16 v[68:71], v[168:171], v[208:211], v[68:71]
	v_mfma_f32_16x16x32_bf16 v[68:71], v[172:175], v[212:215], v[68:71]
	s_setprio 2
	s_add_i32 s40, s66, s47
	v_lshl_add_u64 v[160:161], v[160:161], 0, s[16:17]
	s_mov_b32 m0, s40
	ds_read_b128 v[184:187], v165 offset:49152
	ds_read_b128 v[188:191], v165 offset:50176
	ds_read_b128 v[192:195], v165 offset:51200
	ds_read_b128 v[196:199], v165 offset:52224
	ds_read_b128 v[200:203], v165 offset:53248
	ds_read_b128 v[204:207], v165 offset:54272
	ds_read_b128 v[208:211], v165 offset:55296
	ds_read_b128 v[212:215], v165 offset:56320
	global_load_lds_dwordx4 v[160:161], off
	s_add_i32 m0, s40, 0x2000
	s_add_u32 s38, s38, 0x40080
	v_lshl_add_u64 v[160:161], v[216:217], 0, s[16:17]
	s_addc_u32 s39, s39, 0
	s_add_i32 s40, s67, s47
	global_load_lds_dwordx4 v[160:161], off
	s_mov_b32 m0, s40
	v_lshl_add_u64 v[160:161], s[38:39], 0, v[132:133]
	global_load_lds_dwordx4 v[160:161], off
	s_add_i32 m0, s40, 0x2000
	v_lshl_add_u64 v[160:161], s[38:39], 0, v[128:129]
	global_load_lds_dwordx4 v[160:161], off
	s_mov_b32 m0, s57
	v_lshl_add_u64 v[160:161], v[218:219], 0, s[16:17]
	global_load_lds_dwordx4 v[160:161], off
	s_mov_b32 m0, s58
	v_lshl_add_u64 v[160:161], v[220:221], 0, s[16:17]
	global_load_lds_dwordx4 v[160:161], off
	s_waitcnt vmcnt(8) lgkmcnt(0)
	s_barrier
	s_setprio 1
	v_mfma_f32_16x16x32_bf16 v[60:63], v[144:147], v[184:187], v[60:63]
	v_mfma_f32_16x16x32_bf16 v[60:63], v[148:151], v[188:191], v[60:63]
	v_mfma_f32_16x16x32_bf16 v[56:59], v[152:155], v[184:187], v[56:59]
	v_mfma_f32_16x16x32_bf16 v[56:59], v[156:159], v[188:191], v[56:59]
	v_mfma_f32_16x16x32_bf16 v[40:43], v[152:155], v[192:195], v[40:43]
	v_mfma_f32_16x16x32_bf16 v[40:43], v[156:159], v[196:199], v[40:43]
	v_mfma_f32_16x16x32_bf16 v[44:47], v[144:147], v[192:195], v[44:47]
	v_mfma_f32_16x16x32_bf16 v[44:47], v[148:151], v[196:199], v[44:47]
	v_mfma_f32_16x16x32_bf16 v[28:31], v[144:147], v[200:203], v[28:31]
	v_mfma_f32_16x16x32_bf16 v[28:31], v[148:151], v[204:207], v[28:31]
	v_mfma_f32_16x16x32_bf16 v[24:27], v[152:155], v[200:203], v[24:27]
	v_mfma_f32_16x16x32_bf16 v[24:27], v[156:159], v[204:207], v[24:27]
	v_mfma_f32_16x16x32_bf16 v[8:11], v[152:155], v[208:211], v[8:11]
	v_mfma_f32_16x16x32_bf16 v[8:11], v[156:159], v[212:215], v[8:11]
	v_mfma_f32_16x16x32_bf16 v[12:15], v[144:147], v[208:211], v[12:15]
	v_mfma_f32_16x16x32_bf16 v[12:15], v[148:151], v[212:215], v[12:15]
	v_mfma_f32_16x16x32_bf16 v[52:55], v[168:171], v[184:187], v[52:55]
	v_mfma_f32_16x16x32_bf16 v[52:55], v[172:175], v[188:191], v[52:55]
	v_mfma_f32_16x16x32_bf16 v[48:51], v[176:179], v[184:187], v[48:51]
	v_mfma_f32_16x16x32_bf16 v[48:51], v[180:183], v[188:191], v[48:51]
	v_mfma_f32_16x16x32_bf16 v[32:35], v[176:179], v[192:195], v[32:35]
	v_mfma_f32_16x16x32_bf16 v[32:35], v[180:183], v[196:199], v[32:35]
	v_mfma_f32_16x16x32_bf16 v[36:39], v[168:171], v[192:195], v[36:39]
	v_mfma_f32_16x16x32_bf16 v[36:39], v[172:175], v[196:199], v[36:39]
	v_mfma_f32_16x16x32_bf16 v[20:23], v[168:171], v[200:203], v[20:23]
	v_mfma_f32_16x16x32_bf16 v[20:23], v[172:175], v[204:207], v[20:23]
	v_mfma_f32_16x16x32_bf16 v[16:19], v[176:179], v[200:203], v[16:19]
	v_mfma_f32_16x16x32_bf16 v[16:19], v[180:183], v[204:207], v[16:19]
	s_setprio 2
	s_barrier
	v_mfma_f32_16x16x32_bf16 v[0:3], v[176:179], v[208:211], v[0:3]
	v_mfma_f32_16x16x32_bf16 v[0:3], v[180:183], v[212:215], v[0:3]
	v_mfma_f32_16x16x32_bf16 v[4:7], v[168:171], v[208:211], v[4:7]
	v_mfma_f32_16x16x32_bf16 v[4:7], v[172:175], v[212:215], v[4:7]
	s_setprio 0
	s_add_i32 s65, s65, 2
	s_add_u32 s36, s36, 0x100
	s_addc_u32 s37, s37, 0
	s_add_u32 s63, s63, 0x100
	s_addc_u32 s64, s64, 0
	s_cmp_gt_u32 s65, 13
.LBB0_784:
	ds_read_b128 v[144:147], v163
	ds_read_b128 v[148:151], v163 offset:1024
	ds_read_b128 v[152:155], v163 offset:2048
	ds_read_b128 v[156:159], v163 offset:3072
	ds_read_b128 v[168:171], v164
	ds_read_b128 v[172:175], v164 offset:1024
	ds_read_b128 v[176:179], v164 offset:2048
	ds_read_b128 v[180:183], v164 offset:3072
	s_add_u32 s38, s36, 0xfffc0080
	s_addc_u32 s39, s37, -1
	s_cmp_eq_u32 s65, 12
	s_cselect_b32 s41, s23, s39
	s_cselect_b32 s40, s31, s38
	s_cselect_b32 s39, s25, s64
	s_cselect_b32 s38, s62, s63
	v_lshl_add_u64 v[160:161], s[36:37], 0, v[136:137]
	s_add_i32 m0, s50, 0xc000
	ds_read_b128 v[184:187], v165
	ds_read_b128 v[188:191], v165 offset:1024
	ds_read_b128 v[192:195], v165 offset:2048
	ds_read_b128 v[196:199], v165 offset:3072
	ds_read_b128 v[200:203], v165 offset:4096
	ds_read_b128 v[204:207], v165 offset:5120
	ds_read_b128 v[208:211], v165 offset:6144
	ds_read_b128 v[212:215], v165 offset:7168
	global_load_lds_dwordx4 v[160:161], off
	s_add_i32 m0, s50, 0xe000
	v_lshl_add_u64 v[160:161], s[36:37], 0, v[138:139]
	global_load_lds_dwordx4 v[160:161], off
	s_waitcnt vmcnt(8) lgkmcnt(0)
	s_barrier
	s_setprio 1
	v_mfma_f32_16x16x32_bf16 v[124:127], v[144:147], v[184:187], v[124:127]
	v_mfma_f32_16x16x32_bf16 v[124:127], v[148:151], v[188:191], v[124:127]
	v_mfma_f32_16x16x32_bf16 v[120:123], v[152:155], v[184:187], v[120:123]
	v_mfma_f32_16x16x32_bf16 v[120:123], v[156:159], v[188:191], v[120:123]
	v_mfma_f32_16x16x32_bf16 v[104:107], v[152:155], v[192:195], v[104:107]
	v_mfma_f32_16x16x32_bf16 v[104:107], v[156:159], v[196:199], v[104:107]
	v_mfma_f32_16x16x32_bf16 v[108:111], v[144:147], v[192:195], v[108:111]
	v_mfma_f32_16x16x32_bf16 v[108:111], v[148:151], v[196:199], v[108:111]
	v_mfma_f32_16x16x32_bf16 v[92:95], v[144:147], v[200:203], v[92:95]
	v_mfma_f32_16x16x32_bf16 v[92:95], v[148:151], v[204:207], v[92:95]
	v_mfma_f32_16x16x32_bf16 v[88:91], v[152:155], v[200:203], v[88:91]
	v_mfma_f32_16x16x32_bf16 v[88:91], v[156:159], v[204:207], v[88:91]
	v_mfma_f32_16x16x32_bf16 v[72:75], v[152:155], v[208:211], v[72:75]
	v_mfma_f32_16x16x32_bf16 v[72:75], v[156:159], v[212:215], v[72:75]
	v_mfma_f32_16x16x32_bf16 v[76:79], v[144:147], v[208:211], v[76:79]
	v_mfma_f32_16x16x32_bf16 v[76:79], v[148:151], v[212:215], v[76:79]
	v_mfma_f32_16x16x32_bf16 v[116:119], v[168:171], v[184:187], v[116:119]
	v_mfma_f32_16x16x32_bf16 v[116:119], v[172:175], v[188:191], v[116:119]
	v_mfma_f32_16x16x32_bf16 v[112:115], v[176:179], v[184:187], v[112:115]
	v_mfma_f32_16x16x32_bf16 v[112:115], v[180:183], v[188:191], v[112:115]
	v_mfma_f32_16x16x32_bf16 v[96:99], v[176:179], v[192:195], v[96:99]
	v_mfma_f32_16x16x32_bf16 v[96:99], v[180:183], v[196:199], v[96:99]
	v_mfma_f32_16x16x32_bf16 v[100:103], v[168:171], v[192:195], v[100:103]
	v_mfma_f32_16x16x32_bf16 v[100:103], v[172:175], v[196:199], v[100:103]
	v_mfma_f32_16x16x32_bf16 v[84:87], v[168:171], v[200:203], v[84:87]
	v_mfma_f32_16x16x32_bf16 v[84:87], v[172:175], v[204:207], v[84:87]
	v_mfma_f32_16x16x32_bf16 v[80:83], v[176:179], v[200:203], v[80:83]
	v_mfma_f32_16x16x32_bf16 v[80:83], v[180:183], v[204:207], v[80:83]
	s_setprio 2
	s_barrier
	v_mfma_f32_16x16x32_bf16 v[64:67], v[176:179], v[208:211], v[64:67]
	v_mfma_f32_16x16x32_bf16 v[64:67], v[180:183], v[212:215], v[64:67]
	v_mfma_f32_16x16x32_bf16 v[68:71], v[168:171], v[208:211], v[68:71]
	v_mfma_f32_16x16x32_bf16 v[68:71], v[172:175], v[212:215], v[68:71]
	s_setprio 2
	s_add_i32 s66, s59, s47
	v_lshl_add_u64 v[160:161], s[38:39], 0, v[132:133]
	s_mov_b32 m0, s66
	ds_read_b128 v[184:187], v165 offset:16384
	ds_read_b128 v[188:191], v165 offset:17408
	ds_read_b128 v[192:195], v165 offset:18432
	ds_read_b128 v[196:199], v165 offset:19456
	ds_read_b128 v[200:203], v165 offset:20480
	ds_read_b128 v[204:207], v165 offset:21504
	ds_read_b128 v[208:211], v165 offset:22528
	ds_read_b128 v[212:215], v165 offset:23552
	global_load_lds_dwordx4 v[160:161], off
	s_add_i32 m0, s66, 0x2000
	s_add_u32 s66, s38, 0x40000
	v_lshl_add_u64 v[216:217], s[38:39], 0, v[128:129]
	s_addc_u32 s67, s39, 0
	s_add_i32 s68, s60, s47
	global_load_lds_dwordx4 v[216:217], off
	v_lshl_add_u64 v[218:219], s[66:67], 0, v[132:133]
	s_mov_b32 m0, s68
	v_lshl_add_u64 v[220:221], s[40:41], 0, v[130:131]
	global_load_lds_dwordx4 v[218:219], off
	s_add_i32 m0, s68, 0x2000
	v_lshl_add_u64 v[218:219], s[66:67], 0, v[128:129]
	global_load_lds_dwordx4 v[218:219], off
	s_mov_b32 m0, s50
	v_lshl_add_u64 v[218:219], s[40:41], 0, v[134:135]
	global_load_lds_dwordx4 v[218:219], off
	s_mov_b32 m0, s51
	s_nop 0
	global_load_lds_dwordx4 v[220:221], off
	s_waitcnt vmcnt(8) lgkmcnt(0)
	s_barrier
	s_setprio 1
	v_mfma_f32_16x16x32_bf16 v[60:63], v[144:147], v[184:187], v[60:63]
	v_mfma_f32_16x16x32_bf16 v[60:63], v[148:151], v[188:191], v[60:63]
	v_mfma_f32_16x16x32_bf16 v[56:59], v[152:155], v[184:187], v[56:59]
	v_mfma_f32_16x16x32_bf16 v[56:59], v[156:159], v[188:191], v[56:59]
	v_mfma_f32_16x16x32_bf16 v[40:43], v[152:155], v[192:195], v[40:43]
	v_mfma_f32_16x16x32_bf16 v[40:43], v[156:159], v[196:199], v[40:43]
	v_mfma_f32_16x16x32_bf16 v[44:47], v[144:147], v[192:195], v[44:47]
	v_mfma_f32_16x16x32_bf16 v[44:47], v[148:151], v[196:199], v[44:47]
	v_mfma_f32_16x16x32_bf16 v[28:31], v[144:147], v[200:203], v[28:31]
	v_mfma_f32_16x16x32_bf16 v[28:31], v[148:151], v[204:207], v[28:31]
	v_mfma_f32_16x16x32_bf16 v[24:27], v[152:155], v[200:203], v[24:27]
	v_mfma_f32_16x16x32_bf16 v[24:27], v[156:159], v[204:207], v[24:27]
	v_mfma_f32_16x16x32_bf16 v[8:11], v[152:155], v[208:211], v[8:11]
	v_mfma_f32_16x16x32_bf16 v[8:11], v[156:159], v[212:215], v[8:11]
	v_mfma_f32_16x16x32_bf16 v[12:15], v[144:147], v[208:211], v[12:15]
	v_mfma_f32_16x16x32_bf16 v[12:15], v[148:151], v[212:215], v[12:15]
	v_mfma_f32_16x16x32_bf16 v[52:55], v[168:171], v[184:187], v[52:55]
	v_mfma_f32_16x16x32_bf16 v[52:55], v[172:175], v[188:191], v[52:55]
	v_mfma_f32_16x16x32_bf16 v[48:51], v[176:179], v[184:187], v[48:51]
	v_mfma_f32_16x16x32_bf16 v[48:51], v[180:183], v[188:191], v[48:51]
	v_mfma_f32_16x16x32_bf16 v[32:35], v[176:179], v[192:195], v[32:35]
	v_mfma_f32_16x16x32_bf16 v[32:35], v[180:183], v[196:199], v[32:35]
	v_mfma_f32_16x16x32_bf16 v[36:39], v[168:171], v[192:195], v[36:39]
	v_mfma_f32_16x16x32_bf16 v[36:39], v[172:175], v[196:199], v[36:39]
	v_mfma_f32_16x16x32_bf16 v[20:23], v[168:171], v[200:203], v[20:23]
	v_mfma_f32_16x16x32_bf16 v[20:23], v[172:175], v[204:207], v[20:23]
	v_mfma_f32_16x16x32_bf16 v[16:19], v[176:179], v[200:203], v[16:19]
	v_mfma_f32_16x16x32_bf16 v[16:19], v[180:183], v[204:207], v[16:19]
	s_setprio 2
	s_barrier
	v_mfma_f32_16x16x32_bf16 v[0:3], v[176:179], v[208:211], v[0:3]
	v_mfma_f32_16x16x32_bf16 v[0:3], v[180:183], v[212:215], v[0:3]
	v_mfma_f32_16x16x32_bf16 v[4:7], v[168:171], v[208:211], v[4:7]
	v_mfma_f32_16x16x32_bf16 v[4:7], v[172:175], v[212:215], v[4:7]
	s_setprio 0
	s_add_i32 s66, 0, 0x18000
	s_add_i32 s67, 0, 0x1c000
	v_add_u32_e32 v156, s66, v162
	v_add_u32_e32 v167, s67, v162
	ds_read_b128 v[144:147], v156
	ds_read_b128 v[148:151], v156 offset:1024
	ds_read_b128 v[152:155], v156 offset:2048
	ds_read_b128 v[156:159], v156 offset:3072
	ds_read_b128 v[168:171], v167
	ds_read_b128 v[172:175], v167 offset:1024
	ds_read_b128 v[176:179], v167 offset:2048
	ds_read_b128 v[180:183], v167 offset:3072
	s_add_u32 s40, s40, 0x40000
	s_addc_u32 s41, s41, 0
	s_mov_b32 m0, s54
	v_lshl_add_u64 v[222:223], s[40:41], 0, v[134:135]
	ds_read_b128 v[184:187], v165 offset:32768
	ds_read_b128 v[188:191], v165 offset:33792
	ds_read_b128 v[192:195], v165 offset:34816
	ds_read_b128 v[196:199], v165 offset:35840
	ds_read_b128 v[200:203], v165 offset:36864
	ds_read_b128 v[204:207], v165 offset:37888
	ds_read_b128 v[208:211], v165 offset:38912
	ds_read_b128 v[212:215], v165 offset:39936
	global_load_lds_dwordx4 v[222:223], off
	s_mov_b32 m0, s55
	v_lshl_add_u64 v[222:223], s[40:41], 0, v[130:131]
	global_load_lds_dwordx4 v[222:223], off
	s_waitcnt vmcnt(8) lgkmcnt(0)
	s_barrier
	s_setprio 1
	v_mfma_f32_16x16x32_bf16 v[124:127], v[144:147], v[184:187], v[124:127]
	v_mfma_f32_16x16x32_bf16 v[124:127], v[148:151], v[188:191], v[124:127]
	v_mfma_f32_16x16x32_bf16 v[120:123], v[152:155], v[184:187], v[120:123]
	v_mfma_f32_16x16x32_bf16 v[120:123], v[156:159], v[188:191], v[120:123]
	v_mfma_f32_16x16x32_bf16 v[104:107], v[152:155], v[192:195], v[104:107]
	v_mfma_f32_16x16x32_bf16 v[104:107], v[156:159], v[196:199], v[104:107]
	v_mfma_f32_16x16x32_bf16 v[108:111], v[144:147], v[192:195], v[108:111]
	v_mfma_f32_16x16x32_bf16 v[108:111], v[148:151], v[196:199], v[108:111]
	v_mfma_f32_16x16x32_bf16 v[92:95], v[144:147], v[200:203], v[92:95]
	v_mfma_f32_16x16x32_bf16 v[92:95], v[148:151], v[204:207], v[92:95]
	v_mfma_f32_16x16x32_bf16 v[88:91], v[152:155], v[200:203], v[88:91]
	v_mfma_f32_16x16x32_bf16 v[88:91], v[156:159], v[204:207], v[88:91]
	v_mfma_f32_16x16x32_bf16 v[72:75], v[152:155], v[208:211], v[72:75]
	v_mfma_f32_16x16x32_bf16 v[72:75], v[156:159], v[212:215], v[72:75]
	v_mfma_f32_16x16x32_bf16 v[76:79], v[144:147], v[208:211], v[76:79]
	v_mfma_f32_16x16x32_bf16 v[76:79], v[148:151], v[212:215], v[76:79]
	v_mfma_f32_16x16x32_bf16 v[116:119], v[168:171], v[184:187], v[116:119]
	v_mfma_f32_16x16x32_bf16 v[116:119], v[172:175], v[188:191], v[116:119]
	v_mfma_f32_16x16x32_bf16 v[112:115], v[176:179], v[184:187], v[112:115]
	v_mfma_f32_16x16x32_bf16 v[112:115], v[180:183], v[188:191], v[112:115]
	v_mfma_f32_16x16x32_bf16 v[96:99], v[176:179], v[192:195], v[96:99]
	v_mfma_f32_16x16x32_bf16 v[96:99], v[180:183], v[196:199], v[96:99]
	v_mfma_f32_16x16x32_bf16 v[100:103], v[168:171], v[192:195], v[100:103]
	v_mfma_f32_16x16x32_bf16 v[100:103], v[172:175], v[196:199], v[100:103]
	v_mfma_f32_16x16x32_bf16 v[84:87], v[168:171], v[200:203], v[84:87]
	v_mfma_f32_16x16x32_bf16 v[84:87], v[172:175], v[204:207], v[84:87]
	v_mfma_f32_16x16x32_bf16 v[80:83], v[176:179], v[200:203], v[80:83]
	v_mfma_f32_16x16x32_bf16 v[80:83], v[180:183], v[204:207], v[80:83]
	s_setprio 2
	s_barrier
	v_mfma_f32_16x16x32_bf16 v[64:67], v[176:179], v[208:211], v[64:67]
	v_mfma_f32_16x16x32_bf16 v[64:67], v[180:183], v[212:215], v[64:67]
	v_mfma_f32_16x16x32_bf16 v[68:71], v[168:171], v[208:211], v[68:71]
	v_mfma_f32_16x16x32_bf16 v[68:71], v[172:175], v[212:215], v[68:71]
	s_setprio 2
	s_add_i32 s40, s66, s47
	v_lshl_add_u64 v[160:161], v[160:161], 0, s[16:17]
	s_mov_b32 m0, s40
	ds_read_b128 v[184:187], v165 offset:49152
	ds_read_b128 v[188:191], v165 offset:50176
	ds_read_b128 v[192:195], v165 offset:51200
	ds_read_b128 v[196:199], v165 offset:52224
	ds_read_b128 v[200:203], v165 offset:53248
	ds_read_b128 v[204:207], v165 offset:54272
	ds_read_b128 v[208:211], v165 offset:55296
	ds_read_b128 v[212:215], v165 offset:56320
	global_load_lds_dwordx4 v[160:161], off
	s_add_i32 m0, s40, 0x2000
	s_add_u32 s38, s38, 0x40080
	v_lshl_add_u64 v[160:161], v[216:217], 0, s[16:17]
	s_addc_u32 s39, s39, 0
	s_add_i32 s40, s67, s47
	global_load_lds_dwordx4 v[160:161], off
	s_mov_b32 m0, s40
	v_lshl_add_u64 v[160:161], s[38:39], 0, v[132:133]
	global_load_lds_dwordx4 v[160:161], off
	s_add_i32 m0, s40, 0x2000
	v_lshl_add_u64 v[160:161], s[38:39], 0, v[128:129]
	global_load_lds_dwordx4 v[160:161], off
	s_mov_b32 m0, s57
	v_lshl_add_u64 v[160:161], v[218:219], 0, s[16:17]
	global_load_lds_dwordx4 v[160:161], off
	s_mov_b32 m0, s58
	v_lshl_add_u64 v[160:161], v[220:221], 0, s[16:17]
	global_load_lds_dwordx4 v[160:161], off
	s_waitcnt vmcnt(8) lgkmcnt(0)
	s_barrier
	s_setprio 1
	v_mfma_f32_16x16x32_bf16 v[60:63], v[144:147], v[184:187], v[60:63]
	v_mfma_f32_16x16x32_bf16 v[60:63], v[148:151], v[188:191], v[60:63]
	v_mfma_f32_16x16x32_bf16 v[56:59], v[152:155], v[184:187], v[56:59]
	v_mfma_f32_16x16x32_bf16 v[56:59], v[156:159], v[188:191], v[56:59]
	v_mfma_f32_16x16x32_bf16 v[40:43], v[152:155], v[192:195], v[40:43]
	v_mfma_f32_16x16x32_bf16 v[40:43], v[156:159], v[196:199], v[40:43]
	v_mfma_f32_16x16x32_bf16 v[44:47], v[144:147], v[192:195], v[44:47]
	v_mfma_f32_16x16x32_bf16 v[44:47], v[148:151], v[196:199], v[44:47]
	v_mfma_f32_16x16x32_bf16 v[28:31], v[144:147], v[200:203], v[28:31]
	v_mfma_f32_16x16x32_bf16 v[28:31], v[148:151], v[204:207], v[28:31]
	v_mfma_f32_16x16x32_bf16 v[24:27], v[152:155], v[200:203], v[24:27]
	v_mfma_f32_16x16x32_bf16 v[24:27], v[156:159], v[204:207], v[24:27]
	v_mfma_f32_16x16x32_bf16 v[8:11], v[152:155], v[208:211], v[8:11]
	v_mfma_f32_16x16x32_bf16 v[8:11], v[156:159], v[212:215], v[8:11]
	v_mfma_f32_16x16x32_bf16 v[12:15], v[144:147], v[208:211], v[12:15]
	v_mfma_f32_16x16x32_bf16 v[12:15], v[148:151], v[212:215], v[12:15]
	v_mfma_f32_16x16x32_bf16 v[52:55], v[168:171], v[184:187], v[52:55]
	v_mfma_f32_16x16x32_bf16 v[52:55], v[172:175], v[188:191], v[52:55]
	v_mfma_f32_16x16x32_bf16 v[48:51], v[176:179], v[184:187], v[48:51]
	v_mfma_f32_16x16x32_bf16 v[48:51], v[180:183], v[188:191], v[48:51]
	v_mfma_f32_16x16x32_bf16 v[32:35], v[176:179], v[192:195], v[32:35]
	v_mfma_f32_16x16x32_bf16 v[32:35], v[180:183], v[196:199], v[32:35]
	v_mfma_f32_16x16x32_bf16 v[36:39], v[168:171], v[192:195], v[36:39]
	v_mfma_f32_16x16x32_bf16 v[36:39], v[172:175], v[196:199], v[36:39]
	v_mfma_f32_16x16x32_bf16 v[20:23], v[168:171], v[200:203], v[20:23]
	v_mfma_f32_16x16x32_bf16 v[20:23], v[172:175], v[204:207], v[20:23]
	v_mfma_f32_16x16x32_bf16 v[16:19], v[176:179], v[200:203], v[16:19]
	v_mfma_f32_16x16x32_bf16 v[16:19], v[180:183], v[204:207], v[16:19]
	s_setprio 2
	s_barrier
	v_mfma_f32_16x16x32_bf16 v[0:3], v[176:179], v[208:211], v[0:3]
	v_mfma_f32_16x16x32_bf16 v[0:3], v[180:183], v[212:215], v[0:3]
	v_mfma_f32_16x16x32_bf16 v[4:7], v[168:171], v[208:211], v[4:7]
	v_mfma_f32_16x16x32_bf16 v[4:7], v[172:175], v[212:215], v[4:7]
	s_setprio 0
	s_add_i32 s65, s65, 2
	s_add_u32 s36, s36, 0x100
	s_addc_u32 s37, s37, 0
	s_add_u32 s63, s63, 0x100
	s_addc_u32 s64, s64, 0
	s_cmp_gt_u32 s65, 13
	s_cbranch_scc0 .LBB0_784

.LBB0_865:
	s_add_u32 s62, s28, 0x100
	s_addc_u32 s63, s29, 0
	s_mov_b32 s64, -2
	ds_read_b128 v[120:123], v233
	ds_read_b128 v[124:127], v233 offset:1024
	ds_read_b128 v[136:139], v233 offset:2048
	ds_read_b128 v[140:143], v233 offset:3072
	ds_read_b128 v[144:147], v234
	ds_read_b128 v[148:151], v234 offset:1024
	ds_read_b128 v[152:155], v234 offset:2048
	ds_read_b128 v[156:159], v234 offset:3072
	s_add_u32 s28, s26, 0x100
	s_addc_u32 s29, s27, 0
	s_cmp_eq_u32 s64, 40
	s_cselect_b32 s37, s7, s29
	s_cselect_b32 s36, s6, s28
	s_cselect_b32 s31, s25, s63
	s_cselect_b32 s30, s24, s62
	v_lshl_add_u64 v[208:209], s[26:27], 0, v[192:193]
	s_add_i32 m0, s44, 0xc000
	ds_read_b128 v[160:163], v235
	ds_read_b128 v[164:167], v235 offset:1024
	ds_read_b128 v[168:171], v235 offset:2048
	ds_read_b128 v[172:175], v235 offset:3072
	ds_read_b128 v[176:179], v235 offset:4096
	ds_read_b128 v[180:183], v235 offset:5120
	ds_read_b128 v[200:203], v235 offset:6144
	ds_read_b128 v[204:207], v235 offset:7168
	global_load_lds_dwordx4 v[208:209], off
	s_add_i32 m0, s44, 0xe000
	v_lshl_add_u64 v[208:209], s[26:27], 0, v[194:195]
	global_load_lds_dwordx4 v[208:209], off
	s_waitcnt vmcnt(8) lgkmcnt(0)
	s_barrier
	s_setprio 1
	v_mfma_f32_16x16x32_bf16 v[132:135], v[120:123], v[160:163], 0
	v_mfma_f32_16x16x32_bf16 v[132:135], v[124:127], v[164:167], v[132:135]
	v_mfma_f32_16x16x32_bf16 v[128:131], v[136:139], v[160:163], 0
	v_mfma_f32_16x16x32_bf16 v[128:131], v[140:143], v[164:167], v[128:131]
	v_mfma_f32_16x16x32_bf16 v[104:107], v[136:139], v[168:171], 0
	v_mfma_f32_16x16x32_bf16 v[104:107], v[140:143], v[172:175], v[104:107]
	v_mfma_f32_16x16x32_bf16 v[108:111], v[120:123], v[168:171], 0
	v_mfma_f32_16x16x32_bf16 v[108:111], v[124:127], v[172:175], v[108:111]
	v_mfma_f32_16x16x32_bf16 v[92:95], v[120:123], v[176:179], 0
	v_mfma_f32_16x16x32_bf16 v[92:95], v[124:127], v[180:183], v[92:95]
	v_mfma_f32_16x16x32_bf16 v[88:91], v[136:139], v[176:179], 0
	v_mfma_f32_16x16x32_bf16 v[88:91], v[140:143], v[180:183], v[88:91]
	v_mfma_f32_16x16x32_bf16 v[72:75], v[136:139], v[200:203], 0
	v_mfma_f32_16x16x32_bf16 v[72:75], v[140:143], v[204:207], v[72:75]
	v_mfma_f32_16x16x32_bf16 v[76:79], v[120:123], v[200:203], 0
	v_mfma_f32_16x16x32_bf16 v[76:79], v[124:127], v[204:207], v[76:79]
	v_mfma_f32_16x16x32_bf16 v[116:119], v[144:147], v[160:163], 0
	v_mfma_f32_16x16x32_bf16 v[116:119], v[148:151], v[164:167], v[116:119]
	v_mfma_f32_16x16x32_bf16 v[112:115], v[152:155], v[160:163], 0
	v_mfma_f32_16x16x32_bf16 v[112:115], v[156:159], v[164:167], v[112:115]
	v_mfma_f32_16x16x32_bf16 v[96:99], v[152:155], v[168:171], 0
	v_mfma_f32_16x16x32_bf16 v[96:99], v[156:159], v[172:175], v[96:99]
	v_mfma_f32_16x16x32_bf16 v[100:103], v[144:147], v[168:171], 0
	v_mfma_f32_16x16x32_bf16 v[100:103], v[148:151], v[172:175], v[100:103]
	v_mfma_f32_16x16x32_bf16 v[84:87], v[144:147], v[176:179], 0
	v_mfma_f32_16x16x32_bf16 v[84:87], v[148:151], v[180:183], v[84:87]
	v_mfma_f32_16x16x32_bf16 v[80:83], v[152:155], v[176:179], 0
	v_mfma_f32_16x16x32_bf16 v[80:83], v[156:159], v[180:183], v[80:83]
	s_setprio 2
	s_barrier
	v_mfma_f32_16x16x32_bf16 v[64:67], v[152:155], v[200:203], 0
	v_mfma_f32_16x16x32_bf16 v[64:67], v[156:159], v[204:207], v[64:67]
	v_mfma_f32_16x16x32_bf16 v[68:71], v[144:147], v[200:203], 0
	v_mfma_f32_16x16x32_bf16 v[68:71], v[148:151], v[204:207], v[68:71]
	s_setprio 2
	s_add_i32 s26, s56, s43
	v_lshl_add_u64 v[208:209], s[30:31], 0, v[186:187]
	s_mov_b32 m0, s26
	ds_read_b128 v[160:163], v235 offset:16384
	ds_read_b128 v[164:167], v235 offset:17408
	ds_read_b128 v[168:171], v235 offset:18432
	ds_read_b128 v[172:175], v235 offset:19456
	ds_read_b128 v[176:179], v235 offset:20480
	ds_read_b128 v[180:183], v235 offset:21504
	ds_read_b128 v[200:203], v235 offset:22528
	ds_read_b128 v[204:207], v235 offset:23552
	global_load_lds_dwordx4 v[208:209], off
	s_add_i32 m0, s26, 0x2000
	s_add_u32 s26, s30, 0xb0000
	v_lshl_add_u64 v[210:211], s[30:31], 0, v[190:191]
	s_addc_u32 s27, s31, 0
	s_add_i32 s65, s57, s43
	global_load_lds_dwordx4 v[210:211], off
	v_lshl_add_u64 v[212:213], s[26:27], 0, v[186:187]
	s_mov_b32 m0, s65
	v_lshl_add_u64 v[214:215], s[36:37], 0, v[188:189]
	global_load_lds_dwordx4 v[212:213], off
	s_add_i32 m0, s65, 0x2000
	v_lshl_add_u64 v[212:213], s[26:27], 0, v[190:191]
	global_load_lds_dwordx4 v[212:213], off
	s_mov_b32 m0, s44
	v_lshl_add_u64 v[212:213], s[36:37], 0, v[184:185]
	global_load_lds_dwordx4 v[212:213], off
	s_mov_b32 m0, s45
	s_nop 0
	global_load_lds_dwordx4 v[214:215], off
	s_waitcnt vmcnt(8) lgkmcnt(0)
	s_barrier
	s_setprio 1
	v_mfma_f32_16x16x32_bf16 v[60:63], v[120:123], v[160:163], 0
	v_mfma_f32_16x16x32_bf16 v[60:63], v[124:127], v[164:167], v[60:63]
	v_mfma_f32_16x16x32_bf16 v[56:59], v[136:139], v[160:163], 0
	v_mfma_f32_16x16x32_bf16 v[56:59], v[140:143], v[164:167], v[56:59]
	v_mfma_f32_16x16x32_bf16 v[40:43], v[136:139], v[168:171], 0
	v_mfma_f32_16x16x32_bf16 v[40:43], v[140:143], v[172:175], v[40:43]
	v_mfma_f32_16x16x32_bf16 v[44:47], v[120:123], v[168:171], 0
	v_mfma_f32_16x16x32_bf16 v[44:47], v[124:127], v[172:175], v[44:47]
	v_mfma_f32_16x16x32_bf16 v[28:31], v[120:123], v[176:179], 0
	v_mfma_f32_16x16x32_bf16 v[28:31], v[124:127], v[180:183], v[28:31]
	v_mfma_f32_16x16x32_bf16 v[24:27], v[136:139], v[176:179], 0
	v_mfma_f32_16x16x32_bf16 v[24:27], v[140:143], v[180:183], v[24:27]
	v_mfma_f32_16x16x32_bf16 v[8:11], v[136:139], v[200:203], 0
	v_mfma_f32_16x16x32_bf16 v[8:11], v[140:143], v[204:207], v[8:11]
	v_mfma_f32_16x16x32_bf16 v[12:15], v[120:123], v[200:203], 0
	v_mfma_f32_16x16x32_bf16 v[12:15], v[124:127], v[204:207], v[12:15]
	v_mfma_f32_16x16x32_bf16 v[52:55], v[144:147], v[160:163], 0
	v_mfma_f32_16x16x32_bf16 v[52:55], v[148:151], v[164:167], v[52:55]
	v_mfma_f32_16x16x32_bf16 v[48:51], v[152:155], v[160:163], 0
	v_mfma_f32_16x16x32_bf16 v[48:51], v[156:159], v[164:167], v[48:51]
	v_mfma_f32_16x16x32_bf16 v[32:35], v[152:155], v[168:171], 0
	v_mfma_f32_16x16x32_bf16 v[32:35], v[156:159], v[172:175], v[32:35]
	v_mfma_f32_16x16x32_bf16 v[36:39], v[144:147], v[168:171], 0
	v_mfma_f32_16x16x32_bf16 v[36:39], v[148:151], v[172:175], v[36:39]
	v_mfma_f32_16x16x32_bf16 v[20:23], v[144:147], v[176:179], 0
	v_mfma_f32_16x16x32_bf16 v[20:23], v[148:151], v[180:183], v[20:23]
	v_mfma_f32_16x16x32_bf16 v[16:19], v[152:155], v[176:179], 0
	v_mfma_f32_16x16x32_bf16 v[16:19], v[156:159], v[180:183], v[16:19]
	s_setprio 2
	s_barrier
	v_mfma_f32_16x16x32_bf16 v[0:3], v[152:155], v[200:203], 0
	v_mfma_f32_16x16x32_bf16 v[0:3], v[156:159], v[204:207], v[0:3]
	v_mfma_f32_16x16x32_bf16 v[4:7], v[144:147], v[200:203], 0
	v_mfma_f32_16x16x32_bf16 v[4:7], v[148:151], v[204:207], v[4:7]
	s_setprio 0
	s_add_i32 s65, 0, 0x18000
	s_add_i32 s66, 0, 0x1c000
	v_add_u32_e32 v140, s65, v232
	v_add_u32_e32 v156, s66, v232
	ds_read_b128 v[120:123], v140
	ds_read_b128 v[124:127], v140 offset:1024
	ds_read_b128 v[136:139], v140 offset:2048
	ds_read_b128 v[140:143], v140 offset:3072
	ds_read_b128 v[144:147], v156
	ds_read_b128 v[148:151], v156 offset:1024
	ds_read_b128 v[152:155], v156 offset:2048
	ds_read_b128 v[156:159], v156 offset:3072
	s_add_u32 s26, s36, 0xb0000
	s_addc_u32 s27, s37, 0
	s_mov_b32 m0, s46
	v_lshl_add_u64 v[216:217], s[26:27], 0, v[184:185]
	ds_read_b128 v[160:163], v235 offset:32768
	ds_read_b128 v[164:167], v235 offset:33792
	ds_read_b128 v[168:171], v235 offset:34816
	ds_read_b128 v[172:175], v235 offset:35840
	ds_read_b128 v[176:179], v235 offset:36864
	ds_read_b128 v[180:183], v235 offset:37888
	ds_read_b128 v[200:203], v235 offset:38912
	ds_read_b128 v[204:207], v235 offset:39936
	global_load_lds_dwordx4 v[216:217], off
	s_mov_b32 m0, s47
	v_lshl_add_u64 v[216:217], s[26:27], 0, v[188:189]
	global_load_lds_dwordx4 v[216:217], off
	s_waitcnt vmcnt(8) lgkmcnt(0)
	s_barrier
	s_setprio 1
	v_mfma_f32_16x16x32_bf16 v[132:135], v[120:123], v[160:163], v[132:135]
	v_mfma_f32_16x16x32_bf16 v[132:135], v[124:127], v[164:167], v[132:135]
	v_mfma_f32_16x16x32_bf16 v[128:131], v[136:139], v[160:163], v[128:131]
	v_mfma_f32_16x16x32_bf16 v[128:131], v[140:143], v[164:167], v[128:131]
	v_mfma_f32_16x16x32_bf16 v[104:107], v[136:139], v[168:171], v[104:107]
	v_mfma_f32_16x16x32_bf16 v[104:107], v[140:143], v[172:175], v[104:107]
	v_mfma_f32_16x16x32_bf16 v[108:111], v[120:123], v[168:171], v[108:111]
	v_mfma_f32_16x16x32_bf16 v[108:111], v[124:127], v[172:175], v[108:111]
	v_mfma_f32_16x16x32_bf16 v[92:95], v[120:123], v[176:179], v[92:95]
	v_mfma_f32_16x16x32_bf16 v[92:95], v[124:127], v[180:183], v[92:95]
	v_mfma_f32_16x16x32_bf16 v[88:91], v[136:139], v[176:179], v[88:91]
	v_mfma_f32_16x16x32_bf16 v[88:91], v[140:143], v[180:183], v[88:91]
	v_mfma_f32_16x16x32_bf16 v[72:75], v[136:139], v[200:203], v[72:75]
	v_mfma_f32_16x16x32_bf16 v[72:75], v[140:143], v[204:207], v[72:75]
	v_mfma_f32_16x16x32_bf16 v[76:79], v[120:123], v[200:203], v[76:79]
	v_mfma_f32_16x16x32_bf16 v[76:79], v[124:127], v[204:207], v[76:79]
	v_mfma_f32_16x16x32_bf16 v[116:119], v[144:147], v[160:163], v[116:119]
	v_mfma_f32_16x16x32_bf16 v[116:119], v[148:151], v[164:167], v[116:119]
	v_mfma_f32_16x16x32_bf16 v[112:115], v[152:155], v[160:163], v[112:115]
	v_mfma_f32_16x16x32_bf16 v[112:115], v[156:159], v[164:167], v[112:115]
	v_mfma_f32_16x16x32_bf16 v[96:99], v[152:155], v[168:171], v[96:99]
	v_mfma_f32_16x16x32_bf16 v[96:99], v[156:159], v[172:175], v[96:99]
	v_mfma_f32_16x16x32_bf16 v[100:103], v[144:147], v[168:171], v[100:103]
	v_mfma_f32_16x16x32_bf16 v[100:103], v[148:151], v[172:175], v[100:103]
	v_mfma_f32_16x16x32_bf16 v[84:87], v[144:147], v[176:179], v[84:87]
	v_mfma_f32_16x16x32_bf16 v[84:87], v[148:151], v[180:183], v[84:87]
	v_mfma_f32_16x16x32_bf16 v[80:83], v[152:155], v[176:179], v[80:83]
	v_mfma_f32_16x16x32_bf16 v[80:83], v[156:159], v[180:183], v[80:83]
	s_setprio 2
	s_barrier
	v_mfma_f32_16x16x32_bf16 v[64:67], v[152:155], v[200:203], v[64:67]
	v_mfma_f32_16x16x32_bf16 v[64:67], v[156:159], v[204:207], v[64:67]
	v_mfma_f32_16x16x32_bf16 v[68:71], v[144:147], v[200:203], v[68:71]
	v_mfma_f32_16x16x32_bf16 v[68:71], v[148:151], v[204:207], v[68:71]
	s_setprio 2
	s_add_i32 s26, s65, s43
	v_lshl_add_u64 v[208:209], v[208:209], 0, s[20:21]
	s_mov_b32 m0, s26
	ds_read_b128 v[160:163], v235 offset:49152
	ds_read_b128 v[164:167], v235 offset:50176
	ds_read_b128 v[168:171], v235 offset:51200
	ds_read_b128 v[172:175], v235 offset:52224
	ds_read_b128 v[176:179], v235 offset:53248
	ds_read_b128 v[180:183], v235 offset:54272
	ds_read_b128 v[200:203], v235 offset:55296
	ds_read_b128 v[204:207], v235 offset:56320
	global_load_lds_dwordx4 v[208:209], off
	s_add_i32 m0, s26, 0x2000
	s_add_u32 s26, s30, 0xb0080
	v_lshl_add_u64 v[208:209], v[210:211], 0, s[20:21]
	s_addc_u32 s27, s31, 0
	s_add_i32 s30, s66, s43
	global_load_lds_dwordx4 v[208:209], off
	s_mov_b32 m0, s30
	v_lshl_add_u64 v[208:209], s[26:27], 0, v[186:187]
	global_load_lds_dwordx4 v[208:209], off
	s_add_i32 m0, s30, 0x2000
	v_lshl_add_u64 v[208:209], s[26:27], 0, v[190:191]
	global_load_lds_dwordx4 v[208:209], off
	s_mov_b32 m0, s49
	v_lshl_add_u64 v[208:209], v[212:213], 0, s[20:21]
	global_load_lds_dwordx4 v[208:209], off
	s_mov_b32 m0, s50
	v_lshl_add_u64 v[208:209], v[214:215], 0, s[20:21]
	global_load_lds_dwordx4 v[208:209], off
	s_waitcnt vmcnt(8) lgkmcnt(0)
	s_barrier
	s_setprio 1
	v_mfma_f32_16x16x32_bf16 v[60:63], v[120:123], v[160:163], v[60:63]
	v_mfma_f32_16x16x32_bf16 v[60:63], v[124:127], v[164:167], v[60:63]
	v_mfma_f32_16x16x32_bf16 v[56:59], v[136:139], v[160:163], v[56:59]
	v_mfma_f32_16x16x32_bf16 v[56:59], v[140:143], v[164:167], v[56:59]
	v_mfma_f32_16x16x32_bf16 v[40:43], v[136:139], v[168:171], v[40:43]
	v_mfma_f32_16x16x32_bf16 v[40:43], v[140:143], v[172:175], v[40:43]
	v_mfma_f32_16x16x32_bf16 v[44:47], v[120:123], v[168:171], v[44:47]
	v_mfma_f32_16x16x32_bf16 v[44:47], v[124:127], v[172:175], v[44:47]
	v_mfma_f32_16x16x32_bf16 v[28:31], v[120:123], v[176:179], v[28:31]
	v_mfma_f32_16x16x32_bf16 v[28:31], v[124:127], v[180:183], v[28:31]
	v_mfma_f32_16x16x32_bf16 v[24:27], v[136:139], v[176:179], v[24:27]
	v_mfma_f32_16x16x32_bf16 v[24:27], v[140:143], v[180:183], v[24:27]
	v_mfma_f32_16x16x32_bf16 v[8:11], v[136:139], v[200:203], v[8:11]
	v_mfma_f32_16x16x32_bf16 v[8:11], v[140:143], v[204:207], v[8:11]
	v_mfma_f32_16x16x32_bf16 v[12:15], v[120:123], v[200:203], v[12:15]
	v_mfma_f32_16x16x32_bf16 v[12:15], v[124:127], v[204:207], v[12:15]
	v_mfma_f32_16x16x32_bf16 v[52:55], v[144:147], v[160:163], v[52:55]
	v_mfma_f32_16x16x32_bf16 v[52:55], v[148:151], v[164:167], v[52:55]
	v_mfma_f32_16x16x32_bf16 v[48:51], v[152:155], v[160:163], v[48:51]
	v_mfma_f32_16x16x32_bf16 v[48:51], v[156:159], v[164:167], v[48:51]
	v_mfma_f32_16x16x32_bf16 v[32:35], v[152:155], v[168:171], v[32:35]
	v_mfma_f32_16x16x32_bf16 v[32:35], v[156:159], v[172:175], v[32:35]
	v_mfma_f32_16x16x32_bf16 v[36:39], v[144:147], v[168:171], v[36:39]
	v_mfma_f32_16x16x32_bf16 v[36:39], v[148:151], v[172:175], v[36:39]
	v_mfma_f32_16x16x32_bf16 v[20:23], v[144:147], v[176:179], v[20:23]
	v_mfma_f32_16x16x32_bf16 v[20:23], v[148:151], v[180:183], v[20:23]
	v_mfma_f32_16x16x32_bf16 v[16:19], v[152:155], v[176:179], v[16:19]
	v_mfma_f32_16x16x32_bf16 v[16:19], v[156:159], v[180:183], v[16:19]
	s_setprio 2
	s_barrier
	v_mfma_f32_16x16x32_bf16 v[0:3], v[152:155], v[200:203], v[0:3]
	v_mfma_f32_16x16x32_bf16 v[0:3], v[156:159], v[204:207], v[0:3]
	v_mfma_f32_16x16x32_bf16 v[4:7], v[144:147], v[200:203], v[4:7]
	v_mfma_f32_16x16x32_bf16 v[4:7], v[148:151], v[204:207], v[4:7]
	s_setprio 0
	s_add_i32 s64, s64, 2
	s_add_u32 s62, s62, 0x100
	s_addc_u32 s63, s63, 0
	s_cmp_gt_u32 s64, 41
	s_mov_b64 s[26:27], s[28:29]
.LBB0_866:
	ds_read_b128 v[120:123], v233
	ds_read_b128 v[124:127], v233 offset:1024
	ds_read_b128 v[136:139], v233 offset:2048
	ds_read_b128 v[140:143], v233 offset:3072
	ds_read_b128 v[144:147], v234
	ds_read_b128 v[148:151], v234 offset:1024
	ds_read_b128 v[152:155], v234 offset:2048
	ds_read_b128 v[156:159], v234 offset:3072
	s_add_u32 s28, s26, 0x100
	s_addc_u32 s29, s27, 0
	s_cmp_eq_u32 s64, 40
	s_cselect_b32 s37, s7, s29
	s_cselect_b32 s36, s6, s28
	s_cselect_b32 s31, s25, s63
	s_cselect_b32 s30, s24, s62
	v_lshl_add_u64 v[208:209], s[26:27], 0, v[192:193]
	s_add_i32 m0, s44, 0xc000
	ds_read_b128 v[160:163], v235
	ds_read_b128 v[164:167], v235 offset:1024
	ds_read_b128 v[168:171], v235 offset:2048
	ds_read_b128 v[172:175], v235 offset:3072
	ds_read_b128 v[176:179], v235 offset:4096
	ds_read_b128 v[180:183], v235 offset:5120
	ds_read_b128 v[200:203], v235 offset:6144
	ds_read_b128 v[204:207], v235 offset:7168
	global_load_lds_dwordx4 v[208:209], off
	s_add_i32 m0, s44, 0xe000
	v_lshl_add_u64 v[208:209], s[26:27], 0, v[194:195]
	global_load_lds_dwordx4 v[208:209], off
	s_waitcnt vmcnt(8) lgkmcnt(0)
	s_barrier
	s_setprio 1
	v_mfma_f32_16x16x32_bf16 v[132:135], v[120:123], v[160:163], v[132:135]
	v_mfma_f32_16x16x32_bf16 v[132:135], v[124:127], v[164:167], v[132:135]
	v_mfma_f32_16x16x32_bf16 v[128:131], v[136:139], v[160:163], v[128:131]
	v_mfma_f32_16x16x32_bf16 v[128:131], v[140:143], v[164:167], v[128:131]
	v_mfma_f32_16x16x32_bf16 v[104:107], v[136:139], v[168:171], v[104:107]
	v_mfma_f32_16x16x32_bf16 v[104:107], v[140:143], v[172:175], v[104:107]
	v_mfma_f32_16x16x32_bf16 v[108:111], v[120:123], v[168:171], v[108:111]
	v_mfma_f32_16x16x32_bf16 v[108:111], v[124:127], v[172:175], v[108:111]
	v_mfma_f32_16x16x32_bf16 v[92:95], v[120:123], v[176:179], v[92:95]
	v_mfma_f32_16x16x32_bf16 v[92:95], v[124:127], v[180:183], v[92:95]
	v_mfma_f32_16x16x32_bf16 v[88:91], v[136:139], v[176:179], v[88:91]
	v_mfma_f32_16x16x32_bf16 v[88:91], v[140:143], v[180:183], v[88:91]
	v_mfma_f32_16x16x32_bf16 v[72:75], v[136:139], v[200:203], v[72:75]
	v_mfma_f32_16x16x32_bf16 v[72:75], v[140:143], v[204:207], v[72:75]
	v_mfma_f32_16x16x32_bf16 v[76:79], v[120:123], v[200:203], v[76:79]
	v_mfma_f32_16x16x32_bf16 v[76:79], v[124:127], v[204:207], v[76:79]
	v_mfma_f32_16x16x32_bf16 v[116:119], v[144:147], v[160:163], v[116:119]
	v_mfma_f32_16x16x32_bf16 v[116:119], v[148:151], v[164:167], v[116:119]
	v_mfma_f32_16x16x32_bf16 v[112:115], v[152:155], v[160:163], v[112:115]
	v_mfma_f32_16x16x32_bf16 v[112:115], v[156:159], v[164:167], v[112:115]
	v_mfma_f32_16x16x32_bf16 v[96:99], v[152:155], v[168:171], v[96:99]
	v_mfma_f32_16x16x32_bf16 v[96:99], v[156:159], v[172:175], v[96:99]
	v_mfma_f32_16x16x32_bf16 v[100:103], v[144:147], v[168:171], v[100:103]
	v_mfma_f32_16x16x32_bf16 v[100:103], v[148:151], v[172:175], v[100:103]
	v_mfma_f32_16x16x32_bf16 v[84:87], v[144:147], v[176:179], v[84:87]
	v_mfma_f32_16x16x32_bf16 v[84:87], v[148:151], v[180:183], v[84:87]
	v_mfma_f32_16x16x32_bf16 v[80:83], v[152:155], v[176:179], v[80:83]
	v_mfma_f32_16x16x32_bf16 v[80:83], v[156:159], v[180:183], v[80:83]
	s_setprio 2
	s_barrier
	v_mfma_f32_16x16x32_bf16 v[64:67], v[152:155], v[200:203], v[64:67]
	v_mfma_f32_16x16x32_bf16 v[64:67], v[156:159], v[204:207], v[64:67]
	v_mfma_f32_16x16x32_bf16 v[68:71], v[144:147], v[200:203], v[68:71]
	v_mfma_f32_16x16x32_bf16 v[68:71], v[148:151], v[204:207], v[68:71]
	s_setprio 2
	s_add_i32 s26, s56, s43
	v_lshl_add_u64 v[208:209], s[30:31], 0, v[186:187]
	s_mov_b32 m0, s26
	ds_read_b128 v[160:163], v235 offset:16384
	ds_read_b128 v[164:167], v235 offset:17408
	ds_read_b128 v[168:171], v235 offset:18432
	ds_read_b128 v[172:175], v235 offset:19456
	ds_read_b128 v[176:179], v235 offset:20480
	ds_read_b128 v[180:183], v235 offset:21504
	ds_read_b128 v[200:203], v235 offset:22528
	ds_read_b128 v[204:207], v235 offset:23552
	global_load_lds_dwordx4 v[208:209], off
	s_add_i32 m0, s26, 0x2000
	s_add_u32 s26, s30, 0xb0000
	v_lshl_add_u64 v[210:211], s[30:31], 0, v[190:191]
	s_addc_u32 s27, s31, 0
	s_add_i32 s65, s57, s43
	global_load_lds_dwordx4 v[210:211], off
	v_lshl_add_u64 v[212:213], s[26:27], 0, v[186:187]
	s_mov_b32 m0, s65
	v_lshl_add_u64 v[214:215], s[36:37], 0, v[188:189]
	global_load_lds_dwordx4 v[212:213], off
	s_add_i32 m0, s65, 0x2000
	v_lshl_add_u64 v[212:213], s[26:27], 0, v[190:191]
	global_load_lds_dwordx4 v[212:213], off
	s_mov_b32 m0, s44
	v_lshl_add_u64 v[212:213], s[36:37], 0, v[184:185]
	global_load_lds_dwordx4 v[212:213], off
	s_mov_b32 m0, s45
	s_nop 0
	global_load_lds_dwordx4 v[214:215], off
	s_waitcnt vmcnt(8) lgkmcnt(0)
	s_barrier
	s_setprio 1
	v_mfma_f32_16x16x32_bf16 v[60:63], v[120:123], v[160:163], v[60:63]
	v_mfma_f32_16x16x32_bf16 v[60:63], v[124:127], v[164:167], v[60:63]
	v_mfma_f32_16x16x32_bf16 v[56:59], v[136:139], v[160:163], v[56:59]
	v_mfma_f32_16x16x32_bf16 v[56:59], v[140:143], v[164:167], v[56:59]
	v_mfma_f32_16x16x32_bf16 v[40:43], v[136:139], v[168:171], v[40:43]
	v_mfma_f32_16x16x32_bf16 v[40:43], v[140:143], v[172:175], v[40:43]
	v_mfma_f32_16x16x32_bf16 v[44:47], v[120:123], v[168:171], v[44:47]
	v_mfma_f32_16x16x32_bf16 v[44:47], v[124:127], v[172:175], v[44:47]
	v_mfma_f32_16x16x32_bf16 v[28:31], v[120:123], v[176:179], v[28:31]
	v_mfma_f32_16x16x32_bf16 v[28:31], v[124:127], v[180:183], v[28:31]
	v_mfma_f32_16x16x32_bf16 v[24:27], v[136:139], v[176:179], v[24:27]
	v_mfma_f32_16x16x32_bf16 v[24:27], v[140:143], v[180:183], v[24:27]
	v_mfma_f32_16x16x32_bf16 v[8:11], v[136:139], v[200:203], v[8:11]
	v_mfma_f32_16x16x32_bf16 v[8:11], v[140:143], v[204:207], v[8:11]
	v_mfma_f32_16x16x32_bf16 v[12:15], v[120:123], v[200:203], v[12:15]
	v_mfma_f32_16x16x32_bf16 v[12:15], v[124:127], v[204:207], v[12:15]
	v_mfma_f32_16x16x32_bf16 v[52:55], v[144:147], v[160:163], v[52:55]
	v_mfma_f32_16x16x32_bf16 v[52:55], v[148:151], v[164:167], v[52:55]
	v_mfma_f32_16x16x32_bf16 v[48:51], v[152:155], v[160:163], v[48:51]
	v_mfma_f32_16x16x32_bf16 v[48:51], v[156:159], v[164:167], v[48:51]
	v_mfma_f32_16x16x32_bf16 v[32:35], v[152:155], v[168:171], v[32:35]
	v_mfma_f32_16x16x32_bf16 v[32:35], v[156:159], v[172:175], v[32:35]
	v_mfma_f32_16x16x32_bf16 v[36:39], v[144:147], v[168:171], v[36:39]
	v_mfma_f32_16x16x32_bf16 v[36:39], v[148:151], v[172:175], v[36:39]
	v_mfma_f32_16x16x32_bf16 v[20:23], v[144:147], v[176:179], v[20:23]
	v_mfma_f32_16x16x32_bf16 v[20:23], v[148:151], v[180:183], v[20:23]
	v_mfma_f32_16x16x32_bf16 v[16:19], v[152:155], v[176:179], v[16:19]
	v_mfma_f32_16x16x32_bf16 v[16:19], v[156:159], v[180:183], v[16:19]
	s_setprio 2
	s_barrier
	v_mfma_f32_16x16x32_bf16 v[0:3], v[152:155], v[200:203], v[0:3]
	v_mfma_f32_16x16x32_bf16 v[0:3], v[156:159], v[204:207], v[0:3]
	v_mfma_f32_16x16x32_bf16 v[4:7], v[144:147], v[200:203], v[4:7]
	v_mfma_f32_16x16x32_bf16 v[4:7], v[148:151], v[204:207], v[4:7]
	s_setprio 0
	s_add_i32 s65, 0, 0x18000
	s_add_i32 s66, 0, 0x1c000
	v_add_u32_e32 v140, s65, v232
	v_add_u32_e32 v156, s66, v232
	ds_read_b128 v[120:123], v140
	ds_read_b128 v[124:127], v140 offset:1024
	ds_read_b128 v[136:139], v140 offset:2048
	ds_read_b128 v[140:143], v140 offset:3072
	ds_read_b128 v[144:147], v156
	ds_read_b128 v[148:151], v156 offset:1024
	ds_read_b128 v[152:155], v156 offset:2048
	ds_read_b128 v[156:159], v156 offset:3072
	s_add_u32 s26, s36, 0xb0000
	s_addc_u32 s27, s37, 0
	s_mov_b32 m0, s46
	v_lshl_add_u64 v[216:217], s[26:27], 0, v[184:185]
	ds_read_b128 v[160:163], v235 offset:32768
	ds_read_b128 v[164:167], v235 offset:33792
	ds_read_b128 v[168:171], v235 offset:34816
	ds_read_b128 v[172:175], v235 offset:35840
	ds_read_b128 v[176:179], v235 offset:36864
	ds_read_b128 v[180:183], v235 offset:37888
	ds_read_b128 v[200:203], v235 offset:38912
	ds_read_b128 v[204:207], v235 offset:39936
	global_load_lds_dwordx4 v[216:217], off
	s_mov_b32 m0, s47
	v_lshl_add_u64 v[216:217], s[26:27], 0, v[188:189]
	global_load_lds_dwordx4 v[216:217], off
	s_waitcnt vmcnt(8) lgkmcnt(0)
	s_barrier
	s_setprio 1
	v_mfma_f32_16x16x32_bf16 v[132:135], v[120:123], v[160:163], v[132:135]
	v_mfma_f32_16x16x32_bf16 v[132:135], v[124:127], v[164:167], v[132:135]
	v_mfma_f32_16x16x32_bf16 v[128:131], v[136:139], v[160:163], v[128:131]
	v_mfma_f32_16x16x32_bf16 v[128:131], v[140:143], v[164:167], v[128:131]
	v_mfma_f32_16x16x32_bf16 v[104:107], v[136:139], v[168:171], v[104:107]
	v_mfma_f32_16x16x32_bf16 v[104:107], v[140:143], v[172:175], v[104:107]
	v_mfma_f32_16x16x32_bf16 v[108:111], v[120:123], v[168:171], v[108:111]
	v_mfma_f32_16x16x32_bf16 v[108:111], v[124:127], v[172:175], v[108:111]
	v_mfma_f32_16x16x32_bf16 v[92:95], v[120:123], v[176:179], v[92:95]
	v_mfma_f32_16x16x32_bf16 v[92:95], v[124:127], v[180:183], v[92:95]
	v_mfma_f32_16x16x32_bf16 v[88:91], v[136:139], v[176:179], v[88:91]
	v_mfma_f32_16x16x32_bf16 v[88:91], v[140:143], v[180:183], v[88:91]
	v_mfma_f32_16x16x32_bf16 v[72:75], v[136:139], v[200:203], v[72:75]
	v_mfma_f32_16x16x32_bf16 v[72:75], v[140:143], v[204:207], v[72:75]
	v_mfma_f32_16x16x32_bf16 v[76:79], v[120:123], v[200:203], v[76:79]
	v_mfma_f32_16x16x32_bf16 v[76:79], v[124:127], v[204:207], v[76:79]
	v_mfma_f32_16x16x32_bf16 v[116:119], v[144:147], v[160:163], v[116:119]
	v_mfma_f32_16x16x32_bf16 v[116:119], v[148:151], v[164:167], v[116:119]
	v_mfma_f32_16x16x32_bf16 v[112:115], v[152:155], v[160:163], v[112:115]
	v_mfma_f32_16x16x32_bf16 v[112:115], v[156:159], v[164:167], v[112:115]
	v_mfma_f32_16x16x32_bf16 v[96:99], v[152:155], v[168:171], v[96:99]
	v_mfma_f32_16x16x32_bf16 v[96:99], v[156:159], v[172:175], v[96:99]
	v_mfma_f32_16x16x32_bf16 v[100:103], v[144:147], v[168:171], v[100:103]
	v_mfma_f32_16x16x32_bf16 v[100:103], v[148:151], v[172:175], v[100:103]
	v_mfma_f32_16x16x32_bf16 v[84:87], v[144:147], v[176:179], v[84:87]
	v_mfma_f32_16x16x32_bf16 v[84:87], v[148:151], v[180:183], v[84:87]
	v_mfma_f32_16x16x32_bf16 v[80:83], v[152:155], v[176:179], v[80:83]
	v_mfma_f32_16x16x32_bf16 v[80:83], v[156:159], v[180:183], v[80:83]
	s_setprio 2
	s_barrier
	v_mfma_f32_16x16x32_bf16 v[64:67], v[152:155], v[200:203], v[64:67]
	v_mfma_f32_16x16x32_bf16 v[64:67], v[156:159], v[204:207], v[64:67]
	v_mfma_f32_16x16x32_bf16 v[68:71], v[144:147], v[200:203], v[68:71]
	v_mfma_f32_16x16x32_bf16 v[68:71], v[148:151], v[204:207], v[68:71]
	s_setprio 2
	s_add_i32 s26, s65, s43
	v_lshl_add_u64 v[208:209], v[208:209], 0, s[20:21]
	s_mov_b32 m0, s26
	ds_read_b128 v[160:163], v235 offset:49152
	ds_read_b128 v[164:167], v235 offset:50176
	ds_read_b128 v[168:171], v235 offset:51200
	ds_read_b128 v[172:175], v235 offset:52224
	ds_read_b128 v[176:179], v235 offset:53248
	ds_read_b128 v[180:183], v235 offset:54272
	ds_read_b128 v[200:203], v235 offset:55296
	ds_read_b128 v[204:207], v235 offset:56320
	global_load_lds_dwordx4 v[208:209], off
	s_add_i32 m0, s26, 0x2000
	s_add_u32 s26, s30, 0xb0080
	v_lshl_add_u64 v[208:209], v[210:211], 0, s[20:21]
	s_addc_u32 s27, s31, 0
	s_add_i32 s30, s66, s43
	global_load_lds_dwordx4 v[208:209], off
	s_mov_b32 m0, s30
	v_lshl_add_u64 v[208:209], s[26:27], 0, v[186:187]
	global_load_lds_dwordx4 v[208:209], off
	s_add_i32 m0, s30, 0x2000
	v_lshl_add_u64 v[208:209], s[26:27], 0, v[190:191]
	global_load_lds_dwordx4 v[208:209], off
	s_mov_b32 m0, s49
	v_lshl_add_u64 v[208:209], v[212:213], 0, s[20:21]
	global_load_lds_dwordx4 v[208:209], off
	s_mov_b32 m0, s50
	v_lshl_add_u64 v[208:209], v[214:215], 0, s[20:21]
	global_load_lds_dwordx4 v[208:209], off
	s_waitcnt vmcnt(8) lgkmcnt(0)
	s_barrier
	s_setprio 1
	v_mfma_f32_16x16x32_bf16 v[60:63], v[120:123], v[160:163], v[60:63]
	v_mfma_f32_16x16x32_bf16 v[60:63], v[124:127], v[164:167], v[60:63]
	v_mfma_f32_16x16x32_bf16 v[56:59], v[136:139], v[160:163], v[56:59]
	v_mfma_f32_16x16x32_bf16 v[56:59], v[140:143], v[164:167], v[56:59]
	v_mfma_f32_16x16x32_bf16 v[40:43], v[136:139], v[168:171], v[40:43]
	v_mfma_f32_16x16x32_bf16 v[40:43], v[140:143], v[172:175], v[40:43]
	v_mfma_f32_16x16x32_bf16 v[44:47], v[120:123], v[168:171], v[44:47]
	v_mfma_f32_16x16x32_bf16 v[44:47], v[124:127], v[172:175], v[44:47]
	v_mfma_f32_16x16x32_bf16 v[28:31], v[120:123], v[176:179], v[28:31]
	v_mfma_f32_16x16x32_bf16 v[28:31], v[124:127], v[180:183], v[28:31]
	v_mfma_f32_16x16x32_bf16 v[24:27], v[136:139], v[176:179], v[24:27]
	v_mfma_f32_16x16x32_bf16 v[24:27], v[140:143], v[180:183], v[24:27]
	v_mfma_f32_16x16x32_bf16 v[8:11], v[136:139], v[200:203], v[8:11]
	v_mfma_f32_16x16x32_bf16 v[8:11], v[140:143], v[204:207], v[8:11]
	v_mfma_f32_16x16x32_bf16 v[12:15], v[120:123], v[200:203], v[12:15]
	v_mfma_f32_16x16x32_bf16 v[12:15], v[124:127], v[204:207], v[12:15]
	v_mfma_f32_16x16x32_bf16 v[52:55], v[144:147], v[160:163], v[52:55]
	v_mfma_f32_16x16x32_bf16 v[52:55], v[148:151], v[164:167], v[52:55]
	v_mfma_f32_16x16x32_bf16 v[48:51], v[152:155], v[160:163], v[48:51]
	v_mfma_f32_16x16x32_bf16 v[48:51], v[156:159], v[164:167], v[48:51]
	v_mfma_f32_16x16x32_bf16 v[32:35], v[152:155], v[168:171], v[32:35]
	v_mfma_f32_16x16x32_bf16 v[32:35], v[156:159], v[172:175], v[32:35]
	v_mfma_f32_16x16x32_bf16 v[36:39], v[144:147], v[168:171], v[36:39]
	v_mfma_f32_16x16x32_bf16 v[36:39], v[148:151], v[172:175], v[36:39]
	v_mfma_f32_16x16x32_bf16 v[20:23], v[144:147], v[176:179], v[20:23]
	v_mfma_f32_16x16x32_bf16 v[20:23], v[148:151], v[180:183], v[20:23]
	v_mfma_f32_16x16x32_bf16 v[16:19], v[152:155], v[176:179], v[16:19]
	v_mfma_f32_16x16x32_bf16 v[16:19], v[156:159], v[180:183], v[16:19]
	s_setprio 2
	s_barrier
	v_mfma_f32_16x16x32_bf16 v[0:3], v[152:155], v[200:203], v[0:3]
	v_mfma_f32_16x16x32_bf16 v[0:3], v[156:159], v[204:207], v[0:3]
	v_mfma_f32_16x16x32_bf16 v[4:7], v[144:147], v[200:203], v[4:7]
	v_mfma_f32_16x16x32_bf16 v[4:7], v[148:151], v[204:207], v[4:7]
	s_setprio 0
	s_add_i32 s64, s64, 2
	s_add_u32 s62, s62, 0x100
	s_addc_u32 s63, s63, 0
	s_cmp_gt_u32 s64, 41
	s_mov_b64 s[26:27], s[28:29]
	s_cbranch_scc0 .LBB0_866

.LBB0_951:
	s_ashr_i32 s27, s26, 31
	s_lshl_b64 s[30:31], s[26:27], 19
	s_add_u32 s30, s47, s30
	s_addc_u32 s31, s48, s31
	s_and_b64 s[36:37], s[4:5], exec
	s_cselect_b32 s27, s31, s7
	s_cselect_b32 s39, s30, s6
	s_ashr_i32 s29, s28, 31
	s_lshl_b64 s[36:37], s[28:29], 19
	s_add_u32 s36, s49, s36
	s_addc_u32 s37, s50, s37
	s_and_b64 s[44:45], s[4:5], exec
	s_cselect_b32 s29, s37, s41
	s_cselect_b32 s43, s36, s40
	s_add_u32 s6, s6, 0x40080
	s_addc_u32 s7, s7, 0
	s_add_u32 s71, s40, 0x100
	s_addc_u32 s72, s41, 0
	s_mov_b32 s73, -2
	ds_read_b128 v[144:147], v179
	ds_read_b128 v[148:151], v179 offset:1024
	ds_read_b128 v[152:155], v179 offset:2048
	ds_read_b128 v[156:159], v179 offset:3072
	ds_read_b128 v[160:163], v180
	ds_read_b128 v[164:167], v180 offset:1024
	ds_read_b128 v[168:171], v180 offset:2048
	ds_read_b128 v[172:175], v180 offset:3072
	s_add_u32 s40, s6, 0xfffc0080
	s_addc_u32 s41, s7, -1
	s_cmp_eq_u32 s73, 12
	s_cselect_b32 s45, s27, s41
	s_cselect_b32 s44, s39, s40
	s_cselect_b32 s41, s29, s72
	s_cselect_b32 s40, s43, s71
	v_lshl_add_u64 v[176:177], s[6:7], 0, v[136:137]
	s_add_i32 m0, s54, 0xc000
	ds_read_b128 v[184:187], v181
	ds_read_b128 v[188:191], v181 offset:1024
	ds_read_b128 v[192:195], v181 offset:2048
	ds_read_b128 v[196:199], v181 offset:3072
	ds_read_b128 v[200:203], v181 offset:4096
	ds_read_b128 v[204:207], v181 offset:5120
	ds_read_b128 v[208:211], v181 offset:6144
	ds_read_b128 v[212:215], v181 offset:7168
	global_load_lds_dwordx4 v[176:177], off
	s_add_i32 m0, s54, 0xe000
	v_lshl_add_u64 v[176:177], s[6:7], 0, v[138:139]
	global_load_lds_dwordx4 v[176:177], off
	s_waitcnt vmcnt(8) lgkmcnt(0)
	s_barrier
	s_setprio 1
	v_mfma_f32_16x16x32_bf16 v[124:127], v[144:147], v[184:187], 0
	v_mfma_f32_16x16x32_bf16 v[124:127], v[148:151], v[188:191], v[124:127]
	v_mfma_f32_16x16x32_bf16 v[120:123], v[152:155], v[184:187], 0
	v_mfma_f32_16x16x32_bf16 v[120:123], v[156:159], v[188:191], v[120:123]
	v_mfma_f32_16x16x32_bf16 v[104:107], v[152:155], v[192:195], 0
	v_mfma_f32_16x16x32_bf16 v[104:107], v[156:159], v[196:199], v[104:107]
	v_mfma_f32_16x16x32_bf16 v[108:111], v[144:147], v[192:195], 0
	v_mfma_f32_16x16x32_bf16 v[108:111], v[148:151], v[196:199], v[108:111]
	v_mfma_f32_16x16x32_bf16 v[92:95], v[144:147], v[200:203], 0
	v_mfma_f32_16x16x32_bf16 v[92:95], v[148:151], v[204:207], v[92:95]
	v_mfma_f32_16x16x32_bf16 v[88:91], v[152:155], v[200:203], 0
	v_mfma_f32_16x16x32_bf16 v[88:91], v[156:159], v[204:207], v[88:91]
	v_mfma_f32_16x16x32_bf16 v[72:75], v[152:155], v[208:211], 0
	v_mfma_f32_16x16x32_bf16 v[72:75], v[156:159], v[212:215], v[72:75]
	v_mfma_f32_16x16x32_bf16 v[76:79], v[144:147], v[208:211], 0
	v_mfma_f32_16x16x32_bf16 v[76:79], v[148:151], v[212:215], v[76:79]
	v_mfma_f32_16x16x32_bf16 v[116:119], v[160:163], v[184:187], 0
	v_mfma_f32_16x16x32_bf16 v[116:119], v[164:167], v[188:191], v[116:119]
	v_mfma_f32_16x16x32_bf16 v[112:115], v[168:171], v[184:187], 0
	v_mfma_f32_16x16x32_bf16 v[112:115], v[172:175], v[188:191], v[112:115]
	v_mfma_f32_16x16x32_bf16 v[96:99], v[168:171], v[192:195], 0
	v_mfma_f32_16x16x32_bf16 v[96:99], v[172:175], v[196:199], v[96:99]
	v_mfma_f32_16x16x32_bf16 v[100:103], v[160:163], v[192:195], 0
	v_mfma_f32_16x16x32_bf16 v[100:103], v[164:167], v[196:199], v[100:103]
	v_mfma_f32_16x16x32_bf16 v[84:87], v[160:163], v[200:203], 0
	v_mfma_f32_16x16x32_bf16 v[84:87], v[164:167], v[204:207], v[84:87]
	v_mfma_f32_16x16x32_bf16 v[80:83], v[168:171], v[200:203], 0
	v_mfma_f32_16x16x32_bf16 v[80:83], v[172:175], v[204:207], v[80:83]
	s_setprio 2
	s_barrier
	v_mfma_f32_16x16x32_bf16 v[64:67], v[168:171], v[208:211], 0
	v_mfma_f32_16x16x32_bf16 v[64:67], v[172:175], v[212:215], v[64:67]
	v_mfma_f32_16x16x32_bf16 v[68:71], v[160:163], v[208:211], 0
	v_mfma_f32_16x16x32_bf16 v[68:71], v[164:167], v[212:215], v[68:71]
	s_setprio 2
	s_add_i32 s74, s69, s51
	v_lshl_add_u64 v[176:177], s[40:41], 0, v[130:131]
	s_mov_b32 m0, s74
	ds_read_b128 v[184:187], v181 offset:16384
	ds_read_b128 v[188:191], v181 offset:17408
	ds_read_b128 v[192:195], v181 offset:18432
	ds_read_b128 v[196:199], v181 offset:19456
	ds_read_b128 v[200:203], v181 offset:20480
	ds_read_b128 v[204:207], v181 offset:21504
	ds_read_b128 v[208:211], v181 offset:22528
	ds_read_b128 v[212:215], v181 offset:23552
	global_load_lds_dwordx4 v[176:177], off
	s_add_i32 m0, s74, 0x2000
	s_add_u32 s74, s40, 0x40000
	v_lshl_add_u64 v[216:217], s[40:41], 0, v[134:135]
	s_addc_u32 s75, s41, 0
	s_add_i32 s76, s70, s51
	global_load_lds_dwordx4 v[216:217], off
	v_lshl_add_u64 v[218:219], s[74:75], 0, v[130:131]
	s_mov_b32 m0, s76
	v_lshl_add_u64 v[220:221], s[44:45], 0, v[132:133]
	global_load_lds_dwordx4 v[218:219], off
	s_add_i32 m0, s76, 0x2000
	v_lshl_add_u64 v[218:219], s[74:75], 0, v[134:135]
	global_load_lds_dwordx4 v[218:219], off
	s_mov_b32 m0, s54
	v_lshl_add_u64 v[218:219], s[44:45], 0, v[128:129]
	global_load_lds_dwordx4 v[218:219], off
	s_mov_b32 m0, s55
	s_nop 0
	global_load_lds_dwordx4 v[220:221], off
	s_waitcnt vmcnt(8) lgkmcnt(0)
	s_barrier
	s_setprio 1
	v_mfma_f32_16x16x32_bf16 v[60:63], v[144:147], v[184:187], 0
	v_mfma_f32_16x16x32_bf16 v[60:63], v[148:151], v[188:191], v[60:63]
	v_mfma_f32_16x16x32_bf16 v[56:59], v[152:155], v[184:187], 0
	v_mfma_f32_16x16x32_bf16 v[56:59], v[156:159], v[188:191], v[56:59]
	v_mfma_f32_16x16x32_bf16 v[40:43], v[152:155], v[192:195], 0
	v_mfma_f32_16x16x32_bf16 v[40:43], v[156:159], v[196:199], v[40:43]
	v_mfma_f32_16x16x32_bf16 v[44:47], v[144:147], v[192:195], 0
	v_mfma_f32_16x16x32_bf16 v[44:47], v[148:151], v[196:199], v[44:47]
	v_mfma_f32_16x16x32_bf16 v[28:31], v[144:147], v[200:203], 0
	v_mfma_f32_16x16x32_bf16 v[28:31], v[148:151], v[204:207], v[28:31]
	v_mfma_f32_16x16x32_bf16 v[24:27], v[152:155], v[200:203], 0
	v_mfma_f32_16x16x32_bf16 v[24:27], v[156:159], v[204:207], v[24:27]
	v_mfma_f32_16x16x32_bf16 v[8:11], v[152:155], v[208:211], 0
	v_mfma_f32_16x16x32_bf16 v[8:11], v[156:159], v[212:215], v[8:11]
	v_mfma_f32_16x16x32_bf16 v[12:15], v[144:147], v[208:211], 0
	v_mfma_f32_16x16x32_bf16 v[12:15], v[148:151], v[212:215], v[12:15]
	v_mfma_f32_16x16x32_bf16 v[52:55], v[160:163], v[184:187], 0
	v_mfma_f32_16x16x32_bf16 v[52:55], v[164:167], v[188:191], v[52:55]
	v_mfma_f32_16x16x32_bf16 v[48:51], v[168:171], v[184:187], 0
	v_mfma_f32_16x16x32_bf16 v[48:51], v[172:175], v[188:191], v[48:51]
	v_mfma_f32_16x16x32_bf16 v[32:35], v[168:171], v[192:195], 0
	v_mfma_f32_16x16x32_bf16 v[32:35], v[172:175], v[196:199], v[32:35]
	v_mfma_f32_16x16x32_bf16 v[36:39], v[160:163], v[192:195], 0
	v_mfma_f32_16x16x32_bf16 v[36:39], v[164:167], v[196:199], v[36:39]
	v_mfma_f32_16x16x32_bf16 v[20:23], v[160:163], v[200:203], 0
	v_mfma_f32_16x16x32_bf16 v[20:23], v[164:167], v[204:207], v[20:23]
	v_mfma_f32_16x16x32_bf16 v[16:19], v[168:171], v[200:203], 0
	v_mfma_f32_16x16x32_bf16 v[16:19], v[172:175], v[204:207], v[16:19]
	s_setprio 2
	s_barrier
	v_mfma_f32_16x16x32_bf16 v[0:3], v[168:171], v[208:211], 0
	v_mfma_f32_16x16x32_bf16 v[0:3], v[172:175], v[212:215], v[0:3]
	v_mfma_f32_16x16x32_bf16 v[4:7], v[160:163], v[208:211], 0
	v_mfma_f32_16x16x32_bf16 v[4:7], v[164:167], v[212:215], v[4:7]
	s_setprio 0
	s_add_i32 s74, 0, 0x18000
	s_add_i32 s75, 0, 0x1c000
	v_add_u32_e32 v156, s74, v178
	v_add_u32_e32 v172, s75, v178
	ds_read_b128 v[144:147], v156
	ds_read_b128 v[148:151], v156 offset:1024
	ds_read_b128 v[152:155], v156 offset:2048
	ds_read_b128 v[156:159], v156 offset:3072
	ds_read_b128 v[160:163], v172
	ds_read_b128 v[164:167], v172 offset:1024
	ds_read_b128 v[168:171], v172 offset:2048
	ds_read_b128 v[172:175], v172 offset:3072
	s_add_u32 s44, s44, 0x40000
	s_addc_u32 s45, s45, 0
	s_mov_b32 m0, s56
	v_lshl_add_u64 v[222:223], s[44:45], 0, v[128:129]
	ds_read_b128 v[184:187], v181 offset:32768
	ds_read_b128 v[188:191], v181 offset:33792
	ds_read_b128 v[192:195], v181 offset:34816
	ds_read_b128 v[196:199], v181 offset:35840
	ds_read_b128 v[200:203], v181 offset:36864
	ds_read_b128 v[204:207], v181 offset:37888
	ds_read_b128 v[208:211], v181 offset:38912
	ds_read_b128 v[212:215], v181 offset:39936
	global_load_lds_dwordx4 v[222:223], off
	s_mov_b32 m0, s57
	v_lshl_add_u64 v[222:223], s[44:45], 0, v[132:133]
	global_load_lds_dwordx4 v[222:223], off
	s_waitcnt vmcnt(8) lgkmcnt(0)
	s_barrier
	s_setprio 1
	v_mfma_f32_16x16x32_bf16 v[124:127], v[144:147], v[184:187], v[124:127]
	v_mfma_f32_16x16x32_bf16 v[124:127], v[148:151], v[188:191], v[124:127]
	v_mfma_f32_16x16x32_bf16 v[120:123], v[152:155], v[184:187], v[120:123]
	v_mfma_f32_16x16x32_bf16 v[120:123], v[156:159], v[188:191], v[120:123]
	v_mfma_f32_16x16x32_bf16 v[104:107], v[152:155], v[192:195], v[104:107]
	v_mfma_f32_16x16x32_bf16 v[104:107], v[156:159], v[196:199], v[104:107]
	v_mfma_f32_16x16x32_bf16 v[108:111], v[144:147], v[192:195], v[108:111]
	v_mfma_f32_16x16x32_bf16 v[108:111], v[148:151], v[196:199], v[108:111]
	v_mfma_f32_16x16x32_bf16 v[92:95], v[144:147], v[200:203], v[92:95]
	v_mfma_f32_16x16x32_bf16 v[92:95], v[148:151], v[204:207], v[92:95]
	v_mfma_f32_16x16x32_bf16 v[88:91], v[152:155], v[200:203], v[88:91]
	v_mfma_f32_16x16x32_bf16 v[88:91], v[156:159], v[204:207], v[88:91]
	v_mfma_f32_16x16x32_bf16 v[72:75], v[152:155], v[208:211], v[72:75]
	v_mfma_f32_16x16x32_bf16 v[72:75], v[156:159], v[212:215], v[72:75]
	v_mfma_f32_16x16x32_bf16 v[76:79], v[144:147], v[208:211], v[76:79]
	v_mfma_f32_16x16x32_bf16 v[76:79], v[148:151], v[212:215], v[76:79]
	v_mfma_f32_16x16x32_bf16 v[116:119], v[160:163], v[184:187], v[116:119]
	v_mfma_f32_16x16x32_bf16 v[116:119], v[164:167], v[188:191], v[116:119]
	v_mfma_f32_16x16x32_bf16 v[112:115], v[168:171], v[184:187], v[112:115]
	v_mfma_f32_16x16x32_bf16 v[112:115], v[172:175], v[188:191], v[112:115]
	v_mfma_f32_16x16x32_bf16 v[96:99], v[168:171], v[192:195], v[96:99]
	v_mfma_f32_16x16x32_bf16 v[96:99], v[172:175], v[196:199], v[96:99]
	v_mfma_f32_16x16x32_bf16 v[100:103], v[160:163], v[192:195], v[100:103]
	v_mfma_f32_16x16x32_bf16 v[100:103], v[164:167], v[196:199], v[100:103]
	v_mfma_f32_16x16x32_bf16 v[84:87], v[160:163], v[200:203], v[84:87]
	v_mfma_f32_16x16x32_bf16 v[84:87], v[164:167], v[204:207], v[84:87]
	v_mfma_f32_16x16x32_bf16 v[80:83], v[168:171], v[200:203], v[80:83]
	v_mfma_f32_16x16x32_bf16 v[80:83], v[172:175], v[204:207], v[80:83]
	s_setprio 2
	s_barrier
	v_mfma_f32_16x16x32_bf16 v[64:67], v[168:171], v[208:211], v[64:67]
	v_mfma_f32_16x16x32_bf16 v[64:67], v[172:175], v[212:215], v[64:67]
	v_mfma_f32_16x16x32_bf16 v[68:71], v[160:163], v[208:211], v[68:71]
	v_mfma_f32_16x16x32_bf16 v[68:71], v[164:167], v[212:215], v[68:71]
	s_setprio 2
	s_add_i32 s44, s74, s51
	v_lshl_add_u64 v[176:177], v[176:177], 0, s[22:23]
	s_mov_b32 m0, s44
	ds_read_b128 v[184:187], v181 offset:49152
	ds_read_b128 v[188:191], v181 offset:50176
	ds_read_b128 v[192:195], v181 offset:51200
	ds_read_b128 v[196:199], v181 offset:52224
	ds_read_b128 v[200:203], v181 offset:53248
	ds_read_b128 v[204:207], v181 offset:54272
	ds_read_b128 v[208:211], v181 offset:55296
	ds_read_b128 v[212:215], v181 offset:56320
	global_load_lds_dwordx4 v[176:177], off
	s_add_i32 m0, s44, 0x2000
	s_add_u32 s40, s40, 0x40080
	v_lshl_add_u64 v[176:177], v[216:217], 0, s[22:23]
	s_addc_u32 s41, s41, 0
	s_add_i32 s44, s75, s51
	global_load_lds_dwordx4 v[176:177], off
	s_mov_b32 m0, s44
	v_lshl_add_u64 v[176:177], s[40:41], 0, v[130:131]
	global_load_lds_dwordx4 v[176:177], off
	s_add_i32 m0, s44, 0x2000
	v_lshl_add_u64 v[176:177], s[40:41], 0, v[134:135]
	global_load_lds_dwordx4 v[176:177], off
	s_mov_b32 m0, s64
	v_lshl_add_u64 v[176:177], v[218:219], 0, s[22:23]
	global_load_lds_dwordx4 v[176:177], off
	s_mov_b32 m0, s65
	v_lshl_add_u64 v[176:177], v[220:221], 0, s[22:23]
	global_load_lds_dwordx4 v[176:177], off
	s_waitcnt vmcnt(8) lgkmcnt(0)
	s_barrier
	s_setprio 1
	v_mfma_f32_16x16x32_bf16 v[60:63], v[144:147], v[184:187], v[60:63]
	v_mfma_f32_16x16x32_bf16 v[60:63], v[148:151], v[188:191], v[60:63]
	v_mfma_f32_16x16x32_bf16 v[56:59], v[152:155], v[184:187], v[56:59]
	v_mfma_f32_16x16x32_bf16 v[56:59], v[156:159], v[188:191], v[56:59]
	v_mfma_f32_16x16x32_bf16 v[40:43], v[152:155], v[192:195], v[40:43]
	v_mfma_f32_16x16x32_bf16 v[40:43], v[156:159], v[196:199], v[40:43]
	v_mfma_f32_16x16x32_bf16 v[44:47], v[144:147], v[192:195], v[44:47]
	v_mfma_f32_16x16x32_bf16 v[44:47], v[148:151], v[196:199], v[44:47]
	v_mfma_f32_16x16x32_bf16 v[28:31], v[144:147], v[200:203], v[28:31]
	v_mfma_f32_16x16x32_bf16 v[28:31], v[148:151], v[204:207], v[28:31]
	v_mfma_f32_16x16x32_bf16 v[24:27], v[152:155], v[200:203], v[24:27]
	v_mfma_f32_16x16x32_bf16 v[24:27], v[156:159], v[204:207], v[24:27]
	v_mfma_f32_16x16x32_bf16 v[8:11], v[152:155], v[208:211], v[8:11]
	v_mfma_f32_16x16x32_bf16 v[8:11], v[156:159], v[212:215], v[8:11]
	v_mfma_f32_16x16x32_bf16 v[12:15], v[144:147], v[208:211], v[12:15]
	v_mfma_f32_16x16x32_bf16 v[12:15], v[148:151], v[212:215], v[12:15]
	v_mfma_f32_16x16x32_bf16 v[52:55], v[160:163], v[184:187], v[52:55]
	v_mfma_f32_16x16x32_bf16 v[52:55], v[164:167], v[188:191], v[52:55]
	v_mfma_f32_16x16x32_bf16 v[48:51], v[168:171], v[184:187], v[48:51]
	v_mfma_f32_16x16x32_bf16 v[48:51], v[172:175], v[188:191], v[48:51]
	v_mfma_f32_16x16x32_bf16 v[32:35], v[168:171], v[192:195], v[32:35]
	v_mfma_f32_16x16x32_bf16 v[32:35], v[172:175], v[196:199], v[32:35]
	v_mfma_f32_16x16x32_bf16 v[36:39], v[160:163], v[192:195], v[36:39]
	v_mfma_f32_16x16x32_bf16 v[36:39], v[164:167], v[196:199], v[36:39]
	v_mfma_f32_16x16x32_bf16 v[20:23], v[160:163], v[200:203], v[20:23]
	v_mfma_f32_16x16x32_bf16 v[20:23], v[164:167], v[204:207], v[20:23]
	v_mfma_f32_16x16x32_bf16 v[16:19], v[168:171], v[200:203], v[16:19]
	v_mfma_f32_16x16x32_bf16 v[16:19], v[172:175], v[204:207], v[16:19]
	s_setprio 2
	s_barrier
	v_mfma_f32_16x16x32_bf16 v[0:3], v[168:171], v[208:211], v[0:3]
	v_mfma_f32_16x16x32_bf16 v[0:3], v[172:175], v[212:215], v[0:3]
	v_mfma_f32_16x16x32_bf16 v[4:7], v[160:163], v[208:211], v[4:7]
	v_mfma_f32_16x16x32_bf16 v[4:7], v[164:167], v[212:215], v[4:7]
	s_setprio 0
	s_add_i32 s73, s73, 2
	s_add_u32 s6, s6, 0x100
	s_addc_u32 s7, s7, 0
	s_add_u32 s71, s71, 0x100
	s_addc_u32 s72, s72, 0
	s_cmp_gt_u32 s73, 13
.LBB0_952:
	ds_read_b128 v[144:147], v179
	ds_read_b128 v[148:151], v179 offset:1024
	ds_read_b128 v[152:155], v179 offset:2048
	ds_read_b128 v[156:159], v179 offset:3072
	ds_read_b128 v[160:163], v180
	ds_read_b128 v[164:167], v180 offset:1024
	ds_read_b128 v[168:171], v180 offset:2048
	ds_read_b128 v[172:175], v180 offset:3072
	s_add_u32 s40, s6, 0xfffc0080
	s_addc_u32 s41, s7, -1
	s_cmp_eq_u32 s73, 12
	s_cselect_b32 s45, s27, s41
	s_cselect_b32 s44, s39, s40
	s_cselect_b32 s41, s29, s72
	s_cselect_b32 s40, s43, s71
	v_lshl_add_u64 v[176:177], s[6:7], 0, v[136:137]
	s_add_i32 m0, s54, 0xc000
	ds_read_b128 v[184:187], v181
	ds_read_b128 v[188:191], v181 offset:1024
	ds_read_b128 v[192:195], v181 offset:2048
	ds_read_b128 v[196:199], v181 offset:3072
	ds_read_b128 v[200:203], v181 offset:4096
	ds_read_b128 v[204:207], v181 offset:5120
	ds_read_b128 v[208:211], v181 offset:6144
	ds_read_b128 v[212:215], v181 offset:7168
	global_load_lds_dwordx4 v[176:177], off
	s_add_i32 m0, s54, 0xe000
	v_lshl_add_u64 v[176:177], s[6:7], 0, v[138:139]
	global_load_lds_dwordx4 v[176:177], off
	s_waitcnt vmcnt(8) lgkmcnt(0)
	s_barrier
	s_setprio 1
	v_mfma_f32_16x16x32_bf16 v[124:127], v[144:147], v[184:187], v[124:127]
	v_mfma_f32_16x16x32_bf16 v[124:127], v[148:151], v[188:191], v[124:127]
	v_mfma_f32_16x16x32_bf16 v[120:123], v[152:155], v[184:187], v[120:123]
	v_mfma_f32_16x16x32_bf16 v[120:123], v[156:159], v[188:191], v[120:123]
	v_mfma_f32_16x16x32_bf16 v[104:107], v[152:155], v[192:195], v[104:107]
	v_mfma_f32_16x16x32_bf16 v[104:107], v[156:159], v[196:199], v[104:107]
	v_mfma_f32_16x16x32_bf16 v[108:111], v[144:147], v[192:195], v[108:111]
	v_mfma_f32_16x16x32_bf16 v[108:111], v[148:151], v[196:199], v[108:111]
	v_mfma_f32_16x16x32_bf16 v[92:95], v[144:147], v[200:203], v[92:95]
	v_mfma_f32_16x16x32_bf16 v[92:95], v[148:151], v[204:207], v[92:95]
	v_mfma_f32_16x16x32_bf16 v[88:91], v[152:155], v[200:203], v[88:91]
	v_mfma_f32_16x16x32_bf16 v[88:91], v[156:159], v[204:207], v[88:91]
	v_mfma_f32_16x16x32_bf16 v[72:75], v[152:155], v[208:211], v[72:75]
	v_mfma_f32_16x16x32_bf16 v[72:75], v[156:159], v[212:215], v[72:75]
	v_mfma_f32_16x16x32_bf16 v[76:79], v[144:147], v[208:211], v[76:79]
	v_mfma_f32_16x16x32_bf16 v[76:79], v[148:151], v[212:215], v[76:79]
	v_mfma_f32_16x16x32_bf16 v[116:119], v[160:163], v[184:187], v[116:119]
	v_mfma_f32_16x16x32_bf16 v[116:119], v[164:167], v[188:191], v[116:119]
	v_mfma_f32_16x16x32_bf16 v[112:115], v[168:171], v[184:187], v[112:115]
	v_mfma_f32_16x16x32_bf16 v[112:115], v[172:175], v[188:191], v[112:115]
	v_mfma_f32_16x16x32_bf16 v[96:99], v[168:171], v[192:195], v[96:99]
	v_mfma_f32_16x16x32_bf16 v[96:99], v[172:175], v[196:199], v[96:99]
	v_mfma_f32_16x16x32_bf16 v[100:103], v[160:163], v[192:195], v[100:103]
	v_mfma_f32_16x16x32_bf16 v[100:103], v[164:167], v[196:199], v[100:103]
	v_mfma_f32_16x16x32_bf16 v[84:87], v[160:163], v[200:203], v[84:87]
	v_mfma_f32_16x16x32_bf16 v[84:87], v[164:167], v[204:207], v[84:87]
	v_mfma_f32_16x16x32_bf16 v[80:83], v[168:171], v[200:203], v[80:83]
	v_mfma_f32_16x16x32_bf16 v[80:83], v[172:175], v[204:207], v[80:83]
	s_setprio 2
	s_barrier
	v_mfma_f32_16x16x32_bf16 v[64:67], v[168:171], v[208:211], v[64:67]
	v_mfma_f32_16x16x32_bf16 v[64:67], v[172:175], v[212:215], v[64:67]
	v_mfma_f32_16x16x32_bf16 v[68:71], v[160:163], v[208:211], v[68:71]
	v_mfma_f32_16x16x32_bf16 v[68:71], v[164:167], v[212:215], v[68:71]
	s_setprio 2
	s_add_i32 s74, s69, s51
	v_lshl_add_u64 v[176:177], s[40:41], 0, v[130:131]
	s_mov_b32 m0, s74
	ds_read_b128 v[184:187], v181 offset:16384
	ds_read_b128 v[188:191], v181 offset:17408
	ds_read_b128 v[192:195], v181 offset:18432
	ds_read_b128 v[196:199], v181 offset:19456
	ds_read_b128 v[200:203], v181 offset:20480
	ds_read_b128 v[204:207], v181 offset:21504
	ds_read_b128 v[208:211], v181 offset:22528
	ds_read_b128 v[212:215], v181 offset:23552
	global_load_lds_dwordx4 v[176:177], off
	s_add_i32 m0, s74, 0x2000
	s_add_u32 s74, s40, 0x40000
	v_lshl_add_u64 v[216:217], s[40:41], 0, v[134:135]
	s_addc_u32 s75, s41, 0
	s_add_i32 s76, s70, s51
	global_load_lds_dwordx4 v[216:217], off
	v_lshl_add_u64 v[218:219], s[74:75], 0, v[130:131]
	s_mov_b32 m0, s76
	v_lshl_add_u64 v[220:221], s[44:45], 0, v[132:133]
	global_load_lds_dwordx4 v[218:219], off
	s_add_i32 m0, s76, 0x2000
	v_lshl_add_u64 v[218:219], s[74:75], 0, v[134:135]
	global_load_lds_dwordx4 v[218:219], off
	s_mov_b32 m0, s54
	v_lshl_add_u64 v[218:219], s[44:45], 0, v[128:129]
	global_load_lds_dwordx4 v[218:219], off
	s_mov_b32 m0, s55
	s_nop 0
	global_load_lds_dwordx4 v[220:221], off
	s_waitcnt vmcnt(8) lgkmcnt(0)
	s_barrier
	s_setprio 1
	v_mfma_f32_16x16x32_bf16 v[60:63], v[144:147], v[184:187], v[60:63]
	v_mfma_f32_16x16x32_bf16 v[60:63], v[148:151], v[188:191], v[60:63]
	v_mfma_f32_16x16x32_bf16 v[56:59], v[152:155], v[184:187], v[56:59]
	v_mfma_f32_16x16x32_bf16 v[56:59], v[156:159], v[188:191], v[56:59]
	v_mfma_f32_16x16x32_bf16 v[40:43], v[152:155], v[192:195], v[40:43]
	v_mfma_f32_16x16x32_bf16 v[40:43], v[156:159], v[196:199], v[40:43]
	v_mfma_f32_16x16x32_bf16 v[44:47], v[144:147], v[192:195], v[44:47]
	v_mfma_f32_16x16x32_bf16 v[44:47], v[148:151], v[196:199], v[44:47]
	v_mfma_f32_16x16x32_bf16 v[28:31], v[144:147], v[200:203], v[28:31]
	v_mfma_f32_16x16x32_bf16 v[28:31], v[148:151], v[204:207], v[28:31]
	v_mfma_f32_16x16x32_bf16 v[24:27], v[152:155], v[200:203], v[24:27]
	v_mfma_f32_16x16x32_bf16 v[24:27], v[156:159], v[204:207], v[24:27]
	v_mfma_f32_16x16x32_bf16 v[8:11], v[152:155], v[208:211], v[8:11]
	v_mfma_f32_16x16x32_bf16 v[8:11], v[156:159], v[212:215], v[8:11]
	v_mfma_f32_16x16x32_bf16 v[12:15], v[144:147], v[208:211], v[12:15]
	v_mfma_f32_16x16x32_bf16 v[12:15], v[148:151], v[212:215], v[12:15]
	v_mfma_f32_16x16x32_bf16 v[52:55], v[160:163], v[184:187], v[52:55]
	v_mfma_f32_16x16x32_bf16 v[52:55], v[164:167], v[188:191], v[52:55]
	v_mfma_f32_16x16x32_bf16 v[48:51], v[168:171], v[184:187], v[48:51]
	v_mfma_f32_16x16x32_bf16 v[48:51], v[172:175], v[188:191], v[48:51]
	v_mfma_f32_16x16x32_bf16 v[32:35], v[168:171], v[192:195], v[32:35]
	v_mfma_f32_16x16x32_bf16 v[32:35], v[172:175], v[196:199], v[32:35]
	v_mfma_f32_16x16x32_bf16 v[36:39], v[160:163], v[192:195], v[36:39]
	v_mfma_f32_16x16x32_bf16 v[36:39], v[164:167], v[196:199], v[36:39]
	v_mfma_f32_16x16x32_bf16 v[20:23], v[160:163], v[200:203], v[20:23]
	v_mfma_f32_16x16x32_bf16 v[20:23], v[164:167], v[204:207], v[20:23]
	v_mfma_f32_16x16x32_bf16 v[16:19], v[168:171], v[200:203], v[16:19]
	v_mfma_f32_16x16x32_bf16 v[16:19], v[172:175], v[204:207], v[16:19]
	s_setprio 2
	s_barrier
	v_mfma_f32_16x16x32_bf16 v[0:3], v[168:171], v[208:211], v[0:3]
	v_mfma_f32_16x16x32_bf16 v[0:3], v[172:175], v[212:215], v[0:3]
	v_mfma_f32_16x16x32_bf16 v[4:7], v[160:163], v[208:211], v[4:7]
	v_mfma_f32_16x16x32_bf16 v[4:7], v[164:167], v[212:215], v[4:7]
	s_setprio 0
	s_add_i32 s74, 0, 0x18000
	s_add_i32 s75, 0, 0x1c000
	v_add_u32_e32 v156, s74, v178
	v_add_u32_e32 v172, s75, v178
	ds_read_b128 v[144:147], v156
	ds_read_b128 v[148:151], v156 offset:1024
	ds_read_b128 v[152:155], v156 offset:2048
	ds_read_b128 v[156:159], v156 offset:3072
	ds_read_b128 v[160:163], v172
	ds_read_b128 v[164:167], v172 offset:1024
	ds_read_b128 v[168:171], v172 offset:2048
	ds_read_b128 v[172:175], v172 offset:3072
	s_add_u32 s44, s44, 0x40000
	s_addc_u32 s45, s45, 0
	s_mov_b32 m0, s56
	v_lshl_add_u64 v[222:223], s[44:45], 0, v[128:129]
	ds_read_b128 v[184:187], v181 offset:32768
	ds_read_b128 v[188:191], v181 offset:33792
	ds_read_b128 v[192:195], v181 offset:34816
	ds_read_b128 v[196:199], v181 offset:35840
	ds_read_b128 v[200:203], v181 offset:36864
	ds_read_b128 v[204:207], v181 offset:37888
	ds_read_b128 v[208:211], v181 offset:38912
	ds_read_b128 v[212:215], v181 offset:39936
	global_load_lds_dwordx4 v[222:223], off
	s_mov_b32 m0, s57
	v_lshl_add_u64 v[222:223], s[44:45], 0, v[132:133]
	global_load_lds_dwordx4 v[222:223], off
	s_waitcnt vmcnt(8) lgkmcnt(0)
	s_barrier
	s_setprio 1
	v_mfma_f32_16x16x32_bf16 v[124:127], v[144:147], v[184:187], v[124:127]
	v_mfma_f32_16x16x32_bf16 v[124:127], v[148:151], v[188:191], v[124:127]
	v_mfma_f32_16x16x32_bf16 v[120:123], v[152:155], v[184:187], v[120:123]
	v_mfma_f32_16x16x32_bf16 v[120:123], v[156:159], v[188:191], v[120:123]
	v_mfma_f32_16x16x32_bf16 v[104:107], v[152:155], v[192:195], v[104:107]
	v_mfma_f32_16x16x32_bf16 v[104:107], v[156:159], v[196:199], v[104:107]
	v_mfma_f32_16x16x32_bf16 v[108:111], v[144:147], v[192:195], v[108:111]
	v_mfma_f32_16x16x32_bf16 v[108:111], v[148:151], v[196:199], v[108:111]
	v_mfma_f32_16x16x32_bf16 v[92:95], v[144:147], v[200:203], v[92:95]
	v_mfma_f32_16x16x32_bf16 v[92:95], v[148:151], v[204:207], v[92:95]
	v_mfma_f32_16x16x32_bf16 v[88:91], v[152:155], v[200:203], v[88:91]
	v_mfma_f32_16x16x32_bf16 v[88:91], v[156:159], v[204:207], v[88:91]
	v_mfma_f32_16x16x32_bf16 v[72:75], v[152:155], v[208:211], v[72:75]
	v_mfma_f32_16x16x32_bf16 v[72:75], v[156:159], v[212:215], v[72:75]
	v_mfma_f32_16x16x32_bf16 v[76:79], v[144:147], v[208:211], v[76:79]
	v_mfma_f32_16x16x32_bf16 v[76:79], v[148:151], v[212:215], v[76:79]
	v_mfma_f32_16x16x32_bf16 v[116:119], v[160:163], v[184:187], v[116:119]
	v_mfma_f32_16x16x32_bf16 v[116:119], v[164:167], v[188:191], v[116:119]
	v_mfma_f32_16x16x32_bf16 v[112:115], v[168:171], v[184:187], v[112:115]
	v_mfma_f32_16x16x32_bf16 v[112:115], v[172:175], v[188:191], v[112:115]
	v_mfma_f32_16x16x32_bf16 v[96:99], v[168:171], v[192:195], v[96:99]
	v_mfma_f32_16x16x32_bf16 v[96:99], v[172:175], v[196:199], v[96:99]
	v_mfma_f32_16x16x32_bf16 v[100:103], v[160:163], v[192:195], v[100:103]
	v_mfma_f32_16x16x32_bf16 v[100:103], v[164:167], v[196:199], v[100:103]
	v_mfma_f32_16x16x32_bf16 v[84:87], v[160:163], v[200:203], v[84:87]
	v_mfma_f32_16x16x32_bf16 v[84:87], v[164:167], v[204:207], v[84:87]
	v_mfma_f32_16x16x32_bf16 v[80:83], v[168:171], v[200:203], v[80:83]
	v_mfma_f32_16x16x32_bf16 v[80:83], v[172:175], v[204:207], v[80:83]
	s_setprio 2
	s_barrier
	v_mfma_f32_16x16x32_bf16 v[64:67], v[168:171], v[208:211], v[64:67]
	v_mfma_f32_16x16x32_bf16 v[64:67], v[172:175], v[212:215], v[64:67]
	v_mfma_f32_16x16x32_bf16 v[68:71], v[160:163], v[208:211], v[68:71]
	v_mfma_f32_16x16x32_bf16 v[68:71], v[164:167], v[212:215], v[68:71]
	s_setprio 2
	s_add_i32 s44, s74, s51
	v_lshl_add_u64 v[176:177], v[176:177], 0, s[22:23]
	s_mov_b32 m0, s44
	ds_read_b128 v[184:187], v181 offset:49152
	ds_read_b128 v[188:191], v181 offset:50176
	ds_read_b128 v[192:195], v181 offset:51200
	ds_read_b128 v[196:199], v181 offset:52224
	ds_read_b128 v[200:203], v181 offset:53248
	ds_read_b128 v[204:207], v181 offset:54272
	ds_read_b128 v[208:211], v181 offset:55296
	ds_read_b128 v[212:215], v181 offset:56320
	global_load_lds_dwordx4 v[176:177], off
	s_add_i32 m0, s44, 0x2000
	s_add_u32 s40, s40, 0x40080
	v_lshl_add_u64 v[176:177], v[216:217], 0, s[22:23]
	s_addc_u32 s41, s41, 0
	s_add_i32 s44, s75, s51
	global_load_lds_dwordx4 v[176:177], off
	s_mov_b32 m0, s44
	v_lshl_add_u64 v[176:177], s[40:41], 0, v[130:131]
	global_load_lds_dwordx4 v[176:177], off
	s_add_i32 m0, s44, 0x2000
	v_lshl_add_u64 v[176:177], s[40:41], 0, v[134:135]
	global_load_lds_dwordx4 v[176:177], off
	s_mov_b32 m0, s64
	v_lshl_add_u64 v[176:177], v[218:219], 0, s[22:23]
	global_load_lds_dwordx4 v[176:177], off
	s_mov_b32 m0, s65
	v_lshl_add_u64 v[176:177], v[220:221], 0, s[22:23]
	global_load_lds_dwordx4 v[176:177], off
	s_waitcnt vmcnt(8) lgkmcnt(0)
	s_barrier
	s_setprio 1
	v_mfma_f32_16x16x32_bf16 v[60:63], v[144:147], v[184:187], v[60:63]
	v_mfma_f32_16x16x32_bf16 v[60:63], v[148:151], v[188:191], v[60:63]
	v_mfma_f32_16x16x32_bf16 v[56:59], v[152:155], v[184:187], v[56:59]
	v_mfma_f32_16x16x32_bf16 v[56:59], v[156:159], v[188:191], v[56:59]
	v_mfma_f32_16x16x32_bf16 v[40:43], v[152:155], v[192:195], v[40:43]
	v_mfma_f32_16x16x32_bf16 v[40:43], v[156:159], v[196:199], v[40:43]
	v_mfma_f32_16x16x32_bf16 v[44:47], v[144:147], v[192:195], v[44:47]
	v_mfma_f32_16x16x32_bf16 v[44:47], v[148:151], v[196:199], v[44:47]
	v_mfma_f32_16x16x32_bf16 v[28:31], v[144:147], v[200:203], v[28:31]
	v_mfma_f32_16x16x32_bf16 v[28:31], v[148:151], v[204:207], v[28:31]
	v_mfma_f32_16x16x32_bf16 v[24:27], v[152:155], v[200:203], v[24:27]
	v_mfma_f32_16x16x32_bf16 v[24:27], v[156:159], v[204:207], v[24:27]
	v_mfma_f32_16x16x32_bf16 v[8:11], v[152:155], v[208:211], v[8:11]
	v_mfma_f32_16x16x32_bf16 v[8:11], v[156:159], v[212:215], v[8:11]
	v_mfma_f32_16x16x32_bf16 v[12:15], v[144:147], v[208:211], v[12:15]
	v_mfma_f32_16x16x32_bf16 v[12:15], v[148:151], v[212:215], v[12:15]
	v_mfma_f32_16x16x32_bf16 v[52:55], v[160:163], v[184:187], v[52:55]
	v_mfma_f32_16x16x32_bf16 v[52:55], v[164:167], v[188:191], v[52:55]
	v_mfma_f32_16x16x32_bf16 v[48:51], v[168:171], v[184:187], v[48:51]
	v_mfma_f32_16x16x32_bf16 v[48:51], v[172:175], v[188:191], v[48:51]
	v_mfma_f32_16x16x32_bf16 v[32:35], v[168:171], v[192:195], v[32:35]
	v_mfma_f32_16x16x32_bf16 v[32:35], v[172:175], v[196:199], v[32:35]
	v_mfma_f32_16x16x32_bf16 v[36:39], v[160:163], v[192:195], v[36:39]
	v_mfma_f32_16x16x32_bf16 v[36:39], v[164:167], v[196:199], v[36:39]
	v_mfma_f32_16x16x32_bf16 v[20:23], v[160:163], v[200:203], v[20:23]
	v_mfma_f32_16x16x32_bf16 v[20:23], v[164:167], v[204:207], v[20:23]
	v_mfma_f32_16x16x32_bf16 v[16:19], v[168:171], v[200:203], v[16:19]
	v_mfma_f32_16x16x32_bf16 v[16:19], v[172:175], v[204:207], v[16:19]
	s_setprio 2
	s_barrier
	v_mfma_f32_16x16x32_bf16 v[0:3], v[168:171], v[208:211], v[0:3]
	v_mfma_f32_16x16x32_bf16 v[0:3], v[172:175], v[212:215], v[0:3]
	v_mfma_f32_16x16x32_bf16 v[4:7], v[160:163], v[208:211], v[4:7]
	v_mfma_f32_16x16x32_bf16 v[4:7], v[164:167], v[212:215], v[4:7]
	s_setprio 0
	s_add_i32 s73, s73, 2
	s_add_u32 s6, s6, 0x100
	s_addc_u32 s7, s7, 0
	s_add_u32 s71, s71, 0x100
	s_addc_u32 s72, s72, 0
	s_cmp_gt_u32 s73, 13
	s_cbranch_scc0 .LBB0_952

.LBB0_1145:
	s_ashr_i32 s23, s22, 31
	s_lshl_b64 s[26:27], s[22:23], 19
	s_add_u32 s26, s45, s26
	s_addc_u32 s27, s46, s27
	s_and_b64 s[28:29], s[4:5], exec
	s_cselect_b32 s23, s27, s39
	s_cselect_b32 s31, s26, s38
	s_ashr_i32 s25, s24, 31
	s_lshl_b64 s[28:29], s[24:25], 19
	s_add_u32 s28, s47, s28
	s_addc_u32 s29, s48, s29
	s_and_b64 s[42:43], s[4:5], exec
	s_cselect_b32 s25, s29, s41
	s_cselect_b32 s37, s28, s40
	s_add_u32 s38, s38, 0x40080
	s_addc_u32 s39, s39, 0
	s_add_u32 s64, s40, 0x100
	s_addc_u32 s65, s41, 0
	s_mov_b32 s66, -2
	ds_read_b128 v[120:123], v233
	ds_read_b128 v[132:135], v233 offset:1024
	ds_read_b128 v[136:139], v233 offset:2048
	ds_read_b128 v[140:143], v233 offset:3072
	ds_read_b128 v[144:147], v234
	ds_read_b128 v[148:151], v234 offset:1024
	ds_read_b128 v[152:155], v234 offset:2048
	ds_read_b128 v[156:159], v234 offset:3072
	s_add_u32 s40, s38, 0xfffc0080
	s_addc_u32 s41, s39, -1
	s_cmp_eq_u32 s66, 12
	s_cselect_b32 s43, s23, s41
	s_cselect_b32 s42, s31, s40
	s_cselect_b32 s41, s25, s65
	s_cselect_b32 s40, s37, s64
	v_lshl_add_u64 v[208:209], s[38:39], 0, v[192:193]
	s_add_i32 m0, s50, 0xc000
	ds_read_b128 v[160:163], v235
	ds_read_b128 v[164:167], v235 offset:1024
	ds_read_b128 v[168:171], v235 offset:2048
	ds_read_b128 v[172:175], v235 offset:3072
	ds_read_b128 v[176:179], v235 offset:4096
	ds_read_b128 v[180:183], v235 offset:5120
	ds_read_b128 v[200:203], v235 offset:6144
	ds_read_b128 v[204:207], v235 offset:7168
	global_load_lds_dwordx4 v[208:209], off
	s_add_i32 m0, s50, 0xe000
	v_lshl_add_u64 v[208:209], s[38:39], 0, v[194:195]
	global_load_lds_dwordx4 v[208:209], off
	s_waitcnt vmcnt(8) lgkmcnt(0)
	s_barrier
	s_setprio 1
	v_mfma_f32_16x16x32_bf16 v[128:131], v[120:123], v[160:163], 0
	v_mfma_f32_16x16x32_bf16 v[128:131], v[132:135], v[164:167], v[128:131]
	v_mfma_f32_16x16x32_bf16 v[124:127], v[136:139], v[160:163], 0
	v_mfma_f32_16x16x32_bf16 v[124:127], v[140:143], v[164:167], v[124:127]
	v_mfma_f32_16x16x32_bf16 v[104:107], v[136:139], v[168:171], 0
	v_mfma_f32_16x16x32_bf16 v[104:107], v[140:143], v[172:175], v[104:107]
	v_mfma_f32_16x16x32_bf16 v[108:111], v[120:123], v[168:171], 0
	v_mfma_f32_16x16x32_bf16 v[108:111], v[132:135], v[172:175], v[108:111]
	v_mfma_f32_16x16x32_bf16 v[92:95], v[120:123], v[176:179], 0
	v_mfma_f32_16x16x32_bf16 v[92:95], v[132:135], v[180:183], v[92:95]
	v_mfma_f32_16x16x32_bf16 v[88:91], v[136:139], v[176:179], 0
	v_mfma_f32_16x16x32_bf16 v[88:91], v[140:143], v[180:183], v[88:91]
	v_mfma_f32_16x16x32_bf16 v[72:75], v[136:139], v[200:203], 0
	v_mfma_f32_16x16x32_bf16 v[72:75], v[140:143], v[204:207], v[72:75]
	v_mfma_f32_16x16x32_bf16 v[76:79], v[120:123], v[200:203], 0
	v_mfma_f32_16x16x32_bf16 v[76:79], v[132:135], v[204:207], v[76:79]
	v_mfma_f32_16x16x32_bf16 v[116:119], v[144:147], v[160:163], 0
	v_mfma_f32_16x16x32_bf16 v[116:119], v[148:151], v[164:167], v[116:119]
	v_mfma_f32_16x16x32_bf16 v[112:115], v[152:155], v[160:163], 0
	v_mfma_f32_16x16x32_bf16 v[112:115], v[156:159], v[164:167], v[112:115]
	v_mfma_f32_16x16x32_bf16 v[96:99], v[152:155], v[168:171], 0
	v_mfma_f32_16x16x32_bf16 v[96:99], v[156:159], v[172:175], v[96:99]
	v_mfma_f32_16x16x32_bf16 v[100:103], v[144:147], v[168:171], 0
	v_mfma_f32_16x16x32_bf16 v[100:103], v[148:151], v[172:175], v[100:103]
	v_mfma_f32_16x16x32_bf16 v[84:87], v[144:147], v[176:179], 0
	v_mfma_f32_16x16x32_bf16 v[84:87], v[148:151], v[180:183], v[84:87]
	v_mfma_f32_16x16x32_bf16 v[80:83], v[152:155], v[176:179], 0
	v_mfma_f32_16x16x32_bf16 v[80:83], v[156:159], v[180:183], v[80:83]
	s_setprio 2
	s_barrier
	v_mfma_f32_16x16x32_bf16 v[64:67], v[152:155], v[200:203], 0
	v_mfma_f32_16x16x32_bf16 v[64:67], v[156:159], v[204:207], v[64:67]
	v_mfma_f32_16x16x32_bf16 v[68:71], v[144:147], v[200:203], 0
	v_mfma_f32_16x16x32_bf16 v[68:71], v[148:151], v[204:207], v[68:71]
	s_setprio 2
	s_add_i32 s67, s62, s49
	v_lshl_add_u64 v[208:209], s[40:41], 0, v[186:187]
	s_mov_b32 m0, s67
	ds_read_b128 v[160:163], v235 offset:16384
	ds_read_b128 v[164:167], v235 offset:17408
	ds_read_b128 v[168:171], v235 offset:18432
	ds_read_b128 v[172:175], v235 offset:19456
	ds_read_b128 v[176:179], v235 offset:20480
	ds_read_b128 v[180:183], v235 offset:21504
	ds_read_b128 v[200:203], v235 offset:22528
	ds_read_b128 v[204:207], v235 offset:23552
	global_load_lds_dwordx4 v[208:209], off
	s_add_i32 m0, s67, 0x2000
	s_add_u32 s68, s40, 0x40000
	v_lshl_add_u64 v[210:211], s[40:41], 0, v[190:191]
	s_addc_u32 s69, s41, 0
	s_add_i32 s67, s63, s49
	global_load_lds_dwordx4 v[210:211], off
	v_lshl_add_u64 v[212:213], s[68:69], 0, v[186:187]
	s_mov_b32 m0, s67
	v_lshl_add_u64 v[214:215], s[42:43], 0, v[188:189]
	global_load_lds_dwordx4 v[212:213], off
	s_add_i32 m0, s67, 0x2000
	v_lshl_add_u64 v[212:213], s[68:69], 0, v[190:191]
	global_load_lds_dwordx4 v[212:213], off
	s_mov_b32 m0, s50
	v_lshl_add_u64 v[212:213], s[42:43], 0, v[184:185]
	global_load_lds_dwordx4 v[212:213], off
	s_mov_b32 m0, s51
	s_nop 0
	global_load_lds_dwordx4 v[214:215], off
	s_waitcnt vmcnt(8) lgkmcnt(0)
	s_barrier
	s_setprio 1
	v_mfma_f32_16x16x32_bf16 v[60:63], v[120:123], v[160:163], 0
	v_mfma_f32_16x16x32_bf16 v[60:63], v[132:135], v[164:167], v[60:63]
	v_mfma_f32_16x16x32_bf16 v[56:59], v[136:139], v[160:163], 0
	v_mfma_f32_16x16x32_bf16 v[56:59], v[140:143], v[164:167], v[56:59]
	v_mfma_f32_16x16x32_bf16 v[40:43], v[136:139], v[168:171], 0
	v_mfma_f32_16x16x32_bf16 v[40:43], v[140:143], v[172:175], v[40:43]
	v_mfma_f32_16x16x32_bf16 v[44:47], v[120:123], v[168:171], 0
	v_mfma_f32_16x16x32_bf16 v[44:47], v[132:135], v[172:175], v[44:47]
	v_mfma_f32_16x16x32_bf16 v[28:31], v[120:123], v[176:179], 0
	v_mfma_f32_16x16x32_bf16 v[28:31], v[132:135], v[180:183], v[28:31]
	v_mfma_f32_16x16x32_bf16 v[24:27], v[136:139], v[176:179], 0
	v_mfma_f32_16x16x32_bf16 v[24:27], v[140:143], v[180:183], v[24:27]
	v_mfma_f32_16x16x32_bf16 v[8:11], v[136:139], v[200:203], 0
	v_mfma_f32_16x16x32_bf16 v[8:11], v[140:143], v[204:207], v[8:11]
	v_mfma_f32_16x16x32_bf16 v[12:15], v[120:123], v[200:203], 0
	v_mfma_f32_16x16x32_bf16 v[12:15], v[132:135], v[204:207], v[12:15]
	v_mfma_f32_16x16x32_bf16 v[52:55], v[144:147], v[160:163], 0
	v_mfma_f32_16x16x32_bf16 v[52:55], v[148:151], v[164:167], v[52:55]
	v_mfma_f32_16x16x32_bf16 v[48:51], v[152:155], v[160:163], 0
	v_mfma_f32_16x16x32_bf16 v[48:51], v[156:159], v[164:167], v[48:51]
	v_mfma_f32_16x16x32_bf16 v[32:35], v[152:155], v[168:171], 0
	v_mfma_f32_16x16x32_bf16 v[32:35], v[156:159], v[172:175], v[32:35]
	v_mfma_f32_16x16x32_bf16 v[36:39], v[144:147], v[168:171], 0
	v_mfma_f32_16x16x32_bf16 v[36:39], v[148:151], v[172:175], v[36:39]
	v_mfma_f32_16x16x32_bf16 v[20:23], v[144:147], v[176:179], 0
	v_mfma_f32_16x16x32_bf16 v[20:23], v[148:151], v[180:183], v[20:23]
	v_mfma_f32_16x16x32_bf16 v[16:19], v[152:155], v[176:179], 0
	v_mfma_f32_16x16x32_bf16 v[16:19], v[156:159], v[180:183], v[16:19]
	s_setprio 2
	s_barrier
	v_mfma_f32_16x16x32_bf16 v[0:3], v[152:155], v[200:203], 0
	v_mfma_f32_16x16x32_bf16 v[0:3], v[156:159], v[204:207], v[0:3]
	v_mfma_f32_16x16x32_bf16 v[4:7], v[144:147], v[200:203], 0
	v_mfma_f32_16x16x32_bf16 v[4:7], v[148:151], v[204:207], v[4:7]
	s_setprio 0
	s_add_i32 s67, 0, 0x18000
	s_add_i32 s68, 0, 0x1c000
	v_add_u32_e32 v140, s67, v232
	v_add_u32_e32 v156, s68, v232
	ds_read_b128 v[120:123], v140
	ds_read_b128 v[132:135], v140 offset:1024
	ds_read_b128 v[136:139], v140 offset:2048
	ds_read_b128 v[140:143], v140 offset:3072
	ds_read_b128 v[144:147], v156
	ds_read_b128 v[148:151], v156 offset:1024
	ds_read_b128 v[152:155], v156 offset:2048
	ds_read_b128 v[156:159], v156 offset:3072
	s_add_u32 s42, s42, 0x40000
	s_addc_u32 s43, s43, 0
	s_mov_b32 m0, s54
	v_lshl_add_u64 v[216:217], s[42:43], 0, v[184:185]
	ds_read_b128 v[160:163], v235 offset:32768
	ds_read_b128 v[164:167], v235 offset:33792
	ds_read_b128 v[168:171], v235 offset:34816
	ds_read_b128 v[172:175], v235 offset:35840
	ds_read_b128 v[176:179], v235 offset:36864
	ds_read_b128 v[180:183], v235 offset:37888
	ds_read_b128 v[200:203], v235 offset:38912
	ds_read_b128 v[204:207], v235 offset:39936
	global_load_lds_dwordx4 v[216:217], off
	s_mov_b32 m0, s55
	v_lshl_add_u64 v[216:217], s[42:43], 0, v[188:189]
	global_load_lds_dwordx4 v[216:217], off
	s_waitcnt vmcnt(8) lgkmcnt(0)
	s_barrier
	s_setprio 1
	v_mfma_f32_16x16x32_bf16 v[128:131], v[120:123], v[160:163], v[128:131]
	v_mfma_f32_16x16x32_bf16 v[128:131], v[132:135], v[164:167], v[128:131]
	v_mfma_f32_16x16x32_bf16 v[124:127], v[136:139], v[160:163], v[124:127]
	v_mfma_f32_16x16x32_bf16 v[124:127], v[140:143], v[164:167], v[124:127]
	v_mfma_f32_16x16x32_bf16 v[104:107], v[136:139], v[168:171], v[104:107]
	v_mfma_f32_16x16x32_bf16 v[104:107], v[140:143], v[172:175], v[104:107]
	v_mfma_f32_16x16x32_bf16 v[108:111], v[120:123], v[168:171], v[108:111]
	v_mfma_f32_16x16x32_bf16 v[108:111], v[132:135], v[172:175], v[108:111]
	v_mfma_f32_16x16x32_bf16 v[92:95], v[120:123], v[176:179], v[92:95]
	v_mfma_f32_16x16x32_bf16 v[92:95], v[132:135], v[180:183], v[92:95]
	v_mfma_f32_16x16x32_bf16 v[88:91], v[136:139], v[176:179], v[88:91]
	v_mfma_f32_16x16x32_bf16 v[88:91], v[140:143], v[180:183], v[88:91]
	v_mfma_f32_16x16x32_bf16 v[72:75], v[136:139], v[200:203], v[72:75]
	v_mfma_f32_16x16x32_bf16 v[72:75], v[140:143], v[204:207], v[72:75]
	v_mfma_f32_16x16x32_bf16 v[76:79], v[120:123], v[200:203], v[76:79]
	v_mfma_f32_16x16x32_bf16 v[76:79], v[132:135], v[204:207], v[76:79]
	v_mfma_f32_16x16x32_bf16 v[116:119], v[144:147], v[160:163], v[116:119]
	v_mfma_f32_16x16x32_bf16 v[116:119], v[148:151], v[164:167], v[116:119]
	v_mfma_f32_16x16x32_bf16 v[112:115], v[152:155], v[160:163], v[112:115]
	v_mfma_f32_16x16x32_bf16 v[112:115], v[156:159], v[164:167], v[112:115]
	v_mfma_f32_16x16x32_bf16 v[96:99], v[152:155], v[168:171], v[96:99]
	v_mfma_f32_16x16x32_bf16 v[96:99], v[156:159], v[172:175], v[96:99]
	v_mfma_f32_16x16x32_bf16 v[100:103], v[144:147], v[168:171], v[100:103]
	v_mfma_f32_16x16x32_bf16 v[100:103], v[148:151], v[172:175], v[100:103]
	v_mfma_f32_16x16x32_bf16 v[84:87], v[144:147], v[176:179], v[84:87]
	v_mfma_f32_16x16x32_bf16 v[84:87], v[148:151], v[180:183], v[84:87]
	v_mfma_f32_16x16x32_bf16 v[80:83], v[152:155], v[176:179], v[80:83]
	v_mfma_f32_16x16x32_bf16 v[80:83], v[156:159], v[180:183], v[80:83]
	s_setprio 2
	s_barrier
	v_mfma_f32_16x16x32_bf16 v[64:67], v[152:155], v[200:203], v[64:67]
	v_mfma_f32_16x16x32_bf16 v[64:67], v[156:159], v[204:207], v[64:67]
	v_mfma_f32_16x16x32_bf16 v[68:71], v[144:147], v[200:203], v[68:71]
	v_mfma_f32_16x16x32_bf16 v[68:71], v[148:151], v[204:207], v[68:71]
	s_setprio 2
	s_add_i32 s42, s67, s49
	v_lshl_add_u64 v[208:209], v[208:209], 0, s[18:19]
	s_mov_b32 m0, s42
	ds_read_b128 v[160:163], v235 offset:49152
	ds_read_b128 v[164:167], v235 offset:50176
	ds_read_b128 v[168:171], v235 offset:51200
	ds_read_b128 v[172:175], v235 offset:52224
	ds_read_b128 v[176:179], v235 offset:53248
	ds_read_b128 v[180:183], v235 offset:54272
	ds_read_b128 v[200:203], v235 offset:55296
	ds_read_b128 v[204:207], v235 offset:56320
	global_load_lds_dwordx4 v[208:209], off
	s_add_i32 m0, s42, 0x2000
	s_add_u32 s40, s40, 0x40080
	v_lshl_add_u64 v[208:209], v[210:211], 0, s[18:19]
	s_addc_u32 s41, s41, 0
	s_add_i32 s42, s68, s49
	global_load_lds_dwordx4 v[208:209], off
	s_mov_b32 m0, s42
	v_lshl_add_u64 v[208:209], s[40:41], 0, v[186:187]
	global_load_lds_dwordx4 v[208:209], off
	s_add_i32 m0, s42, 0x2000
	v_lshl_add_u64 v[208:209], s[40:41], 0, v[190:191]
	global_load_lds_dwordx4 v[208:209], off
	s_mov_b32 m0, s57
	v_lshl_add_u64 v[208:209], v[212:213], 0, s[18:19]
	global_load_lds_dwordx4 v[208:209], off
	s_mov_b32 m0, s58
	v_lshl_add_u64 v[208:209], v[214:215], 0, s[18:19]
	global_load_lds_dwordx4 v[208:209], off
	s_waitcnt vmcnt(8) lgkmcnt(0)
	s_barrier
	s_setprio 1
	v_mfma_f32_16x16x32_bf16 v[60:63], v[120:123], v[160:163], v[60:63]
	v_mfma_f32_16x16x32_bf16 v[60:63], v[132:135], v[164:167], v[60:63]
	v_mfma_f32_16x16x32_bf16 v[56:59], v[136:139], v[160:163], v[56:59]
	v_mfma_f32_16x16x32_bf16 v[56:59], v[140:143], v[164:167], v[56:59]
	v_mfma_f32_16x16x32_bf16 v[40:43], v[136:139], v[168:171], v[40:43]
	v_mfma_f32_16x16x32_bf16 v[40:43], v[140:143], v[172:175], v[40:43]
	v_mfma_f32_16x16x32_bf16 v[44:47], v[120:123], v[168:171], v[44:47]
	v_mfma_f32_16x16x32_bf16 v[44:47], v[132:135], v[172:175], v[44:47]
	v_mfma_f32_16x16x32_bf16 v[28:31], v[120:123], v[176:179], v[28:31]
	v_mfma_f32_16x16x32_bf16 v[28:31], v[132:135], v[180:183], v[28:31]
	v_mfma_f32_16x16x32_bf16 v[24:27], v[136:139], v[176:179], v[24:27]
	v_mfma_f32_16x16x32_bf16 v[24:27], v[140:143], v[180:183], v[24:27]
	v_mfma_f32_16x16x32_bf16 v[8:11], v[136:139], v[200:203], v[8:11]
	v_mfma_f32_16x16x32_bf16 v[8:11], v[140:143], v[204:207], v[8:11]
	v_mfma_f32_16x16x32_bf16 v[12:15], v[120:123], v[200:203], v[12:15]
	v_mfma_f32_16x16x32_bf16 v[12:15], v[132:135], v[204:207], v[12:15]
	v_mfma_f32_16x16x32_bf16 v[52:55], v[144:147], v[160:163], v[52:55]
	v_mfma_f32_16x16x32_bf16 v[52:55], v[148:151], v[164:167], v[52:55]
	v_mfma_f32_16x16x32_bf16 v[48:51], v[152:155], v[160:163], v[48:51]
	v_mfma_f32_16x16x32_bf16 v[48:51], v[156:159], v[164:167], v[48:51]
	v_mfma_f32_16x16x32_bf16 v[32:35], v[152:155], v[168:171], v[32:35]
	v_mfma_f32_16x16x32_bf16 v[32:35], v[156:159], v[172:175], v[32:35]
	v_mfma_f32_16x16x32_bf16 v[36:39], v[144:147], v[168:171], v[36:39]
	v_mfma_f32_16x16x32_bf16 v[36:39], v[148:151], v[172:175], v[36:39]
	v_mfma_f32_16x16x32_bf16 v[20:23], v[144:147], v[176:179], v[20:23]
	v_mfma_f32_16x16x32_bf16 v[20:23], v[148:151], v[180:183], v[20:23]
	v_mfma_f32_16x16x32_bf16 v[16:19], v[152:155], v[176:179], v[16:19]
	v_mfma_f32_16x16x32_bf16 v[16:19], v[156:159], v[180:183], v[16:19]
	s_setprio 2
	s_barrier
	v_mfma_f32_16x16x32_bf16 v[0:3], v[152:155], v[200:203], v[0:3]
	v_mfma_f32_16x16x32_bf16 v[0:3], v[156:159], v[204:207], v[0:3]
	v_mfma_f32_16x16x32_bf16 v[4:7], v[144:147], v[200:203], v[4:7]
	v_mfma_f32_16x16x32_bf16 v[4:7], v[148:151], v[204:207], v[4:7]
	s_setprio 0
	s_add_i32 s66, s66, 2
	s_add_u32 s38, s38, 0x100
	s_addc_u32 s39, s39, 0
	s_add_u32 s64, s64, 0x100
	s_addc_u32 s65, s65, 0
	s_cmp_gt_u32 s66, 13
.LBB0_1146:
	ds_read_b128 v[120:123], v233
	ds_read_b128 v[132:135], v233 offset:1024
	ds_read_b128 v[136:139], v233 offset:2048
	ds_read_b128 v[140:143], v233 offset:3072
	ds_read_b128 v[144:147], v234
	ds_read_b128 v[148:151], v234 offset:1024
	ds_read_b128 v[152:155], v234 offset:2048
	ds_read_b128 v[156:159], v234 offset:3072
	s_add_u32 s40, s38, 0xfffc0080
	s_addc_u32 s41, s39, -1
	s_cmp_eq_u32 s66, 12
	s_cselect_b32 s43, s23, s41
	s_cselect_b32 s42, s31, s40
	s_cselect_b32 s41, s25, s65
	s_cselect_b32 s40, s37, s64
	v_lshl_add_u64 v[208:209], s[38:39], 0, v[192:193]
	s_add_i32 m0, s50, 0xc000
	ds_read_b128 v[160:163], v235
	ds_read_b128 v[164:167], v235 offset:1024
	ds_read_b128 v[168:171], v235 offset:2048
	ds_read_b128 v[172:175], v235 offset:3072
	ds_read_b128 v[176:179], v235 offset:4096
	ds_read_b128 v[180:183], v235 offset:5120
	ds_read_b128 v[200:203], v235 offset:6144
	ds_read_b128 v[204:207], v235 offset:7168
	global_load_lds_dwordx4 v[208:209], off
	s_add_i32 m0, s50, 0xe000
	v_lshl_add_u64 v[208:209], s[38:39], 0, v[194:195]
	global_load_lds_dwordx4 v[208:209], off
	s_waitcnt vmcnt(8) lgkmcnt(0)
	s_barrier
	s_setprio 1
	v_mfma_f32_16x16x32_bf16 v[128:131], v[120:123], v[160:163], v[128:131]
	v_mfma_f32_16x16x32_bf16 v[128:131], v[132:135], v[164:167], v[128:131]
	v_mfma_f32_16x16x32_bf16 v[124:127], v[136:139], v[160:163], v[124:127]
	v_mfma_f32_16x16x32_bf16 v[124:127], v[140:143], v[164:167], v[124:127]
	v_mfma_f32_16x16x32_bf16 v[104:107], v[136:139], v[168:171], v[104:107]
	v_mfma_f32_16x16x32_bf16 v[104:107], v[140:143], v[172:175], v[104:107]
	v_mfma_f32_16x16x32_bf16 v[108:111], v[120:123], v[168:171], v[108:111]
	v_mfma_f32_16x16x32_bf16 v[108:111], v[132:135], v[172:175], v[108:111]
	v_mfma_f32_16x16x32_bf16 v[92:95], v[120:123], v[176:179], v[92:95]
	v_mfma_f32_16x16x32_bf16 v[92:95], v[132:135], v[180:183], v[92:95]
	v_mfma_f32_16x16x32_bf16 v[88:91], v[136:139], v[176:179], v[88:91]
	v_mfma_f32_16x16x32_bf16 v[88:91], v[140:143], v[180:183], v[88:91]
	v_mfma_f32_16x16x32_bf16 v[72:75], v[136:139], v[200:203], v[72:75]
	v_mfma_f32_16x16x32_bf16 v[72:75], v[140:143], v[204:207], v[72:75]
	v_mfma_f32_16x16x32_bf16 v[76:79], v[120:123], v[200:203], v[76:79]
	v_mfma_f32_16x16x32_bf16 v[76:79], v[132:135], v[204:207], v[76:79]
	v_mfma_f32_16x16x32_bf16 v[116:119], v[144:147], v[160:163], v[116:119]
	v_mfma_f32_16x16x32_bf16 v[116:119], v[148:151], v[164:167], v[116:119]
	v_mfma_f32_16x16x32_bf16 v[112:115], v[152:155], v[160:163], v[112:115]
	v_mfma_f32_16x16x32_bf16 v[112:115], v[156:159], v[164:167], v[112:115]
	v_mfma_f32_16x16x32_bf16 v[96:99], v[152:155], v[168:171], v[96:99]
	v_mfma_f32_16x16x32_bf16 v[96:99], v[156:159], v[172:175], v[96:99]
	v_mfma_f32_16x16x32_bf16 v[100:103], v[144:147], v[168:171], v[100:103]
	v_mfma_f32_16x16x32_bf16 v[100:103], v[148:151], v[172:175], v[100:103]
	v_mfma_f32_16x16x32_bf16 v[84:87], v[144:147], v[176:179], v[84:87]
	v_mfma_f32_16x16x32_bf16 v[84:87], v[148:151], v[180:183], v[84:87]
	v_mfma_f32_16x16x32_bf16 v[80:83], v[152:155], v[176:179], v[80:83]
	v_mfma_f32_16x16x32_bf16 v[80:83], v[156:159], v[180:183], v[80:83]
	s_setprio 2
	s_barrier
	v_mfma_f32_16x16x32_bf16 v[64:67], v[152:155], v[200:203], v[64:67]
	v_mfma_f32_16x16x32_bf16 v[64:67], v[156:159], v[204:207], v[64:67]
	v_mfma_f32_16x16x32_bf16 v[68:71], v[144:147], v[200:203], v[68:71]
	v_mfma_f32_16x16x32_bf16 v[68:71], v[148:151], v[204:207], v[68:71]
	s_setprio 2
	s_add_i32 s67, s62, s49
	v_lshl_add_u64 v[208:209], s[40:41], 0, v[186:187]
	s_mov_b32 m0, s67
	ds_read_b128 v[160:163], v235 offset:16384
	ds_read_b128 v[164:167], v235 offset:17408
	ds_read_b128 v[168:171], v235 offset:18432
	ds_read_b128 v[172:175], v235 offset:19456
	ds_read_b128 v[176:179], v235 offset:20480
	ds_read_b128 v[180:183], v235 offset:21504
	ds_read_b128 v[200:203], v235 offset:22528
	ds_read_b128 v[204:207], v235 offset:23552
	global_load_lds_dwordx4 v[208:209], off
	s_add_i32 m0, s67, 0x2000
	s_add_u32 s68, s40, 0x40000
	v_lshl_add_u64 v[210:211], s[40:41], 0, v[190:191]
	s_addc_u32 s69, s41, 0
	s_add_i32 s67, s63, s49
	global_load_lds_dwordx4 v[210:211], off
	v_lshl_add_u64 v[212:213], s[68:69], 0, v[186:187]
	s_mov_b32 m0, s67
	v_lshl_add_u64 v[214:215], s[42:43], 0, v[188:189]
	global_load_lds_dwordx4 v[212:213], off
	s_add_i32 m0, s67, 0x2000
	v_lshl_add_u64 v[212:213], s[68:69], 0, v[190:191]
	global_load_lds_dwordx4 v[212:213], off
	s_mov_b32 m0, s50
	v_lshl_add_u64 v[212:213], s[42:43], 0, v[184:185]
	global_load_lds_dwordx4 v[212:213], off
	s_mov_b32 m0, s51
	s_nop 0
	global_load_lds_dwordx4 v[214:215], off
	s_waitcnt vmcnt(8) lgkmcnt(0)
	s_barrier
	s_setprio 1
	v_mfma_f32_16x16x32_bf16 v[60:63], v[120:123], v[160:163], v[60:63]
	v_mfma_f32_16x16x32_bf16 v[60:63], v[132:135], v[164:167], v[60:63]
	v_mfma_f32_16x16x32_bf16 v[56:59], v[136:139], v[160:163], v[56:59]
	v_mfma_f32_16x16x32_bf16 v[56:59], v[140:143], v[164:167], v[56:59]
	v_mfma_f32_16x16x32_bf16 v[40:43], v[136:139], v[168:171], v[40:43]
	v_mfma_f32_16x16x32_bf16 v[40:43], v[140:143], v[172:175], v[40:43]
	v_mfma_f32_16x16x32_bf16 v[44:47], v[120:123], v[168:171], v[44:47]
	v_mfma_f32_16x16x32_bf16 v[44:47], v[132:135], v[172:175], v[44:47]
	v_mfma_f32_16x16x32_bf16 v[28:31], v[120:123], v[176:179], v[28:31]
	v_mfma_f32_16x16x32_bf16 v[28:31], v[132:135], v[180:183], v[28:31]
	v_mfma_f32_16x16x32_bf16 v[24:27], v[136:139], v[176:179], v[24:27]
	v_mfma_f32_16x16x32_bf16 v[24:27], v[140:143], v[180:183], v[24:27]
	v_mfma_f32_16x16x32_bf16 v[8:11], v[136:139], v[200:203], v[8:11]
	v_mfma_f32_16x16x32_bf16 v[8:11], v[140:143], v[204:207], v[8:11]
	v_mfma_f32_16x16x32_bf16 v[12:15], v[120:123], v[200:203], v[12:15]
	v_mfma_f32_16x16x32_bf16 v[12:15], v[132:135], v[204:207], v[12:15]
	v_mfma_f32_16x16x32_bf16 v[52:55], v[144:147], v[160:163], v[52:55]
	v_mfma_f32_16x16x32_bf16 v[52:55], v[148:151], v[164:167], v[52:55]
	v_mfma_f32_16x16x32_bf16 v[48:51], v[152:155], v[160:163], v[48:51]
	v_mfma_f32_16x16x32_bf16 v[48:51], v[156:159], v[164:167], v[48:51]
	v_mfma_f32_16x16x32_bf16 v[32:35], v[152:155], v[168:171], v[32:35]
	v_mfma_f32_16x16x32_bf16 v[32:35], v[156:159], v[172:175], v[32:35]
	v_mfma_f32_16x16x32_bf16 v[36:39], v[144:147], v[168:171], v[36:39]
	v_mfma_f32_16x16x32_bf16 v[36:39], v[148:151], v[172:175], v[36:39]
	v_mfma_f32_16x16x32_bf16 v[20:23], v[144:147], v[176:179], v[20:23]
	v_mfma_f32_16x16x32_bf16 v[20:23], v[148:151], v[180:183], v[20:23]
	v_mfma_f32_16x16x32_bf16 v[16:19], v[152:155], v[176:179], v[16:19]
	v_mfma_f32_16x16x32_bf16 v[16:19], v[156:159], v[180:183], v[16:19]
	s_setprio 2
	s_barrier
	v_mfma_f32_16x16x32_bf16 v[0:3], v[152:155], v[200:203], v[0:3]
	v_mfma_f32_16x16x32_bf16 v[0:3], v[156:159], v[204:207], v[0:3]
	v_mfma_f32_16x16x32_bf16 v[4:7], v[144:147], v[200:203], v[4:7]
	v_mfma_f32_16x16x32_bf16 v[4:7], v[148:151], v[204:207], v[4:7]
	s_setprio 0
	s_add_i32 s67, 0, 0x18000
	s_add_i32 s68, 0, 0x1c000
	v_add_u32_e32 v140, s67, v232
	v_add_u32_e32 v156, s68, v232
	ds_read_b128 v[120:123], v140
	ds_read_b128 v[132:135], v140 offset:1024
	ds_read_b128 v[136:139], v140 offset:2048
	ds_read_b128 v[140:143], v140 offset:3072
	ds_read_b128 v[144:147], v156
	ds_read_b128 v[148:151], v156 offset:1024
	ds_read_b128 v[152:155], v156 offset:2048
	ds_read_b128 v[156:159], v156 offset:3072
	s_add_u32 s42, s42, 0x40000
	s_addc_u32 s43, s43, 0
	s_mov_b32 m0, s54
	v_lshl_add_u64 v[216:217], s[42:43], 0, v[184:185]
	ds_read_b128 v[160:163], v235 offset:32768
	ds_read_b128 v[164:167], v235 offset:33792
	ds_read_b128 v[168:171], v235 offset:34816
	ds_read_b128 v[172:175], v235 offset:35840
	ds_read_b128 v[176:179], v235 offset:36864
	ds_read_b128 v[180:183], v235 offset:37888
	ds_read_b128 v[200:203], v235 offset:38912
	ds_read_b128 v[204:207], v235 offset:39936
	global_load_lds_dwordx4 v[216:217], off
	s_mov_b32 m0, s55
	v_lshl_add_u64 v[216:217], s[42:43], 0, v[188:189]
	global_load_lds_dwordx4 v[216:217], off
	s_waitcnt vmcnt(8) lgkmcnt(0)
	s_barrier
	s_setprio 1
	v_mfma_f32_16x16x32_bf16 v[128:131], v[120:123], v[160:163], v[128:131]
	v_mfma_f32_16x16x32_bf16 v[128:131], v[132:135], v[164:167], v[128:131]
	v_mfma_f32_16x16x32_bf16 v[124:127], v[136:139], v[160:163], v[124:127]
	v_mfma_f32_16x16x32_bf16 v[124:127], v[140:143], v[164:167], v[124:127]
	v_mfma_f32_16x16x32_bf16 v[104:107], v[136:139], v[168:171], v[104:107]
	v_mfma_f32_16x16x32_bf16 v[104:107], v[140:143], v[172:175], v[104:107]
	v_mfma_f32_16x16x32_bf16 v[108:111], v[120:123], v[168:171], v[108:111]
	v_mfma_f32_16x16x32_bf16 v[108:111], v[132:135], v[172:175], v[108:111]
	v_mfma_f32_16x16x32_bf16 v[92:95], v[120:123], v[176:179], v[92:95]
	v_mfma_f32_16x16x32_bf16 v[92:95], v[132:135], v[180:183], v[92:95]
	v_mfma_f32_16x16x32_bf16 v[88:91], v[136:139], v[176:179], v[88:91]
	v_mfma_f32_16x16x32_bf16 v[88:91], v[140:143], v[180:183], v[88:91]
	v_mfma_f32_16x16x32_bf16 v[72:75], v[136:139], v[200:203], v[72:75]
	v_mfma_f32_16x16x32_bf16 v[72:75], v[140:143], v[204:207], v[72:75]
	v_mfma_f32_16x16x32_bf16 v[76:79], v[120:123], v[200:203], v[76:79]
	v_mfma_f32_16x16x32_bf16 v[76:79], v[132:135], v[204:207], v[76:79]
	v_mfma_f32_16x16x32_bf16 v[116:119], v[144:147], v[160:163], v[116:119]
	v_mfma_f32_16x16x32_bf16 v[116:119], v[148:151], v[164:167], v[116:119]
	v_mfma_f32_16x16x32_bf16 v[112:115], v[152:155], v[160:163], v[112:115]
	v_mfma_f32_16x16x32_bf16 v[112:115], v[156:159], v[164:167], v[112:115]
	v_mfma_f32_16x16x32_bf16 v[96:99], v[152:155], v[168:171], v[96:99]
	v_mfma_f32_16x16x32_bf16 v[96:99], v[156:159], v[172:175], v[96:99]
	v_mfma_f32_16x16x32_bf16 v[100:103], v[144:147], v[168:171], v[100:103]
	v_mfma_f32_16x16x32_bf16 v[100:103], v[148:151], v[172:175], v[100:103]
	v_mfma_f32_16x16x32_bf16 v[84:87], v[144:147], v[176:179], v[84:87]
	v_mfma_f32_16x16x32_bf16 v[84:87], v[148:151], v[180:183], v[84:87]
	v_mfma_f32_16x16x32_bf16 v[80:83], v[152:155], v[176:179], v[80:83]
	v_mfma_f32_16x16x32_bf16 v[80:83], v[156:159], v[180:183], v[80:83]
	s_setprio 2
	s_barrier
	v_mfma_f32_16x16x32_bf16 v[64:67], v[152:155], v[200:203], v[64:67]
	v_mfma_f32_16x16x32_bf16 v[64:67], v[156:159], v[204:207], v[64:67]
	v_mfma_f32_16x16x32_bf16 v[68:71], v[144:147], v[200:203], v[68:71]
	v_mfma_f32_16x16x32_bf16 v[68:71], v[148:151], v[204:207], v[68:71]
	s_setprio 2
	s_add_i32 s42, s67, s49
	v_lshl_add_u64 v[208:209], v[208:209], 0, s[18:19]
	s_mov_b32 m0, s42
	ds_read_b128 v[160:163], v235 offset:49152
	ds_read_b128 v[164:167], v235 offset:50176
	ds_read_b128 v[168:171], v235 offset:51200
	ds_read_b128 v[172:175], v235 offset:52224
	ds_read_b128 v[176:179], v235 offset:53248
	ds_read_b128 v[180:183], v235 offset:54272
	ds_read_b128 v[200:203], v235 offset:55296
	ds_read_b128 v[204:207], v235 offset:56320
	global_load_lds_dwordx4 v[208:209], off
	s_add_i32 m0, s42, 0x2000
	s_add_u32 s40, s40, 0x40080
	v_lshl_add_u64 v[208:209], v[210:211], 0, s[18:19]
	s_addc_u32 s41, s41, 0
	s_add_i32 s42, s68, s49
	global_load_lds_dwordx4 v[208:209], off
	s_mov_b32 m0, s42
	v_lshl_add_u64 v[208:209], s[40:41], 0, v[186:187]
	global_load_lds_dwordx4 v[208:209], off
	s_add_i32 m0, s42, 0x2000
	v_lshl_add_u64 v[208:209], s[40:41], 0, v[190:191]
	global_load_lds_dwordx4 v[208:209], off
	s_mov_b32 m0, s57
	v_lshl_add_u64 v[208:209], v[212:213], 0, s[18:19]
	global_load_lds_dwordx4 v[208:209], off
	s_mov_b32 m0, s58
	v_lshl_add_u64 v[208:209], v[214:215], 0, s[18:19]
	global_load_lds_dwordx4 v[208:209], off
	s_waitcnt vmcnt(8) lgkmcnt(0)
	s_barrier
	s_setprio 1
	v_mfma_f32_16x16x32_bf16 v[60:63], v[120:123], v[160:163], v[60:63]
	v_mfma_f32_16x16x32_bf16 v[60:63], v[132:135], v[164:167], v[60:63]
	v_mfma_f32_16x16x32_bf16 v[56:59], v[136:139], v[160:163], v[56:59]
	v_mfma_f32_16x16x32_bf16 v[56:59], v[140:143], v[164:167], v[56:59]
	v_mfma_f32_16x16x32_bf16 v[40:43], v[136:139], v[168:171], v[40:43]
	v_mfma_f32_16x16x32_bf16 v[40:43], v[140:143], v[172:175], v[40:43]
	v_mfma_f32_16x16x32_bf16 v[44:47], v[120:123], v[168:171], v[44:47]
	v_mfma_f32_16x16x32_bf16 v[44:47], v[132:135], v[172:175], v[44:47]
	v_mfma_f32_16x16x32_bf16 v[28:31], v[120:123], v[176:179], v[28:31]
	v_mfma_f32_16x16x32_bf16 v[28:31], v[132:135], v[180:183], v[28:31]
	v_mfma_f32_16x16x32_bf16 v[24:27], v[136:139], v[176:179], v[24:27]
	v_mfma_f32_16x16x32_bf16 v[24:27], v[140:143], v[180:183], v[24:27]
	v_mfma_f32_16x16x32_bf16 v[8:11], v[136:139], v[200:203], v[8:11]
	v_mfma_f32_16x16x32_bf16 v[8:11], v[140:143], v[204:207], v[8:11]
	v_mfma_f32_16x16x32_bf16 v[12:15], v[120:123], v[200:203], v[12:15]
	v_mfma_f32_16x16x32_bf16 v[12:15], v[132:135], v[204:207], v[12:15]
	v_mfma_f32_16x16x32_bf16 v[52:55], v[144:147], v[160:163], v[52:55]
	v_mfma_f32_16x16x32_bf16 v[52:55], v[148:151], v[164:167], v[52:55]
	v_mfma_f32_16x16x32_bf16 v[48:51], v[152:155], v[160:163], v[48:51]
	v_mfma_f32_16x16x32_bf16 v[48:51], v[156:159], v[164:167], v[48:51]
	v_mfma_f32_16x16x32_bf16 v[32:35], v[152:155], v[168:171], v[32:35]
	v_mfma_f32_16x16x32_bf16 v[32:35], v[156:159], v[172:175], v[32:35]
	v_mfma_f32_16x16x32_bf16 v[36:39], v[144:147], v[168:171], v[36:39]
	v_mfma_f32_16x16x32_bf16 v[36:39], v[148:151], v[172:175], v[36:39]
	v_mfma_f32_16x16x32_bf16 v[20:23], v[144:147], v[176:179], v[20:23]
	v_mfma_f32_16x16x32_bf16 v[20:23], v[148:151], v[180:183], v[20:23]
	v_mfma_f32_16x16x32_bf16 v[16:19], v[152:155], v[176:179], v[16:19]
	v_mfma_f32_16x16x32_bf16 v[16:19], v[156:159], v[180:183], v[16:19]
	s_setprio 2
	s_barrier
	v_mfma_f32_16x16x32_bf16 v[0:3], v[152:155], v[200:203], v[0:3]
	v_mfma_f32_16x16x32_bf16 v[0:3], v[156:159], v[204:207], v[0:3]
	v_mfma_f32_16x16x32_bf16 v[4:7], v[144:147], v[200:203], v[4:7]
	v_mfma_f32_16x16x32_bf16 v[4:7], v[148:151], v[204:207], v[4:7]
	s_setprio 0
	s_add_i32 s66, s66, 2
	s_add_u32 s38, s38, 0x100
	s_addc_u32 s39, s39, 0
	s_add_u32 s64, s64, 0x100
	s_addc_u32 s65, s65, 0
	s_cmp_gt_u32 s66, 13
	s_cbranch_scc0 .LBB0_1146

.LBB0_1309:
	s_add_u32 s51, s26, 0x100
	s_addc_u32 s52, s27, 0
	s_mov_b32 s53, -2
	ds_read_b128 v[128:131], v197
	ds_read_b128 v[132:135], v197 offset:1024
	ds_read_b128 v[136:139], v197 offset:2048
	ds_read_b128 v[140:143], v197 offset:3072
	ds_read_b128 v[144:147], v198
	ds_read_b128 v[148:151], v198 offset:1024
	ds_read_b128 v[152:155], v198 offset:2048
	ds_read_b128 v[156:159], v198 offset:3072
	s_add_u32 s4, s24, 0x100
	s_addc_u32 s5, s25, 0
	s_cmp_eq_u32 s53, 40
	s_cselect_b32 s29, s21, s5
	s_cselect_b32 s28, s20, s4
	s_cselect_b32 s27, s23, s52
	s_cselect_b32 s26, s22, s51
	v_lshl_add_u64 v[212:213], s[24:25], 0, v[172:173]
	s_add_i32 m0, s36, 0xc000
	ds_read_b128 v[160:163], v199
	ds_read_b128 v[180:183], v199 offset:1024
	ds_read_b128 v[184:187], v199 offset:2048
	ds_read_b128 v[188:191], v199 offset:3072
	ds_read_b128 v[192:195], v199 offset:4096
	ds_read_b128 v[200:203], v199 offset:5120
	ds_read_b128 v[204:207], v199 offset:6144
	ds_read_b128 v[208:211], v199 offset:7168
	global_load_lds_dwordx4 v[212:213], off
	s_add_i32 m0, s36, 0xe000
	v_lshl_add_u64 v[212:213], s[24:25], 0, v[174:175]
	global_load_lds_dwordx4 v[212:213], off
	s_waitcnt vmcnt(8) lgkmcnt(0)
	s_barrier
	s_setprio 1
	v_mfma_f32_16x16x32_bf16 v[124:127], v[128:131], v[160:163], 0
	v_mfma_f32_16x16x32_bf16 v[124:127], v[132:135], v[180:183], v[124:127]
	v_mfma_f32_16x16x32_bf16 v[120:123], v[136:139], v[160:163], 0
	v_mfma_f32_16x16x32_bf16 v[120:123], v[140:143], v[180:183], v[120:123]
	v_mfma_f32_16x16x32_bf16 v[108:111], v[136:139], v[184:187], 0
	v_mfma_f32_16x16x32_bf16 v[108:111], v[140:143], v[188:191], v[108:111]
	v_mfma_f32_16x16x32_bf16 v[116:119], v[128:131], v[184:187], 0
	v_mfma_f32_16x16x32_bf16 v[116:119], v[132:135], v[188:191], v[116:119]
	v_mfma_f32_16x16x32_bf16 v[88:91], v[128:131], v[192:195], 0
	v_mfma_f32_16x16x32_bf16 v[88:91], v[132:135], v[200:203], v[88:91]
	v_mfma_f32_16x16x32_bf16 v[100:103], v[136:139], v[192:195], 0
	v_mfma_f32_16x16x32_bf16 v[100:103], v[140:143], v[200:203], v[100:103]
	v_mfma_f32_16x16x32_bf16 v[76:79], v[136:139], v[204:207], 0
	v_mfma_f32_16x16x32_bf16 v[76:79], v[140:143], v[208:211], v[76:79]
	v_mfma_f32_16x16x32_bf16 v[72:75], v[128:131], v[204:207], 0
	v_mfma_f32_16x16x32_bf16 v[72:75], v[132:135], v[208:211], v[72:75]
	v_mfma_f32_16x16x32_bf16 v[112:115], v[144:147], v[160:163], 0
	v_mfma_f32_16x16x32_bf16 v[112:115], v[148:151], v[180:183], v[112:115]
	v_mfma_f32_16x16x32_bf16 v[104:107], v[152:155], v[160:163], 0
	v_mfma_f32_16x16x32_bf16 v[104:107], v[156:159], v[180:183], v[104:107]
	v_mfma_f32_16x16x32_bf16 v[92:95], v[152:155], v[184:187], 0
	v_mfma_f32_16x16x32_bf16 v[92:95], v[156:159], v[188:191], v[92:95]
	v_mfma_f32_16x16x32_bf16 v[96:99], v[144:147], v[184:187], 0
	v_mfma_f32_16x16x32_bf16 v[96:99], v[148:151], v[188:191], v[96:99]
	v_mfma_f32_16x16x32_bf16 v[80:83], v[144:147], v[192:195], 0
	v_mfma_f32_16x16x32_bf16 v[80:83], v[148:151], v[200:203], v[80:83]
	v_mfma_f32_16x16x32_bf16 v[84:87], v[152:155], v[192:195], 0
	v_mfma_f32_16x16x32_bf16 v[84:87], v[156:159], v[200:203], v[84:87]
	s_setprio 2
	s_barrier
	v_mfma_f32_16x16x32_bf16 v[68:71], v[152:155], v[204:207], 0
	v_mfma_f32_16x16x32_bf16 v[68:71], v[156:159], v[208:211], v[68:71]
	v_mfma_f32_16x16x32_bf16 v[64:67], v[144:147], v[204:207], 0
	v_mfma_f32_16x16x32_bf16 v[64:67], v[148:151], v[208:211], v[64:67]
	s_setprio 2
	s_add_i32 s24, s45, s35
	v_lshl_add_u64 v[212:213], s[26:27], 0, v[166:167]
	s_mov_b32 m0, s24
	ds_read_b128 v[160:163], v199 offset:16384
	ds_read_b128 v[180:183], v199 offset:17408
	ds_read_b128 v[184:187], v199 offset:18432
	ds_read_b128 v[188:191], v199 offset:19456
	ds_read_b128 v[192:195], v199 offset:20480
	ds_read_b128 v[200:203], v199 offset:21504
	ds_read_b128 v[204:207], v199 offset:22528
	ds_read_b128 v[208:211], v199 offset:23552
	global_load_lds_dwordx4 v[212:213], off
	s_add_i32 m0, s24, 0x2000
	s_add_u32 s24, s26, 0xb0000
	v_lshl_add_u64 v[214:215], s[26:27], 0, v[170:171]
	s_addc_u32 s25, s27, 0
	s_add_i32 s54, s46, s35
	global_load_lds_dwordx4 v[214:215], off
	v_lshl_add_u64 v[216:217], s[24:25], 0, v[166:167]
	s_mov_b32 m0, s54
	v_lshl_add_u64 v[218:219], s[28:29], 0, v[168:169]
	global_load_lds_dwordx4 v[216:217], off
	s_add_i32 m0, s54, 0x2000
	v_lshl_add_u64 v[216:217], s[24:25], 0, v[170:171]
	global_load_lds_dwordx4 v[216:217], off
	s_mov_b32 m0, s36
	v_lshl_add_u64 v[216:217], s[28:29], 0, v[164:165]
	global_load_lds_dwordx4 v[216:217], off
	s_mov_b32 m0, s37
	s_nop 0
	global_load_lds_dwordx4 v[218:219], off
	s_waitcnt vmcnt(8) lgkmcnt(0)
	s_barrier
	s_setprio 1
	v_mfma_f32_16x16x32_bf16 v[56:59], v[128:131], v[160:163], 0
	v_mfma_f32_16x16x32_bf16 v[56:59], v[132:135], v[180:183], v[56:59]
	v_mfma_f32_16x16x32_bf16 v[60:63], v[136:139], v[160:163], 0
	v_mfma_f32_16x16x32_bf16 v[60:63], v[140:143], v[180:183], v[60:63]
	v_mfma_f32_16x16x32_bf16 v[44:47], v[136:139], v[184:187], 0
	v_mfma_f32_16x16x32_bf16 v[44:47], v[140:143], v[188:191], v[44:47]
	v_mfma_f32_16x16x32_bf16 v[40:43], v[128:131], v[184:187], 0
	v_mfma_f32_16x16x32_bf16 v[40:43], v[132:135], v[188:191], v[40:43]
	v_mfma_f32_16x16x32_bf16 v[24:27], v[128:131], v[192:195], 0
	v_mfma_f32_16x16x32_bf16 v[24:27], v[132:135], v[200:203], v[24:27]
	v_mfma_f32_16x16x32_bf16 v[28:31], v[136:139], v[192:195], 0
	v_mfma_f32_16x16x32_bf16 v[28:31], v[140:143], v[200:203], v[28:31]
	v_mfma_f32_16x16x32_bf16 v[12:15], v[136:139], v[204:207], 0
	v_mfma_f32_16x16x32_bf16 v[12:15], v[140:143], v[208:211], v[12:15]
	v_mfma_f32_16x16x32_bf16 v[8:11], v[128:131], v[204:207], 0
	v_mfma_f32_16x16x32_bf16 v[8:11], v[132:135], v[208:211], v[8:11]
	v_mfma_f32_16x16x32_bf16 v[48:51], v[144:147], v[160:163], 0
	v_mfma_f32_16x16x32_bf16 v[48:51], v[148:151], v[180:183], v[48:51]
	v_mfma_f32_16x16x32_bf16 v[52:55], v[152:155], v[160:163], 0
	v_mfma_f32_16x16x32_bf16 v[52:55], v[156:159], v[180:183], v[52:55]
	v_mfma_f32_16x16x32_bf16 v[36:39], v[152:155], v[184:187], 0
	v_mfma_f32_16x16x32_bf16 v[36:39], v[156:159], v[188:191], v[36:39]
	v_mfma_f32_16x16x32_bf16 v[32:35], v[144:147], v[184:187], 0
	v_mfma_f32_16x16x32_bf16 v[32:35], v[148:151], v[188:191], v[32:35]
	v_mfma_f32_16x16x32_bf16 v[16:19], v[144:147], v[192:195], 0
	v_mfma_f32_16x16x32_bf16 v[16:19], v[148:151], v[200:203], v[16:19]
	v_mfma_f32_16x16x32_bf16 v[20:23], v[152:155], v[192:195], 0
	v_mfma_f32_16x16x32_bf16 v[20:23], v[156:159], v[200:203], v[20:23]
	s_setprio 2
	s_barrier
	v_mfma_f32_16x16x32_bf16 v[4:7], v[152:155], v[204:207], 0
	v_mfma_f32_16x16x32_bf16 v[4:7], v[156:159], v[208:211], v[4:7]
	v_mfma_f32_16x16x32_bf16 v[0:3], v[144:147], v[204:207], 0
	v_mfma_f32_16x16x32_bf16 v[0:3], v[148:151], v[208:211], v[0:3]
	s_setprio 0
	s_add_i32 s54, 0, 0x18000
	s_add_i32 s55, 0, 0x1c000
	v_add_u32_e32 v140, s54, v196
	v_add_u32_e32 v156, s55, v196
	ds_read_b128 v[128:131], v140
	ds_read_b128 v[132:135], v140 offset:1024
	ds_read_b128 v[136:139], v140 offset:2048
	ds_read_b128 v[140:143], v140 offset:3072
	ds_read_b128 v[144:147], v156
	ds_read_b128 v[148:151], v156 offset:1024
	ds_read_b128 v[152:155], v156 offset:2048
	ds_read_b128 v[156:159], v156 offset:3072
	s_add_u32 s24, s28, 0xb0000
	s_addc_u32 s25, s29, 0
	s_mov_b32 m0, s38
	v_lshl_add_u64 v[220:221], s[24:25], 0, v[164:165]
	ds_read_b128 v[160:163], v199 offset:32768
	ds_read_b128 v[180:183], v199 offset:33792
	ds_read_b128 v[184:187], v199 offset:34816
	ds_read_b128 v[188:191], v199 offset:35840
	ds_read_b128 v[192:195], v199 offset:36864
	ds_read_b128 v[200:203], v199 offset:37888
	ds_read_b128 v[204:207], v199 offset:38912
	ds_read_b128 v[208:211], v199 offset:39936
	global_load_lds_dwordx4 v[220:221], off
	s_mov_b32 m0, s39
	v_lshl_add_u64 v[220:221], s[24:25], 0, v[168:169]
	global_load_lds_dwordx4 v[220:221], off
	s_waitcnt vmcnt(8) lgkmcnt(0)
	s_barrier
	s_setprio 1
	v_mfma_f32_16x16x32_bf16 v[124:127], v[128:131], v[160:163], v[124:127]
	v_mfma_f32_16x16x32_bf16 v[124:127], v[132:135], v[180:183], v[124:127]
	v_mfma_f32_16x16x32_bf16 v[120:123], v[136:139], v[160:163], v[120:123]
	v_mfma_f32_16x16x32_bf16 v[120:123], v[140:143], v[180:183], v[120:123]
	v_mfma_f32_16x16x32_bf16 v[108:111], v[136:139], v[184:187], v[108:111]
	v_mfma_f32_16x16x32_bf16 v[108:111], v[140:143], v[188:191], v[108:111]
	v_mfma_f32_16x16x32_bf16 v[116:119], v[128:131], v[184:187], v[116:119]
	v_mfma_f32_16x16x32_bf16 v[116:119], v[132:135], v[188:191], v[116:119]
	v_mfma_f32_16x16x32_bf16 v[88:91], v[128:131], v[192:195], v[88:91]
	v_mfma_f32_16x16x32_bf16 v[88:91], v[132:135], v[200:203], v[88:91]
	v_mfma_f32_16x16x32_bf16 v[100:103], v[136:139], v[192:195], v[100:103]
	v_mfma_f32_16x16x32_bf16 v[100:103], v[140:143], v[200:203], v[100:103]
	v_mfma_f32_16x16x32_bf16 v[76:79], v[136:139], v[204:207], v[76:79]
	v_mfma_f32_16x16x32_bf16 v[76:79], v[140:143], v[208:211], v[76:79]
	v_mfma_f32_16x16x32_bf16 v[72:75], v[128:131], v[204:207], v[72:75]
	v_mfma_f32_16x16x32_bf16 v[72:75], v[132:135], v[208:211], v[72:75]
	v_mfma_f32_16x16x32_bf16 v[112:115], v[144:147], v[160:163], v[112:115]
	v_mfma_f32_16x16x32_bf16 v[112:115], v[148:151], v[180:183], v[112:115]
	v_mfma_f32_16x16x32_bf16 v[104:107], v[152:155], v[160:163], v[104:107]
	v_mfma_f32_16x16x32_bf16 v[104:107], v[156:159], v[180:183], v[104:107]
	v_mfma_f32_16x16x32_bf16 v[92:95], v[152:155], v[184:187], v[92:95]
	v_mfma_f32_16x16x32_bf16 v[92:95], v[156:159], v[188:191], v[92:95]
	v_mfma_f32_16x16x32_bf16 v[96:99], v[144:147], v[184:187], v[96:99]
	v_mfma_f32_16x16x32_bf16 v[96:99], v[148:151], v[188:191], v[96:99]
	v_mfma_f32_16x16x32_bf16 v[80:83], v[144:147], v[192:195], v[80:83]
	v_mfma_f32_16x16x32_bf16 v[80:83], v[148:151], v[200:203], v[80:83]
	v_mfma_f32_16x16x32_bf16 v[84:87], v[152:155], v[192:195], v[84:87]
	v_mfma_f32_16x16x32_bf16 v[84:87], v[156:159], v[200:203], v[84:87]
	s_setprio 2
	s_barrier
	v_mfma_f32_16x16x32_bf16 v[68:71], v[152:155], v[204:207], v[68:71]
	v_mfma_f32_16x16x32_bf16 v[68:71], v[156:159], v[208:211], v[68:71]
	v_mfma_f32_16x16x32_bf16 v[64:67], v[144:147], v[204:207], v[64:67]
	v_mfma_f32_16x16x32_bf16 v[64:67], v[148:151], v[208:211], v[64:67]
	s_setprio 2
	s_add_i32 s24, s54, s35
	v_lshl_add_u64 v[212:213], v[212:213], 0, s[16:17]
	s_mov_b32 m0, s24
	ds_read_b128 v[160:163], v199 offset:49152
	ds_read_b128 v[180:183], v199 offset:50176
	ds_read_b128 v[184:187], v199 offset:51200
	ds_read_b128 v[188:191], v199 offset:52224
	ds_read_b128 v[192:195], v199 offset:53248
	ds_read_b128 v[200:203], v199 offset:54272
	ds_read_b128 v[204:207], v199 offset:55296
	ds_read_b128 v[208:211], v199 offset:56320
	global_load_lds_dwordx4 v[212:213], off
	s_add_i32 m0, s24, 0x2000
	s_add_u32 s24, s26, 0xb0080
	v_lshl_add_u64 v[212:213], v[214:215], 0, s[16:17]
	s_addc_u32 s25, s27, 0
	s_add_i32 s26, s55, s35
	global_load_lds_dwordx4 v[212:213], off
	s_mov_b32 m0, s26
	v_lshl_add_u64 v[212:213], s[24:25], 0, v[166:167]
	global_load_lds_dwordx4 v[212:213], off
	s_add_i32 m0, s26, 0x2000
	v_lshl_add_u64 v[212:213], s[24:25], 0, v[170:171]
	global_load_lds_dwordx4 v[212:213], off
	s_mov_b32 m0, s41
	v_lshl_add_u64 v[212:213], v[216:217], 0, s[16:17]
	global_load_lds_dwordx4 v[212:213], off
	s_mov_b32 m0, s42
	v_lshl_add_u64 v[212:213], v[218:219], 0, s[16:17]
	global_load_lds_dwordx4 v[212:213], off
	s_waitcnt vmcnt(8) lgkmcnt(0)
	s_barrier
	s_setprio 1
	v_mfma_f32_16x16x32_bf16 v[56:59], v[128:131], v[160:163], v[56:59]
	v_mfma_f32_16x16x32_bf16 v[56:59], v[132:135], v[180:183], v[56:59]
	v_mfma_f32_16x16x32_bf16 v[60:63], v[136:139], v[160:163], v[60:63]
	v_mfma_f32_16x16x32_bf16 v[60:63], v[140:143], v[180:183], v[60:63]
	v_mfma_f32_16x16x32_bf16 v[44:47], v[136:139], v[184:187], v[44:47]
	v_mfma_f32_16x16x32_bf16 v[44:47], v[140:143], v[188:191], v[44:47]
	v_mfma_f32_16x16x32_bf16 v[40:43], v[128:131], v[184:187], v[40:43]
	v_mfma_f32_16x16x32_bf16 v[40:43], v[132:135], v[188:191], v[40:43]
	v_mfma_f32_16x16x32_bf16 v[24:27], v[128:131], v[192:195], v[24:27]
	v_mfma_f32_16x16x32_bf16 v[24:27], v[132:135], v[200:203], v[24:27]
	v_mfma_f32_16x16x32_bf16 v[28:31], v[136:139], v[192:195], v[28:31]
	v_mfma_f32_16x16x32_bf16 v[28:31], v[140:143], v[200:203], v[28:31]
	v_mfma_f32_16x16x32_bf16 v[12:15], v[136:139], v[204:207], v[12:15]
	v_mfma_f32_16x16x32_bf16 v[12:15], v[140:143], v[208:211], v[12:15]
	v_mfma_f32_16x16x32_bf16 v[8:11], v[128:131], v[204:207], v[8:11]
	v_mfma_f32_16x16x32_bf16 v[8:11], v[132:135], v[208:211], v[8:11]
	v_mfma_f32_16x16x32_bf16 v[48:51], v[144:147], v[160:163], v[48:51]
	v_mfma_f32_16x16x32_bf16 v[48:51], v[148:151], v[180:183], v[48:51]
	v_mfma_f32_16x16x32_bf16 v[52:55], v[152:155], v[160:163], v[52:55]
	v_mfma_f32_16x16x32_bf16 v[52:55], v[156:159], v[180:183], v[52:55]
	v_mfma_f32_16x16x32_bf16 v[36:39], v[152:155], v[184:187], v[36:39]
	v_mfma_f32_16x16x32_bf16 v[36:39], v[156:159], v[188:191], v[36:39]
	v_mfma_f32_16x16x32_bf16 v[32:35], v[144:147], v[184:187], v[32:35]
	v_mfma_f32_16x16x32_bf16 v[32:35], v[148:151], v[188:191], v[32:35]
	v_mfma_f32_16x16x32_bf16 v[16:19], v[144:147], v[192:195], v[16:19]
	v_mfma_f32_16x16x32_bf16 v[16:19], v[148:151], v[200:203], v[16:19]
	v_mfma_f32_16x16x32_bf16 v[20:23], v[152:155], v[192:195], v[20:23]
	v_mfma_f32_16x16x32_bf16 v[20:23], v[156:159], v[200:203], v[20:23]
	s_setprio 2
	s_barrier
	v_mfma_f32_16x16x32_bf16 v[4:7], v[152:155], v[204:207], v[4:7]
	v_mfma_f32_16x16x32_bf16 v[4:7], v[156:159], v[208:211], v[4:7]
	v_mfma_f32_16x16x32_bf16 v[0:3], v[144:147], v[204:207], v[0:3]
	v_mfma_f32_16x16x32_bf16 v[0:3], v[148:151], v[208:211], v[0:3]
	s_setprio 0
	s_add_i32 s53, s53, 2
	s_add_u32 s51, s51, 0x100
	s_addc_u32 s52, s52, 0
	s_cmp_gt_u32 s53, 41
	s_mov_b64 s[24:25], s[4:5]
.LBB0_1310:
	ds_read_b128 v[128:131], v197
	ds_read_b128 v[132:135], v197 offset:1024
	ds_read_b128 v[136:139], v197 offset:2048
	ds_read_b128 v[140:143], v197 offset:3072
	ds_read_b128 v[144:147], v198
	ds_read_b128 v[148:151], v198 offset:1024
	ds_read_b128 v[152:155], v198 offset:2048
	ds_read_b128 v[156:159], v198 offset:3072
	s_add_u32 s4, s24, 0x100
	s_addc_u32 s5, s25, 0
	s_cmp_eq_u32 s53, 40
	s_cselect_b32 s29, s21, s5
	s_cselect_b32 s28, s20, s4
	s_cselect_b32 s27, s23, s52
	s_cselect_b32 s26, s22, s51
	v_lshl_add_u64 v[212:213], s[24:25], 0, v[172:173]
	s_add_i32 m0, s36, 0xc000
	ds_read_b128 v[160:163], v199
	ds_read_b128 v[180:183], v199 offset:1024
	ds_read_b128 v[184:187], v199 offset:2048
	ds_read_b128 v[188:191], v199 offset:3072
	ds_read_b128 v[192:195], v199 offset:4096
	ds_read_b128 v[200:203], v199 offset:5120
	ds_read_b128 v[204:207], v199 offset:6144
	ds_read_b128 v[208:211], v199 offset:7168
	global_load_lds_dwordx4 v[212:213], off
	s_add_i32 m0, s36, 0xe000
	v_lshl_add_u64 v[212:213], s[24:25], 0, v[174:175]
	global_load_lds_dwordx4 v[212:213], off
	s_waitcnt vmcnt(8) lgkmcnt(0)
	s_barrier
	s_setprio 1
	v_mfma_f32_16x16x32_bf16 v[124:127], v[128:131], v[160:163], v[124:127]
	v_mfma_f32_16x16x32_bf16 v[124:127], v[132:135], v[180:183], v[124:127]
	v_mfma_f32_16x16x32_bf16 v[120:123], v[136:139], v[160:163], v[120:123]
	v_mfma_f32_16x16x32_bf16 v[120:123], v[140:143], v[180:183], v[120:123]
	v_mfma_f32_16x16x32_bf16 v[108:111], v[136:139], v[184:187], v[108:111]
	v_mfma_f32_16x16x32_bf16 v[108:111], v[140:143], v[188:191], v[108:111]
	v_mfma_f32_16x16x32_bf16 v[116:119], v[128:131], v[184:187], v[116:119]
	v_mfma_f32_16x16x32_bf16 v[116:119], v[132:135], v[188:191], v[116:119]
	v_mfma_f32_16x16x32_bf16 v[88:91], v[128:131], v[192:195], v[88:91]
	v_mfma_f32_16x16x32_bf16 v[88:91], v[132:135], v[200:203], v[88:91]
	v_mfma_f32_16x16x32_bf16 v[100:103], v[136:139], v[192:195], v[100:103]
	v_mfma_f32_16x16x32_bf16 v[100:103], v[140:143], v[200:203], v[100:103]
	v_mfma_f32_16x16x32_bf16 v[76:79], v[136:139], v[204:207], v[76:79]
	v_mfma_f32_16x16x32_bf16 v[76:79], v[140:143], v[208:211], v[76:79]
	v_mfma_f32_16x16x32_bf16 v[72:75], v[128:131], v[204:207], v[72:75]
	v_mfma_f32_16x16x32_bf16 v[72:75], v[132:135], v[208:211], v[72:75]
	v_mfma_f32_16x16x32_bf16 v[112:115], v[144:147], v[160:163], v[112:115]
	v_mfma_f32_16x16x32_bf16 v[112:115], v[148:151], v[180:183], v[112:115]
	v_mfma_f32_16x16x32_bf16 v[104:107], v[152:155], v[160:163], v[104:107]
	v_mfma_f32_16x16x32_bf16 v[104:107], v[156:159], v[180:183], v[104:107]
	v_mfma_f32_16x16x32_bf16 v[92:95], v[152:155], v[184:187], v[92:95]
	v_mfma_f32_16x16x32_bf16 v[92:95], v[156:159], v[188:191], v[92:95]
	v_mfma_f32_16x16x32_bf16 v[96:99], v[144:147], v[184:187], v[96:99]
	v_mfma_f32_16x16x32_bf16 v[96:99], v[148:151], v[188:191], v[96:99]
	v_mfma_f32_16x16x32_bf16 v[80:83], v[144:147], v[192:195], v[80:83]
	v_mfma_f32_16x16x32_bf16 v[80:83], v[148:151], v[200:203], v[80:83]
	v_mfma_f32_16x16x32_bf16 v[84:87], v[152:155], v[192:195], v[84:87]
	v_mfma_f32_16x16x32_bf16 v[84:87], v[156:159], v[200:203], v[84:87]
	s_setprio 2
	s_barrier
	v_mfma_f32_16x16x32_bf16 v[68:71], v[152:155], v[204:207], v[68:71]
	v_mfma_f32_16x16x32_bf16 v[68:71], v[156:159], v[208:211], v[68:71]
	v_mfma_f32_16x16x32_bf16 v[64:67], v[144:147], v[204:207], v[64:67]
	v_mfma_f32_16x16x32_bf16 v[64:67], v[148:151], v[208:211], v[64:67]
	s_setprio 2
	s_add_i32 s24, s45, s35
	v_lshl_add_u64 v[212:213], s[26:27], 0, v[166:167]
	s_mov_b32 m0, s24
	ds_read_b128 v[160:163], v199 offset:16384
	ds_read_b128 v[180:183], v199 offset:17408
	ds_read_b128 v[184:187], v199 offset:18432
	ds_read_b128 v[188:191], v199 offset:19456
	ds_read_b128 v[192:195], v199 offset:20480
	ds_read_b128 v[200:203], v199 offset:21504
	ds_read_b128 v[204:207], v199 offset:22528
	ds_read_b128 v[208:211], v199 offset:23552
	global_load_lds_dwordx4 v[212:213], off
	s_add_i32 m0, s24, 0x2000
	s_add_u32 s24, s26, 0xb0000
	v_lshl_add_u64 v[214:215], s[26:27], 0, v[170:171]
	s_addc_u32 s25, s27, 0
	s_add_i32 s54, s46, s35
	global_load_lds_dwordx4 v[214:215], off
	v_lshl_add_u64 v[216:217], s[24:25], 0, v[166:167]
	s_mov_b32 m0, s54
	v_lshl_add_u64 v[218:219], s[28:29], 0, v[168:169]
	global_load_lds_dwordx4 v[216:217], off
	s_add_i32 m0, s54, 0x2000
	v_lshl_add_u64 v[216:217], s[24:25], 0, v[170:171]
	global_load_lds_dwordx4 v[216:217], off
	s_mov_b32 m0, s36
	v_lshl_add_u64 v[216:217], s[28:29], 0, v[164:165]
	global_load_lds_dwordx4 v[216:217], off
	s_mov_b32 m0, s37
	s_nop 0
	global_load_lds_dwordx4 v[218:219], off
	s_waitcnt vmcnt(8) lgkmcnt(0)
	s_barrier
	s_setprio 1
	v_mfma_f32_16x16x32_bf16 v[56:59], v[128:131], v[160:163], v[56:59]
	v_mfma_f32_16x16x32_bf16 v[56:59], v[132:135], v[180:183], v[56:59]
	v_mfma_f32_16x16x32_bf16 v[60:63], v[136:139], v[160:163], v[60:63]
	v_mfma_f32_16x16x32_bf16 v[60:63], v[140:143], v[180:183], v[60:63]
	v_mfma_f32_16x16x32_bf16 v[44:47], v[136:139], v[184:187], v[44:47]
	v_mfma_f32_16x16x32_bf16 v[44:47], v[140:143], v[188:191], v[44:47]
	v_mfma_f32_16x16x32_bf16 v[40:43], v[128:131], v[184:187], v[40:43]
	v_mfma_f32_16x16x32_bf16 v[40:43], v[132:135], v[188:191], v[40:43]
	v_mfma_f32_16x16x32_bf16 v[24:27], v[128:131], v[192:195], v[24:27]
	v_mfma_f32_16x16x32_bf16 v[24:27], v[132:135], v[200:203], v[24:27]
	v_mfma_f32_16x16x32_bf16 v[28:31], v[136:139], v[192:195], v[28:31]
	v_mfma_f32_16x16x32_bf16 v[28:31], v[140:143], v[200:203], v[28:31]
	v_mfma_f32_16x16x32_bf16 v[12:15], v[136:139], v[204:207], v[12:15]
	v_mfma_f32_16x16x32_bf16 v[12:15], v[140:143], v[208:211], v[12:15]
	v_mfma_f32_16x16x32_bf16 v[8:11], v[128:131], v[204:207], v[8:11]
	v_mfma_f32_16x16x32_bf16 v[8:11], v[132:135], v[208:211], v[8:11]
	v_mfma_f32_16x16x32_bf16 v[48:51], v[144:147], v[160:163], v[48:51]
	v_mfma_f32_16x16x32_bf16 v[48:51], v[148:151], v[180:183], v[48:51]
	v_mfma_f32_16x16x32_bf16 v[52:55], v[152:155], v[160:163], v[52:55]
	v_mfma_f32_16x16x32_bf16 v[52:55], v[156:159], v[180:183], v[52:55]
	v_mfma_f32_16x16x32_bf16 v[36:39], v[152:155], v[184:187], v[36:39]
	v_mfma_f32_16x16x32_bf16 v[36:39], v[156:159], v[188:191], v[36:39]
	v_mfma_f32_16x16x32_bf16 v[32:35], v[144:147], v[184:187], v[32:35]
	v_mfma_f32_16x16x32_bf16 v[32:35], v[148:151], v[188:191], v[32:35]
	v_mfma_f32_16x16x32_bf16 v[16:19], v[144:147], v[192:195], v[16:19]
	v_mfma_f32_16x16x32_bf16 v[16:19], v[148:151], v[200:203], v[16:19]
	v_mfma_f32_16x16x32_bf16 v[20:23], v[152:155], v[192:195], v[20:23]
	v_mfma_f32_16x16x32_bf16 v[20:23], v[156:159], v[200:203], v[20:23]
	s_setprio 2
	s_barrier
	v_mfma_f32_16x16x32_bf16 v[4:7], v[152:155], v[204:207], v[4:7]
	v_mfma_f32_16x16x32_bf16 v[4:7], v[156:159], v[208:211], v[4:7]
	v_mfma_f32_16x16x32_bf16 v[0:3], v[144:147], v[204:207], v[0:3]
	v_mfma_f32_16x16x32_bf16 v[0:3], v[148:151], v[208:211], v[0:3]
	s_setprio 0
	s_add_i32 s54, 0, 0x18000
	s_add_i32 s55, 0, 0x1c000
	v_add_u32_e32 v140, s54, v196
	v_add_u32_e32 v156, s55, v196
	ds_read_b128 v[128:131], v140
	ds_read_b128 v[132:135], v140 offset:1024
	ds_read_b128 v[136:139], v140 offset:2048
	ds_read_b128 v[140:143], v140 offset:3072
	ds_read_b128 v[144:147], v156
	ds_read_b128 v[148:151], v156 offset:1024
	ds_read_b128 v[152:155], v156 offset:2048
	ds_read_b128 v[156:159], v156 offset:3072
	s_add_u32 s24, s28, 0xb0000
	s_addc_u32 s25, s29, 0
	s_mov_b32 m0, s38
	v_lshl_add_u64 v[220:221], s[24:25], 0, v[164:165]
	ds_read_b128 v[160:163], v199 offset:32768
	ds_read_b128 v[180:183], v199 offset:33792
	ds_read_b128 v[184:187], v199 offset:34816
	ds_read_b128 v[188:191], v199 offset:35840
	ds_read_b128 v[192:195], v199 offset:36864
	ds_read_b128 v[200:203], v199 offset:37888
	ds_read_b128 v[204:207], v199 offset:38912
	ds_read_b128 v[208:211], v199 offset:39936
	global_load_lds_dwordx4 v[220:221], off
	s_mov_b32 m0, s39
	v_lshl_add_u64 v[220:221], s[24:25], 0, v[168:169]
	global_load_lds_dwordx4 v[220:221], off
	s_waitcnt vmcnt(8) lgkmcnt(0)
	s_barrier
	s_setprio 1
	v_mfma_f32_16x16x32_bf16 v[124:127], v[128:131], v[160:163], v[124:127]
	v_mfma_f32_16x16x32_bf16 v[124:127], v[132:135], v[180:183], v[124:127]
	v_mfma_f32_16x16x32_bf16 v[120:123], v[136:139], v[160:163], v[120:123]
	v_mfma_f32_16x16x32_bf16 v[120:123], v[140:143], v[180:183], v[120:123]
	v_mfma_f32_16x16x32_bf16 v[108:111], v[136:139], v[184:187], v[108:111]
	v_mfma_f32_16x16x32_bf16 v[108:111], v[140:143], v[188:191], v[108:111]
	v_mfma_f32_16x16x32_bf16 v[116:119], v[128:131], v[184:187], v[116:119]
	v_mfma_f32_16x16x32_bf16 v[116:119], v[132:135], v[188:191], v[116:119]
	v_mfma_f32_16x16x32_bf16 v[88:91], v[128:131], v[192:195], v[88:91]
	v_mfma_f32_16x16x32_bf16 v[88:91], v[132:135], v[200:203], v[88:91]
	v_mfma_f32_16x16x32_bf16 v[100:103], v[136:139], v[192:195], v[100:103]
	v_mfma_f32_16x16x32_bf16 v[100:103], v[140:143], v[200:203], v[100:103]
	v_mfma_f32_16x16x32_bf16 v[76:79], v[136:139], v[204:207], v[76:79]
	v_mfma_f32_16x16x32_bf16 v[76:79], v[140:143], v[208:211], v[76:79]
	v_mfma_f32_16x16x32_bf16 v[72:75], v[128:131], v[204:207], v[72:75]
	v_mfma_f32_16x16x32_bf16 v[72:75], v[132:135], v[208:211], v[72:75]
	v_mfma_f32_16x16x32_bf16 v[112:115], v[144:147], v[160:163], v[112:115]
	v_mfma_f32_16x16x32_bf16 v[112:115], v[148:151], v[180:183], v[112:115]
	v_mfma_f32_16x16x32_bf16 v[104:107], v[152:155], v[160:163], v[104:107]
	v_mfma_f32_16x16x32_bf16 v[104:107], v[156:159], v[180:183], v[104:107]
	v_mfma_f32_16x16x32_bf16 v[92:95], v[152:155], v[184:187], v[92:95]
	v_mfma_f32_16x16x32_bf16 v[92:95], v[156:159], v[188:191], v[92:95]
	v_mfma_f32_16x16x32_bf16 v[96:99], v[144:147], v[184:187], v[96:99]
	v_mfma_f32_16x16x32_bf16 v[96:99], v[148:151], v[188:191], v[96:99]
	v_mfma_f32_16x16x32_bf16 v[80:83], v[144:147], v[192:195], v[80:83]
	v_mfma_f32_16x16x32_bf16 v[80:83], v[148:151], v[200:203], v[80:83]
	v_mfma_f32_16x16x32_bf16 v[84:87], v[152:155], v[192:195], v[84:87]
	v_mfma_f32_16x16x32_bf16 v[84:87], v[156:159], v[200:203], v[84:87]
	s_setprio 2
	s_barrier
	v_mfma_f32_16x16x32_bf16 v[68:71], v[152:155], v[204:207], v[68:71]
	v_mfma_f32_16x16x32_bf16 v[68:71], v[156:159], v[208:211], v[68:71]
	v_mfma_f32_16x16x32_bf16 v[64:67], v[144:147], v[204:207], v[64:67]
	v_mfma_f32_16x16x32_bf16 v[64:67], v[148:151], v[208:211], v[64:67]
	s_setprio 2
	s_add_i32 s24, s54, s35
	v_lshl_add_u64 v[212:213], v[212:213], 0, s[16:17]
	s_mov_b32 m0, s24
	ds_read_b128 v[160:163], v199 offset:49152
	ds_read_b128 v[180:183], v199 offset:50176
	ds_read_b128 v[184:187], v199 offset:51200
	ds_read_b128 v[188:191], v199 offset:52224
	ds_read_b128 v[192:195], v199 offset:53248
	ds_read_b128 v[200:203], v199 offset:54272
	ds_read_b128 v[204:207], v199 offset:55296
	ds_read_b128 v[208:211], v199 offset:56320
	global_load_lds_dwordx4 v[212:213], off
	s_add_i32 m0, s24, 0x2000
	s_add_u32 s24, s26, 0xb0080
	v_lshl_add_u64 v[212:213], v[214:215], 0, s[16:17]
	s_addc_u32 s25, s27, 0
	s_add_i32 s26, s55, s35
	global_load_lds_dwordx4 v[212:213], off
	s_mov_b32 m0, s26
	v_lshl_add_u64 v[212:213], s[24:25], 0, v[166:167]
	global_load_lds_dwordx4 v[212:213], off
	s_add_i32 m0, s26, 0x2000
	v_lshl_add_u64 v[212:213], s[24:25], 0, v[170:171]
	global_load_lds_dwordx4 v[212:213], off
	s_mov_b32 m0, s41
	v_lshl_add_u64 v[212:213], v[216:217], 0, s[16:17]
	global_load_lds_dwordx4 v[212:213], off
	s_mov_b32 m0, s42
	v_lshl_add_u64 v[212:213], v[218:219], 0, s[16:17]
	global_load_lds_dwordx4 v[212:213], off
	s_waitcnt vmcnt(8) lgkmcnt(0)
	s_barrier
	s_setprio 1
	v_mfma_f32_16x16x32_bf16 v[56:59], v[128:131], v[160:163], v[56:59]
	v_mfma_f32_16x16x32_bf16 v[56:59], v[132:135], v[180:183], v[56:59]
	v_mfma_f32_16x16x32_bf16 v[60:63], v[136:139], v[160:163], v[60:63]
	v_mfma_f32_16x16x32_bf16 v[60:63], v[140:143], v[180:183], v[60:63]
	v_mfma_f32_16x16x32_bf16 v[44:47], v[136:139], v[184:187], v[44:47]
	v_mfma_f32_16x16x32_bf16 v[44:47], v[140:143], v[188:191], v[44:47]
	v_mfma_f32_16x16x32_bf16 v[40:43], v[128:131], v[184:187], v[40:43]
	v_mfma_f32_16x16x32_bf16 v[40:43], v[132:135], v[188:191], v[40:43]
	v_mfma_f32_16x16x32_bf16 v[24:27], v[128:131], v[192:195], v[24:27]
	v_mfma_f32_16x16x32_bf16 v[24:27], v[132:135], v[200:203], v[24:27]
	v_mfma_f32_16x16x32_bf16 v[28:31], v[136:139], v[192:195], v[28:31]
	v_mfma_f32_16x16x32_bf16 v[28:31], v[140:143], v[200:203], v[28:31]
	v_mfma_f32_16x16x32_bf16 v[12:15], v[136:139], v[204:207], v[12:15]
	v_mfma_f32_16x16x32_bf16 v[12:15], v[140:143], v[208:211], v[12:15]
	v_mfma_f32_16x16x32_bf16 v[8:11], v[128:131], v[204:207], v[8:11]
	v_mfma_f32_16x16x32_bf16 v[8:11], v[132:135], v[208:211], v[8:11]
	v_mfma_f32_16x16x32_bf16 v[48:51], v[144:147], v[160:163], v[48:51]
	v_mfma_f32_16x16x32_bf16 v[48:51], v[148:151], v[180:183], v[48:51]
	v_mfma_f32_16x16x32_bf16 v[52:55], v[152:155], v[160:163], v[52:55]
	v_mfma_f32_16x16x32_bf16 v[52:55], v[156:159], v[180:183], v[52:55]
	v_mfma_f32_16x16x32_bf16 v[36:39], v[152:155], v[184:187], v[36:39]
	v_mfma_f32_16x16x32_bf16 v[36:39], v[156:159], v[188:191], v[36:39]
	v_mfma_f32_16x16x32_bf16 v[32:35], v[144:147], v[184:187], v[32:35]
	v_mfma_f32_16x16x32_bf16 v[32:35], v[148:151], v[188:191], v[32:35]
	v_mfma_f32_16x16x32_bf16 v[16:19], v[144:147], v[192:195], v[16:19]
	v_mfma_f32_16x16x32_bf16 v[16:19], v[148:151], v[200:203], v[16:19]
	v_mfma_f32_16x16x32_bf16 v[20:23], v[152:155], v[192:195], v[20:23]
	v_mfma_f32_16x16x32_bf16 v[20:23], v[156:159], v[200:203], v[20:23]
	s_setprio 2
	s_barrier
	v_mfma_f32_16x16x32_bf16 v[4:7], v[152:155], v[204:207], v[4:7]
	v_mfma_f32_16x16x32_bf16 v[4:7], v[156:159], v[208:211], v[4:7]
	v_mfma_f32_16x16x32_bf16 v[0:3], v[144:147], v[204:207], v[0:3]
	v_mfma_f32_16x16x32_bf16 v[0:3], v[148:151], v[208:211], v[0:3]
	s_setprio 0
	s_add_i32 s53, s53, 2
	s_add_u32 s51, s51, 0x100
	s_addc_u32 s52, s52, 0
	s_cmp_gt_u32 s53, 41
	s_mov_b64 s[24:25], s[4:5]
	s_cbranch_scc0 .LBB0_1310
